# GEMM k-loops: 2 held-back MFMAs restart the matrix pipe right after the barrier, then 2 LDS-DMA pieces, then the fragment ds_reads
# baseline (speedup 1.0000x reference)
.Lg0_top:
	s_waitcnt lgkmcnt(0)
	s_waitcnt vmcnt(0)
	s_barrier
	v_mfma_f32_16x16x32_bf16 v[60:63], v[172:175], v[206:209], v[60:63]
	v_mfma_f32_16x16x32_bf16 v[52:55], v[172:175], v[210:213], v[52:55]
	s_xor_b32 s87, s87, 0x10000
	s_mov_b32 m0, s87
	s_add_u32 s88, s60, s16
	s_addc_u32 s89, s61, s17
	global_load_lds_dwordx4 v144, s[88:89]
	s_add_u32 m0, s87, 0x2000
	s_add_u32 s88, s60, s18
	s_addc_u32 s89, s61, s19
	global_load_lds_dwordx4 v144, s[88:89]
	ds_read_b128 v[156:159], v143
	ds_read_b128 v[160:163], v143 offset:2048
	ds_read_b128 v[164:167], v143 offset:4096
	ds_read_b128 v[168:171], v143 offset:6144
	ds_read_b128 v[190:193], v180 offset:32768
	ds_read_b128 v[194:197], v180 offset:34816
	ds_read_b128 v[198:201], v180 offset:36864
	ds_read_b128 v[202:205], v180 offset:38912
	v_mfma_f32_16x16x32_bf16 v[56:59], v[172:175], v[214:217], v[56:59]
	v_mfma_f32_16x16x32_bf16 v[48:51], v[172:175], v[218:221], v[48:51]
	s_add_u32 m0, s87, 0x4000
	s_add_u32 s88, s60, s22
	s_addc_u32 s89, s61, s23
	global_load_lds_dwordx4 v144, s[88:89]
	v_mfma_f32_16x16x32_bf16 v[44:47], v[176:179], v[206:209], v[44:47]
	v_mfma_f32_16x16x32_bf16 v[36:39], v[176:179], v[210:213], v[36:39]
	s_add_u32 m0, s87, 0x6000
	s_add_u32 s88, s60, s40
	s_addc_u32 s89, s61, s41
	global_load_lds_dwordx4 v144, s[88:89]
	v_mfma_f32_16x16x32_bf16 v[40:43], v[176:179], v[214:217], v[40:43]
	v_mfma_f32_16x16x32_bf16 v[32:35], v[176:179], v[218:221], v[32:35]
	s_add_u32 m0, s87, 0x8000
	s_add_u32 s88, s60, s42
	s_addc_u32 s89, s61, s43
	global_load_lds_dwordx4 v145, s[88:89]
	v_mfma_f32_16x16x32_bf16 v[28:31], v[182:185], v[206:209], v[28:31]
	v_mfma_f32_16x16x32_bf16 v[16:19], v[182:185], v[210:213], v[16:19]
	s_add_u32 m0, s87, 0xa000
	s_add_u32 s88, s60, s52
	s_addc_u32 s89, s61, s53
	global_load_lds_dwordx4 v145, s[88:89]
	v_mfma_f32_16x16x32_bf16 v[24:27], v[182:185], v[214:217], v[24:27]
	v_mfma_f32_16x16x32_bf16 v[12:15], v[182:185], v[218:221], v[12:15]
	s_add_u32 m0, s87, 0xc000
	s_add_u32 s88, s60, s54
	s_addc_u32 s89, s61, s55
	global_load_lds_dwordx4 v145, s[88:89]
	v_mfma_f32_16x16x32_bf16 v[4:7], v[186:189], v[206:209], v[4:7]
	v_mfma_f32_16x16x32_bf16 v[0:3], v[186:189], v[210:213], v[0:3]
	s_add_u32 m0, s87, 0xe000
	s_add_u32 s88, s60, s56
	s_addc_u32 s89, s61, s57
	global_load_lds_dwordx4 v145, s[88:89]
	v_mfma_f32_16x16x32_bf16 v[20:23], v[186:189], v[214:217], v[20:23]
	v_mfma_f32_16x16x32_bf16 v[8:11], v[186:189], v[218:221], v[8:11]
.Lg0_entry:
	ds_read_b128 v[172:175], v143 offset:8192
	ds_read_b128 v[176:179], v143 offset:10240
	ds_read_b128 v[182:185], v143 offset:12288
	ds_read_b128 v[186:189], v143 offset:14336
	s_waitcnt lgkmcnt(4)
	v_mfma_f32_16x16x32_bf16 v[124:127], v[156:159], v[190:193], v[124:127]
	v_mfma_f32_16x16x32_bf16 v[116:119], v[156:159], v[194:197], v[116:119]
	v_mfma_f32_16x16x32_bf16 v[120:123], v[156:159], v[198:201], v[120:123]
	v_mfma_f32_16x16x32_bf16 v[112:115], v[156:159], v[202:205], v[112:115]
	v_mfma_f32_16x16x32_bf16 v[108:111], v[160:163], v[190:193], v[108:111]
	v_mfma_f32_16x16x32_bf16 v[100:103], v[160:163], v[194:197], v[100:103]
	v_mfma_f32_16x16x32_bf16 v[104:107], v[160:163], v[198:201], v[104:107]
	v_mfma_f32_16x16x32_bf16 v[96:99], v[160:163], v[202:205], v[96:99]
	v_mfma_f32_16x16x32_bf16 v[92:95], v[164:167], v[190:193], v[92:95]
	v_mfma_f32_16x16x32_bf16 v[84:87], v[164:167], v[194:197], v[84:87]
	v_mfma_f32_16x16x32_bf16 v[88:91], v[164:167], v[198:201], v[88:91]
	v_mfma_f32_16x16x32_bf16 v[80:83], v[164:167], v[202:205], v[80:83]
	v_mfma_f32_16x16x32_bf16 v[76:79], v[168:171], v[190:193], v[76:79]
	v_mfma_f32_16x16x32_bf16 v[68:71], v[168:171], v[194:197], v[68:71]
	v_mfma_f32_16x16x32_bf16 v[72:75], v[168:171], v[198:201], v[72:75]
	v_mfma_f32_16x16x32_bf16 v[64:67], v[168:171], v[202:205], v[64:67]
	ds_read_b128 v[156:159], v155
	ds_read_b128 v[160:163], v155 offset:2048
	ds_read_b128 v[164:167], v155 offset:4096
	ds_read_b128 v[168:171], v155 offset:6144
	ds_read_b128 v[206:209], v222 offset:32768
	ds_read_b128 v[210:213], v222 offset:34816
	ds_read_b128 v[214:217], v222 offset:36864
	ds_read_b128 v[218:221], v222 offset:38912
	s_waitcnt lgkmcnt(8)
	v_mfma_f32_16x16x32_bf16 v[60:63], v[172:175], v[190:193], v[60:63]
	v_mfma_f32_16x16x32_bf16 v[52:55], v[172:175], v[194:197], v[52:55]
	v_mfma_f32_16x16x32_bf16 v[56:59], v[172:175], v[198:201], v[56:59]
	v_mfma_f32_16x16x32_bf16 v[48:51], v[172:175], v[202:205], v[48:51]
	v_mfma_f32_16x16x32_bf16 v[44:47], v[176:179], v[190:193], v[44:47]
	v_mfma_f32_16x16x32_bf16 v[36:39], v[176:179], v[194:197], v[36:39]
	v_mfma_f32_16x16x32_bf16 v[40:43], v[176:179], v[198:201], v[40:43]
	v_mfma_f32_16x16x32_bf16 v[32:35], v[176:179], v[202:205], v[32:35]
	v_mfma_f32_16x16x32_bf16 v[28:31], v[182:185], v[190:193], v[28:31]
	v_mfma_f32_16x16x32_bf16 v[16:19], v[182:185], v[194:197], v[16:19]
	v_mfma_f32_16x16x32_bf16 v[24:27], v[182:185], v[198:201], v[24:27]
	v_mfma_f32_16x16x32_bf16 v[12:15], v[182:185], v[202:205], v[12:15]
	v_mfma_f32_16x16x32_bf16 v[4:7], v[186:189], v[190:193], v[4:7]
	v_mfma_f32_16x16x32_bf16 v[0:3], v[186:189], v[194:197], v[0:3]
	v_mfma_f32_16x16x32_bf16 v[20:23], v[186:189], v[198:201], v[20:23]
	v_mfma_f32_16x16x32_bf16 v[8:11], v[186:189], v[202:205], v[8:11]
	ds_read_b128 v[172:175], v155 offset:8192
	ds_read_b128 v[176:179], v155 offset:10240
	ds_read_b128 v[182:185], v155 offset:12288
	ds_read_b128 v[186:189], v155 offset:14336
	s_waitcnt lgkmcnt(4)
	v_mfma_f32_16x16x32_bf16 v[124:127], v[156:159], v[206:209], v[124:127]
	v_mfma_f32_16x16x32_bf16 v[116:119], v[156:159], v[210:213], v[116:119]
	v_mfma_f32_16x16x32_bf16 v[120:123], v[156:159], v[214:217], v[120:123]
	v_mfma_f32_16x16x32_bf16 v[112:115], v[156:159], v[218:221], v[112:115]
	v_mfma_f32_16x16x32_bf16 v[108:111], v[160:163], v[206:209], v[108:111]
	v_mfma_f32_16x16x32_bf16 v[100:103], v[160:163], v[210:213], v[100:103]
	v_mfma_f32_16x16x32_bf16 v[104:107], v[160:163], v[214:217], v[104:107]
	v_mfma_f32_16x16x32_bf16 v[96:99], v[160:163], v[218:221], v[96:99]
	v_mfma_f32_16x16x32_bf16 v[92:95], v[164:167], v[206:209], v[92:95]
	v_mfma_f32_16x16x32_bf16 v[84:87], v[164:167], v[210:213], v[84:87]
	v_mfma_f32_16x16x32_bf16 v[88:91], v[164:167], v[214:217], v[88:91]
	v_mfma_f32_16x16x32_bf16 v[80:83], v[164:167], v[218:221], v[80:83]
	v_mfma_f32_16x16x32_bf16 v[76:79], v[168:171], v[206:209], v[76:79]
	v_mfma_f32_16x16x32_bf16 v[68:71], v[168:171], v[210:213], v[68:71]
	v_mfma_f32_16x16x32_bf16 v[72:75], v[168:171], v[214:217], v[72:75]
	v_mfma_f32_16x16x32_bf16 v[64:67], v[168:171], v[218:221], v[64:67]
	s_add_u32 s60, s60, 0x80
	s_addc_u32 s61, s61, 0
	s_add_i32 s59, s59, 1
	s_cmp_lt_u32 s59, 15
	s_cbranch_scc0 .Lg0_last
	s_waitcnt lgkmcnt(0)
	s_waitcnt vmcnt(0)
	s_barrier
	v_mfma_f32_16x16x32_bf16 v[60:63], v[172:175], v[206:209], v[60:63]
	v_mfma_f32_16x16x32_bf16 v[52:55], v[172:175], v[210:213], v[52:55]
	s_xor_b32 s87, s87, 0x10000
	s_mov_b32 m0, s87
	s_add_u32 s88, s60, s16
	s_addc_u32 s89, s61, s17
	global_load_lds_dwordx4 v144, s[88:89]
	s_add_u32 m0, s87, 0x2000
	s_add_u32 s88, s60, s18
	s_addc_u32 s89, s61, s19
	global_load_lds_dwordx4 v144, s[88:89]
	ds_read_b128 v[156:159], v223
	ds_read_b128 v[160:163], v223 offset:2048
	ds_read_b128 v[164:167], v223 offset:4096
	ds_read_b128 v[168:171], v223 offset:6144
	ds_read_b128 v[190:193], v225 offset:32768
	ds_read_b128 v[194:197], v225 offset:34816
	ds_read_b128 v[198:201], v225 offset:36864
	ds_read_b128 v[202:205], v225 offset:38912
	v_mfma_f32_16x16x32_bf16 v[56:59], v[172:175], v[214:217], v[56:59]
	v_mfma_f32_16x16x32_bf16 v[48:51], v[172:175], v[218:221], v[48:51]
	s_add_u32 m0, s87, 0x4000
	s_add_u32 s88, s60, s22
	s_addc_u32 s89, s61, s23
	global_load_lds_dwordx4 v144, s[88:89]
	v_mfma_f32_16x16x32_bf16 v[44:47], v[176:179], v[206:209], v[44:47]
	v_mfma_f32_16x16x32_bf16 v[36:39], v[176:179], v[210:213], v[36:39]
	s_add_u32 m0, s87, 0x6000
	s_add_u32 s88, s60, s40
	s_addc_u32 s89, s61, s41
	global_load_lds_dwordx4 v144, s[88:89]
	v_mfma_f32_16x16x32_bf16 v[40:43], v[176:179], v[214:217], v[40:43]
	v_mfma_f32_16x16x32_bf16 v[32:35], v[176:179], v[218:221], v[32:35]
	s_add_u32 m0, s87, 0x8000
	s_add_u32 s88, s60, s42
	s_addc_u32 s89, s61, s43
	global_load_lds_dwordx4 v145, s[88:89]
	v_mfma_f32_16x16x32_bf16 v[28:31], v[182:185], v[206:209], v[28:31]
	v_mfma_f32_16x16x32_bf16 v[16:19], v[182:185], v[210:213], v[16:19]
	s_add_u32 m0, s87, 0xa000
	s_add_u32 s88, s60, s52
	s_addc_u32 s89, s61, s53
	global_load_lds_dwordx4 v145, s[88:89]
	v_mfma_f32_16x16x32_bf16 v[24:27], v[182:185], v[214:217], v[24:27]
	v_mfma_f32_16x16x32_bf16 v[12:15], v[182:185], v[218:221], v[12:15]
	s_add_u32 m0, s87, 0xc000
	s_add_u32 s88, s60, s54
	s_addc_u32 s89, s61, s55
	global_load_lds_dwordx4 v145, s[88:89]
	v_mfma_f32_16x16x32_bf16 v[4:7], v[186:189], v[206:209], v[4:7]
	v_mfma_f32_16x16x32_bf16 v[0:3], v[186:189], v[210:213], v[0:3]
	s_add_u32 m0, s87, 0xe000
	s_add_u32 s88, s60, s56
	s_addc_u32 s89, s61, s57
	global_load_lds_dwordx4 v145, s[88:89]
	v_mfma_f32_16x16x32_bf16 v[20:23], v[186:189], v[214:217], v[20:23]
	v_mfma_f32_16x16x32_bf16 v[8:11], v[186:189], v[218:221], v[8:11]
	ds_read_b128 v[172:175], v223 offset:8192
	ds_read_b128 v[176:179], v223 offset:10240
	ds_read_b128 v[182:185], v223 offset:12288
	ds_read_b128 v[186:189], v223 offset:14336
	s_waitcnt lgkmcnt(4)
	v_mfma_f32_16x16x32_bf16 v[124:127], v[156:159], v[190:193], v[124:127]
	v_mfma_f32_16x16x32_bf16 v[116:119], v[156:159], v[194:197], v[116:119]
	v_mfma_f32_16x16x32_bf16 v[120:123], v[156:159], v[198:201], v[120:123]
	v_mfma_f32_16x16x32_bf16 v[112:115], v[156:159], v[202:205], v[112:115]
	v_mfma_f32_16x16x32_bf16 v[108:111], v[160:163], v[190:193], v[108:111]
	v_mfma_f32_16x16x32_bf16 v[100:103], v[160:163], v[194:197], v[100:103]
	v_mfma_f32_16x16x32_bf16 v[104:107], v[160:163], v[198:201], v[104:107]
	v_mfma_f32_16x16x32_bf16 v[96:99], v[160:163], v[202:205], v[96:99]
	v_mfma_f32_16x16x32_bf16 v[92:95], v[164:167], v[190:193], v[92:95]
	v_mfma_f32_16x16x32_bf16 v[84:87], v[164:167], v[194:197], v[84:87]
	v_mfma_f32_16x16x32_bf16 v[88:91], v[164:167], v[198:201], v[88:91]
	v_mfma_f32_16x16x32_bf16 v[80:83], v[164:167], v[202:205], v[80:83]
	v_mfma_f32_16x16x32_bf16 v[76:79], v[168:171], v[190:193], v[76:79]
	v_mfma_f32_16x16x32_bf16 v[68:71], v[168:171], v[194:197], v[68:71]
	v_mfma_f32_16x16x32_bf16 v[72:75], v[168:171], v[198:201], v[72:75]
	v_mfma_f32_16x16x32_bf16 v[64:67], v[168:171], v[202:205], v[64:67]
	ds_read_b128 v[156:159], v224
	ds_read_b128 v[160:163], v224 offset:2048
	ds_read_b128 v[164:167], v224 offset:4096
	ds_read_b128 v[168:171], v224 offset:6144
	ds_read_b128 v[206:209], v226 offset:32768
	ds_read_b128 v[210:213], v226 offset:34816
	ds_read_b128 v[214:217], v226 offset:36864
	ds_read_b128 v[218:221], v226 offset:38912
	s_waitcnt lgkmcnt(8)
	v_mfma_f32_16x16x32_bf16 v[60:63], v[172:175], v[190:193], v[60:63]
	v_mfma_f32_16x16x32_bf16 v[52:55], v[172:175], v[194:197], v[52:55]
	v_mfma_f32_16x16x32_bf16 v[56:59], v[172:175], v[198:201], v[56:59]
	v_mfma_f32_16x16x32_bf16 v[48:51], v[172:175], v[202:205], v[48:51]
	v_mfma_f32_16x16x32_bf16 v[44:47], v[176:179], v[190:193], v[44:47]
	v_mfma_f32_16x16x32_bf16 v[36:39], v[176:179], v[194:197], v[36:39]
	v_mfma_f32_16x16x32_bf16 v[40:43], v[176:179], v[198:201], v[40:43]
	v_mfma_f32_16x16x32_bf16 v[32:35], v[176:179], v[202:205], v[32:35]
	v_mfma_f32_16x16x32_bf16 v[28:31], v[182:185], v[190:193], v[28:31]
	v_mfma_f32_16x16x32_bf16 v[16:19], v[182:185], v[194:197], v[16:19]
	v_mfma_f32_16x16x32_bf16 v[24:27], v[182:185], v[198:201], v[24:27]
	v_mfma_f32_16x16x32_bf16 v[12:15], v[182:185], v[202:205], v[12:15]
	v_mfma_f32_16x16x32_bf16 v[4:7], v[186:189], v[190:193], v[4:7]
	v_mfma_f32_16x16x32_bf16 v[0:3], v[186:189], v[194:197], v[0:3]
	v_mfma_f32_16x16x32_bf16 v[20:23], v[186:189], v[198:201], v[20:23]
	v_mfma_f32_16x16x32_bf16 v[8:11], v[186:189], v[202:205], v[8:11]
	ds_read_b128 v[172:175], v224 offset:8192
	ds_read_b128 v[176:179], v224 offset:10240
	ds_read_b128 v[182:185], v224 offset:12288
	ds_read_b128 v[186:189], v224 offset:14336
	s_waitcnt lgkmcnt(4)
	v_mfma_f32_16x16x32_bf16 v[124:127], v[156:159], v[206:209], v[124:127]
	v_mfma_f32_16x16x32_bf16 v[116:119], v[156:159], v[210:213], v[116:119]
	v_mfma_f32_16x16x32_bf16 v[120:123], v[156:159], v[214:217], v[120:123]
	v_mfma_f32_16x16x32_bf16 v[112:115], v[156:159], v[218:221], v[112:115]
	v_mfma_f32_16x16x32_bf16 v[108:111], v[160:163], v[206:209], v[108:111]
	v_mfma_f32_16x16x32_bf16 v[100:103], v[160:163], v[210:213], v[100:103]
	v_mfma_f32_16x16x32_bf16 v[104:107], v[160:163], v[214:217], v[104:107]
	v_mfma_f32_16x16x32_bf16 v[96:99], v[160:163], v[218:221], v[96:99]
	v_mfma_f32_16x16x32_bf16 v[92:95], v[164:167], v[206:209], v[92:95]
	v_mfma_f32_16x16x32_bf16 v[84:87], v[164:167], v[210:213], v[84:87]
	v_mfma_f32_16x16x32_bf16 v[88:91], v[164:167], v[214:217], v[88:91]
	v_mfma_f32_16x16x32_bf16 v[80:83], v[164:167], v[218:221], v[80:83]
	v_mfma_f32_16x16x32_bf16 v[76:79], v[168:171], v[206:209], v[76:79]
	v_mfma_f32_16x16x32_bf16 v[68:71], v[168:171], v[210:213], v[68:71]
	v_mfma_f32_16x16x32_bf16 v[72:75], v[168:171], v[214:217], v[72:75]
	v_mfma_f32_16x16x32_bf16 v[64:67], v[168:171], v[218:221], v[64:67]
	s_add_u32 s60, s60, 0x80
	s_addc_u32 s61, s61, 0
	s_add_i32 s59, s59, 1
	s_branch .Lg0_top
.Lg0_last:
	s_waitcnt lgkmcnt(0)
	s_waitcnt vmcnt(0)
	s_barrier
	v_mfma_f32_16x16x32_bf16 v[60:63], v[172:175], v[206:209], v[60:63]
	v_mfma_f32_16x16x32_bf16 v[52:55], v[172:175], v[210:213], v[52:55]
	s_xor_b32 s87, s87, 0x10000
	ds_read_b128 v[156:159], v223
	ds_read_b128 v[160:163], v223 offset:2048
	ds_read_b128 v[164:167], v223 offset:4096
	ds_read_b128 v[168:171], v223 offset:6144
	ds_read_b128 v[190:193], v225 offset:32768
	ds_read_b128 v[194:197], v225 offset:34816
	ds_read_b128 v[198:201], v225 offset:36864
	ds_read_b128 v[202:205], v225 offset:38912
	v_mfma_f32_16x16x32_bf16 v[56:59], v[172:175], v[214:217], v[56:59]
	v_mfma_f32_16x16x32_bf16 v[48:51], v[172:175], v[218:221], v[48:51]
	v_mfma_f32_16x16x32_bf16 v[44:47], v[176:179], v[206:209], v[44:47]
	v_mfma_f32_16x16x32_bf16 v[36:39], v[176:179], v[210:213], v[36:39]
	v_mfma_f32_16x16x32_bf16 v[40:43], v[176:179], v[214:217], v[40:43]
	v_mfma_f32_16x16x32_bf16 v[32:35], v[176:179], v[218:221], v[32:35]
	v_mfma_f32_16x16x32_bf16 v[28:31], v[182:185], v[206:209], v[28:31]
	v_mfma_f32_16x16x32_bf16 v[16:19], v[182:185], v[210:213], v[16:19]
	v_mfma_f32_16x16x32_bf16 v[24:27], v[182:185], v[214:217], v[24:27]
	v_mfma_f32_16x16x32_bf16 v[12:15], v[182:185], v[218:221], v[12:15]
	v_mfma_f32_16x16x32_bf16 v[4:7], v[186:189], v[206:209], v[4:7]
	v_mfma_f32_16x16x32_bf16 v[0:3], v[186:189], v[210:213], v[0:3]
	v_mfma_f32_16x16x32_bf16 v[20:23], v[186:189], v[214:217], v[20:23]
	v_mfma_f32_16x16x32_bf16 v[8:11], v[186:189], v[218:221], v[8:11]
	ds_read_b128 v[172:175], v223 offset:8192
	ds_read_b128 v[176:179], v223 offset:10240
	ds_read_b128 v[182:185], v223 offset:12288
	ds_read_b128 v[186:189], v223 offset:14336
	s_waitcnt lgkmcnt(4)
	v_mfma_f32_16x16x32_bf16 v[124:127], v[156:159], v[190:193], v[124:127]
	v_mfma_f32_16x16x32_bf16 v[116:119], v[156:159], v[194:197], v[116:119]
	v_mfma_f32_16x16x32_bf16 v[120:123], v[156:159], v[198:201], v[120:123]
	v_mfma_f32_16x16x32_bf16 v[112:115], v[156:159], v[202:205], v[112:115]
	v_mfma_f32_16x16x32_bf16 v[108:111], v[160:163], v[190:193], v[108:111]
	v_mfma_f32_16x16x32_bf16 v[100:103], v[160:163], v[194:197], v[100:103]
	v_mfma_f32_16x16x32_bf16 v[104:107], v[160:163], v[198:201], v[104:107]
	v_mfma_f32_16x16x32_bf16 v[96:99], v[160:163], v[202:205], v[96:99]
	v_mfma_f32_16x16x32_bf16 v[92:95], v[164:167], v[190:193], v[92:95]
	v_mfma_f32_16x16x32_bf16 v[84:87], v[164:167], v[194:197], v[84:87]
	v_mfma_f32_16x16x32_bf16 v[88:91], v[164:167], v[198:201], v[88:91]
	v_mfma_f32_16x16x32_bf16 v[80:83], v[164:167], v[202:205], v[80:83]
	v_mfma_f32_16x16x32_bf16 v[76:79], v[168:171], v[190:193], v[76:79]
	v_mfma_f32_16x16x32_bf16 v[68:71], v[168:171], v[194:197], v[68:71]
	v_mfma_f32_16x16x32_bf16 v[72:75], v[168:171], v[198:201], v[72:75]
	v_mfma_f32_16x16x32_bf16 v[64:67], v[168:171], v[202:205], v[64:67]
	ds_read_b128 v[156:159], v224
	ds_read_b128 v[160:163], v224 offset:2048
	ds_read_b128 v[164:167], v224 offset:4096
	ds_read_b128 v[168:171], v224 offset:6144
	ds_read_b128 v[206:209], v226 offset:32768
	ds_read_b128 v[210:213], v226 offset:34816
	ds_read_b128 v[214:217], v226 offset:36864
	ds_read_b128 v[218:221], v226 offset:38912
	s_waitcnt lgkmcnt(8)
	v_mfma_f32_16x16x32_bf16 v[60:63], v[172:175], v[190:193], v[60:63]
	v_mfma_f32_16x16x32_bf16 v[52:55], v[172:175], v[194:197], v[52:55]
	v_mfma_f32_16x16x32_bf16 v[56:59], v[172:175], v[198:201], v[56:59]
	v_mfma_f32_16x16x32_bf16 v[48:51], v[172:175], v[202:205], v[48:51]
	v_mfma_f32_16x16x32_bf16 v[44:47], v[176:179], v[190:193], v[44:47]
	v_mfma_f32_16x16x32_bf16 v[36:39], v[176:179], v[194:197], v[36:39]
	v_mfma_f32_16x16x32_bf16 v[40:43], v[176:179], v[198:201], v[40:43]
	v_mfma_f32_16x16x32_bf16 v[32:35], v[176:179], v[202:205], v[32:35]
	v_mfma_f32_16x16x32_bf16 v[28:31], v[182:185], v[190:193], v[28:31]
	v_mfma_f32_16x16x32_bf16 v[16:19], v[182:185], v[194:197], v[16:19]
	v_mfma_f32_16x16x32_bf16 v[24:27], v[182:185], v[198:201], v[24:27]
	v_mfma_f32_16x16x32_bf16 v[12:15], v[182:185], v[202:205], v[12:15]
	v_mfma_f32_16x16x32_bf16 v[4:7], v[186:189], v[190:193], v[4:7]
	v_mfma_f32_16x16x32_bf16 v[0:3], v[186:189], v[194:197], v[0:3]
	v_mfma_f32_16x16x32_bf16 v[20:23], v[186:189], v[198:201], v[20:23]
	v_mfma_f32_16x16x32_bf16 v[8:11], v[186:189], v[202:205], v[8:11]
	ds_read_b128 v[172:175], v224 offset:8192
	ds_read_b128 v[176:179], v224 offset:10240
	ds_read_b128 v[182:185], v224 offset:12288
	ds_read_b128 v[186:189], v224 offset:14336
	s_waitcnt lgkmcnt(4)
	v_mfma_f32_16x16x32_bf16 v[124:127], v[156:159], v[206:209], v[124:127]
	v_mfma_f32_16x16x32_bf16 v[116:119], v[156:159], v[210:213], v[116:119]
	v_mfma_f32_16x16x32_bf16 v[120:123], v[156:159], v[214:217], v[120:123]
	v_mfma_f32_16x16x32_bf16 v[112:115], v[156:159], v[218:221], v[112:115]
	v_mfma_f32_16x16x32_bf16 v[108:111], v[160:163], v[206:209], v[108:111]
	v_mfma_f32_16x16x32_bf16 v[100:103], v[160:163], v[210:213], v[100:103]
	v_mfma_f32_16x16x32_bf16 v[104:107], v[160:163], v[214:217], v[104:107]
	v_mfma_f32_16x16x32_bf16 v[96:99], v[160:163], v[218:221], v[96:99]
	v_mfma_f32_16x16x32_bf16 v[92:95], v[164:167], v[206:209], v[92:95]
	v_mfma_f32_16x16x32_bf16 v[84:87], v[164:167], v[210:213], v[84:87]
	v_mfma_f32_16x16x32_bf16 v[88:91], v[164:167], v[214:217], v[88:91]
	v_mfma_f32_16x16x32_bf16 v[80:83], v[164:167], v[218:221], v[80:83]
	v_mfma_f32_16x16x32_bf16 v[76:79], v[168:171], v[206:209], v[76:79]
	v_mfma_f32_16x16x32_bf16 v[68:71], v[168:171], v[210:213], v[68:71]
	v_mfma_f32_16x16x32_bf16 v[72:75], v[168:171], v[214:217], v[72:75]
	v_mfma_f32_16x16x32_bf16 v[64:67], v[168:171], v[218:221], v[64:67]
	s_add_u32 s60, s60, 0x80
	s_addc_u32 s61, s61, 0
	s_add_i32 s59, s59, 1
	s_waitcnt lgkmcnt(0)
	s_waitcnt vmcnt(0)
	s_barrier
	v_mfma_f32_16x16x32_bf16 v[60:63], v[172:175], v[206:209], v[60:63]
	v_mfma_f32_16x16x32_bf16 v[52:55], v[172:175], v[210:213], v[52:55]
	v_mfma_f32_16x16x32_bf16 v[56:59], v[172:175], v[214:217], v[56:59]
	v_mfma_f32_16x16x32_bf16 v[48:51], v[172:175], v[218:221], v[48:51]
	v_mfma_f32_16x16x32_bf16 v[44:47], v[176:179], v[206:209], v[44:47]
	v_mfma_f32_16x16x32_bf16 v[36:39], v[176:179], v[210:213], v[36:39]
	v_mfma_f32_16x16x32_bf16 v[40:43], v[176:179], v[214:217], v[40:43]
	v_mfma_f32_16x16x32_bf16 v[32:35], v[176:179], v[218:221], v[32:35]
	v_mfma_f32_16x16x32_bf16 v[28:31], v[182:185], v[206:209], v[28:31]
	v_mfma_f32_16x16x32_bf16 v[16:19], v[182:185], v[210:213], v[16:19]
	v_mfma_f32_16x16x32_bf16 v[24:27], v[182:185], v[214:217], v[24:27]
	v_mfma_f32_16x16x32_bf16 v[12:15], v[182:185], v[218:221], v[12:15]
	v_mfma_f32_16x16x32_bf16 v[4:7], v[186:189], v[206:209], v[4:7]
	v_mfma_f32_16x16x32_bf16 v[0:3], v[186:189], v[210:213], v[0:3]
	v_mfma_f32_16x16x32_bf16 v[20:23], v[186:189], v[214:217], v[20:23]
	v_mfma_f32_16x16x32_bf16 v[8:11], v[186:189], v[218:221], v[8:11]
	s_nop 7
	s_nop 7
	s_sub_u32 s60, s60, s34
	s_subb_u32 s61, s61, s35
	s_mov_b32 s87, 0x80000
	s_mov_b32 s96, 0x80000
	s_mov_b64 s[88:89], 0
	s_mov_b64 vcc, exec
	s_branch .LBB0_120

.Lg1_top:
	s_waitcnt lgkmcnt(0)
	s_waitcnt vmcnt(0)
	s_barrier
	v_mfma_f32_16x16x32_bf16 v[60:63], v[158:161], v[194:197], v[60:63]
	v_mfma_f32_16x16x32_bf16 v[56:59], v[158:161], v[198:201], v[56:59]
	s_xor_b32 s59, s59, 0x10000
	s_mov_b32 m0, s59
	s_add_u32 s52, s50, s14
	s_addc_u32 s53, s51, s15
	global_load_lds_dwordx4 v178, s[52:53]
	s_add_u32 m0, s59, 0x2000
	s_add_u32 s52, s50, s16
	s_addc_u32 s53, s51, s17
	global_load_lds_dwordx4 v178, s[52:53]
	ds_read_b128 v[142:145], v141
	ds_read_b128 v[146:149], v141 offset:2048
	ds_read_b128 v[150:153], v141 offset:4096
	ds_read_b128 v[154:157], v141 offset:6144
	ds_read_b128 v[174:177], v210 offset:32768
	ds_read_b128 v[182:185], v210 offset:34816
	ds_read_b128 v[186:189], v210 offset:36864
	ds_read_b128 v[190:193], v210 offset:38912
	v_mfma_f32_16x16x32_bf16 v[52:55], v[158:161], v[202:205], v[52:55]
	v_mfma_f32_16x16x32_bf16 v[48:51], v[158:161], v[206:209], v[48:51]
	s_add_u32 m0, s59, 0x4000
	s_add_u32 s52, s50, s18
	s_addc_u32 s53, s51, s19
	global_load_lds_dwordx4 v178, s[52:53]
	v_mfma_f32_16x16x32_bf16 v[44:47], v[162:165], v[194:197], v[44:47]
	v_mfma_f32_16x16x32_bf16 v[40:43], v[162:165], v[198:201], v[40:43]
	s_add_u32 m0, s59, 0x6000
	s_add_u32 s52, s50, s22
	s_addc_u32 s53, s51, s23
	global_load_lds_dwordx4 v178, s[52:53]
	v_mfma_f32_16x16x32_bf16 v[36:39], v[162:165], v[202:205], v[36:39]
	v_mfma_f32_16x16x32_bf16 v[32:35], v[162:165], v[206:209], v[32:35]
	s_add_u32 m0, s59, 0x8000
	s_add_u32 s52, s50, s40
	s_addc_u32 s53, s51, s41
	global_load_lds_dwordx4 v179, s[52:53]
	v_mfma_f32_16x16x32_bf16 v[28:31], v[166:169], v[194:197], v[28:31]
	v_mfma_f32_16x16x32_bf16 v[20:23], v[166:169], v[198:201], v[20:23]
	s_add_u32 m0, s59, 0xa000
	s_add_u32 s52, s50, s42
	s_addc_u32 s53, s51, s43
	global_load_lds_dwordx4 v179, s[52:53]
	v_mfma_f32_16x16x32_bf16 v[16:19], v[166:169], v[202:205], v[16:19]
	v_mfma_f32_16x16x32_bf16 v[8:11], v[166:169], v[206:209], v[8:11]
	s_add_u32 m0, s59, 0xc000
	s_add_u32 s52, s50, s44
	s_addc_u32 s53, s51, s45
	global_load_lds_dwordx4 v179, s[52:53]
	v_mfma_f32_16x16x32_bf16 v[4:7], v[170:173], v[194:197], v[4:7]
	v_mfma_f32_16x16x32_bf16 v[0:3], v[170:173], v[198:201], v[0:3]
	s_add_u32 m0, s59, 0xe000
	s_add_u32 s52, s50, s46
	s_addc_u32 s53, s51, s47
	global_load_lds_dwordx4 v179, s[52:53]
	v_mfma_f32_16x16x32_bf16 v[24:27], v[170:173], v[202:205], v[24:27]
	v_mfma_f32_16x16x32_bf16 v[12:15], v[170:173], v[206:209], v[12:15]
.Lg1_entry:
	ds_read_b128 v[158:161], v141 offset:8192
	ds_read_b128 v[162:165], v141 offset:10240
	ds_read_b128 v[166:169], v141 offset:12288
	ds_read_b128 v[170:173], v141 offset:14336
	s_waitcnt lgkmcnt(4)
	v_mfma_f32_16x16x32_bf16 v[124:127], v[142:145], v[174:177], v[124:127]
	v_mfma_f32_16x16x32_bf16 v[120:123], v[142:145], v[182:185], v[120:123]
	v_mfma_f32_16x16x32_bf16 v[116:119], v[142:145], v[186:189], v[116:119]
	v_mfma_f32_16x16x32_bf16 v[112:115], v[142:145], v[190:193], v[112:115]
	v_mfma_f32_16x16x32_bf16 v[108:111], v[146:149], v[174:177], v[108:111]
	v_mfma_f32_16x16x32_bf16 v[104:107], v[146:149], v[182:185], v[104:107]
	v_mfma_f32_16x16x32_bf16 v[100:103], v[146:149], v[186:189], v[100:103]
	v_mfma_f32_16x16x32_bf16 v[96:99], v[146:149], v[190:193], v[96:99]
	v_mfma_f32_16x16x32_bf16 v[92:95], v[150:153], v[174:177], v[92:95]
	v_mfma_f32_16x16x32_bf16 v[88:91], v[150:153], v[182:185], v[88:91]
	v_mfma_f32_16x16x32_bf16 v[84:87], v[150:153], v[186:189], v[84:87]
	v_mfma_f32_16x16x32_bf16 v[80:83], v[150:153], v[190:193], v[80:83]
	v_mfma_f32_16x16x32_bf16 v[76:79], v[154:157], v[174:177], v[76:79]
	v_mfma_f32_16x16x32_bf16 v[72:75], v[154:157], v[182:185], v[72:75]
	v_mfma_f32_16x16x32_bf16 v[68:71], v[154:157], v[186:189], v[68:71]
	v_mfma_f32_16x16x32_bf16 v[64:67], v[154:157], v[190:193], v[64:67]
	ds_read_b128 v[142:145], v180
	ds_read_b128 v[146:149], v180 offset:2048
	ds_read_b128 v[150:153], v180 offset:4096
	ds_read_b128 v[154:157], v180 offset:6144
	ds_read_b128 v[194:197], v211 offset:32768
	ds_read_b128 v[198:201], v211 offset:34816
	ds_read_b128 v[202:205], v211 offset:36864
	ds_read_b128 v[206:209], v211 offset:38912
	s_waitcnt lgkmcnt(8)
	v_mfma_f32_16x16x32_bf16 v[60:63], v[158:161], v[174:177], v[60:63]
	v_mfma_f32_16x16x32_bf16 v[56:59], v[158:161], v[182:185], v[56:59]
	v_mfma_f32_16x16x32_bf16 v[52:55], v[158:161], v[186:189], v[52:55]
	v_mfma_f32_16x16x32_bf16 v[48:51], v[158:161], v[190:193], v[48:51]
	v_mfma_f32_16x16x32_bf16 v[44:47], v[162:165], v[174:177], v[44:47]
	v_mfma_f32_16x16x32_bf16 v[40:43], v[162:165], v[182:185], v[40:43]
	v_mfma_f32_16x16x32_bf16 v[36:39], v[162:165], v[186:189], v[36:39]
	v_mfma_f32_16x16x32_bf16 v[32:35], v[162:165], v[190:193], v[32:35]
	v_mfma_f32_16x16x32_bf16 v[28:31], v[166:169], v[174:177], v[28:31]
	v_mfma_f32_16x16x32_bf16 v[20:23], v[166:169], v[182:185], v[20:23]
	v_mfma_f32_16x16x32_bf16 v[16:19], v[166:169], v[186:189], v[16:19]
	v_mfma_f32_16x16x32_bf16 v[8:11], v[166:169], v[190:193], v[8:11]
	v_mfma_f32_16x16x32_bf16 v[4:7], v[170:173], v[174:177], v[4:7]
	v_mfma_f32_16x16x32_bf16 v[0:3], v[170:173], v[182:185], v[0:3]
	v_mfma_f32_16x16x32_bf16 v[24:27], v[170:173], v[186:189], v[24:27]
	v_mfma_f32_16x16x32_bf16 v[12:15], v[170:173], v[190:193], v[12:15]
	ds_read_b128 v[158:161], v180 offset:8192
	ds_read_b128 v[162:165], v180 offset:10240
	ds_read_b128 v[166:169], v180 offset:12288
	ds_read_b128 v[170:173], v180 offset:14336
	s_waitcnt lgkmcnt(4)
	v_mfma_f32_16x16x32_bf16 v[124:127], v[142:145], v[194:197], v[124:127]
	v_mfma_f32_16x16x32_bf16 v[120:123], v[142:145], v[198:201], v[120:123]
	v_mfma_f32_16x16x32_bf16 v[116:119], v[142:145], v[202:205], v[116:119]
	v_mfma_f32_16x16x32_bf16 v[112:115], v[142:145], v[206:209], v[112:115]
	v_mfma_f32_16x16x32_bf16 v[108:111], v[146:149], v[194:197], v[108:111]
	v_mfma_f32_16x16x32_bf16 v[104:107], v[146:149], v[198:201], v[104:107]
	v_mfma_f32_16x16x32_bf16 v[100:103], v[146:149], v[202:205], v[100:103]
	v_mfma_f32_16x16x32_bf16 v[96:99], v[146:149], v[206:209], v[96:99]
	v_mfma_f32_16x16x32_bf16 v[92:95], v[150:153], v[194:197], v[92:95]
	v_mfma_f32_16x16x32_bf16 v[88:91], v[150:153], v[198:201], v[88:91]
	v_mfma_f32_16x16x32_bf16 v[84:87], v[150:153], v[202:205], v[84:87]
	v_mfma_f32_16x16x32_bf16 v[80:83], v[150:153], v[206:209], v[80:83]
	v_mfma_f32_16x16x32_bf16 v[76:79], v[154:157], v[194:197], v[76:79]
	v_mfma_f32_16x16x32_bf16 v[72:75], v[154:157], v[198:201], v[72:75]
	v_mfma_f32_16x16x32_bf16 v[68:71], v[154:157], v[202:205], v[68:71]
	v_mfma_f32_16x16x32_bf16 v[64:67], v[154:157], v[206:209], v[64:67]
	s_add_u32 s50, s50, 0x80
	s_addc_u32 s51, s51, 0
	s_add_i32 s49, s49, 1
	s_cmp_lt_u32 s49, 31
	s_cbranch_scc0 .Lg1_last
	s_waitcnt lgkmcnt(0)
	s_waitcnt vmcnt(0)
	s_barrier
	v_mfma_f32_16x16x32_bf16 v[60:63], v[158:161], v[194:197], v[60:63]
	v_mfma_f32_16x16x32_bf16 v[56:59], v[158:161], v[198:201], v[56:59]
	s_xor_b32 s59, s59, 0x10000
	s_mov_b32 m0, s59
	s_add_u32 s52, s50, s14
	s_addc_u32 s53, s51, s15
	global_load_lds_dwordx4 v178, s[52:53]
	s_add_u32 m0, s59, 0x2000
	s_add_u32 s52, s50, s16
	s_addc_u32 s53, s51, s17
	global_load_lds_dwordx4 v178, s[52:53]
	ds_read_b128 v[142:145], v212
	ds_read_b128 v[146:149], v212 offset:2048
	ds_read_b128 v[150:153], v212 offset:4096
	ds_read_b128 v[154:157], v212 offset:6144
	ds_read_b128 v[174:177], v214 offset:32768
	ds_read_b128 v[182:185], v214 offset:34816
	ds_read_b128 v[186:189], v214 offset:36864
	ds_read_b128 v[190:193], v214 offset:38912
	v_mfma_f32_16x16x32_bf16 v[52:55], v[158:161], v[202:205], v[52:55]
	v_mfma_f32_16x16x32_bf16 v[48:51], v[158:161], v[206:209], v[48:51]
	s_add_u32 m0, s59, 0x4000
	s_add_u32 s52, s50, s18
	s_addc_u32 s53, s51, s19
	global_load_lds_dwordx4 v178, s[52:53]
	v_mfma_f32_16x16x32_bf16 v[44:47], v[162:165], v[194:197], v[44:47]
	v_mfma_f32_16x16x32_bf16 v[40:43], v[162:165], v[198:201], v[40:43]
	s_add_u32 m0, s59, 0x6000
	s_add_u32 s52, s50, s22
	s_addc_u32 s53, s51, s23
	global_load_lds_dwordx4 v178, s[52:53]
	v_mfma_f32_16x16x32_bf16 v[36:39], v[162:165], v[202:205], v[36:39]
	v_mfma_f32_16x16x32_bf16 v[32:35], v[162:165], v[206:209], v[32:35]
	s_add_u32 m0, s59, 0x8000
	s_add_u32 s52, s50, s40
	s_addc_u32 s53, s51, s41
	global_load_lds_dwordx4 v179, s[52:53]
	v_mfma_f32_16x16x32_bf16 v[28:31], v[166:169], v[194:197], v[28:31]
	v_mfma_f32_16x16x32_bf16 v[20:23], v[166:169], v[198:201], v[20:23]
	s_add_u32 m0, s59, 0xa000
	s_add_u32 s52, s50, s42
	s_addc_u32 s53, s51, s43
	global_load_lds_dwordx4 v179, s[52:53]
	v_mfma_f32_16x16x32_bf16 v[16:19], v[166:169], v[202:205], v[16:19]
	v_mfma_f32_16x16x32_bf16 v[8:11], v[166:169], v[206:209], v[8:11]
	s_add_u32 m0, s59, 0xc000
	s_add_u32 s52, s50, s44
	s_addc_u32 s53, s51, s45
	global_load_lds_dwordx4 v179, s[52:53]
	v_mfma_f32_16x16x32_bf16 v[4:7], v[170:173], v[194:197], v[4:7]
	v_mfma_f32_16x16x32_bf16 v[0:3], v[170:173], v[198:201], v[0:3]
	s_add_u32 m0, s59, 0xe000
	s_add_u32 s52, s50, s46
	s_addc_u32 s53, s51, s47
	global_load_lds_dwordx4 v179, s[52:53]
	v_mfma_f32_16x16x32_bf16 v[24:27], v[170:173], v[202:205], v[24:27]
	v_mfma_f32_16x16x32_bf16 v[12:15], v[170:173], v[206:209], v[12:15]
	ds_read_b128 v[158:161], v212 offset:8192
	ds_read_b128 v[162:165], v212 offset:10240
	ds_read_b128 v[166:169], v212 offset:12288
	ds_read_b128 v[170:173], v212 offset:14336
	s_waitcnt lgkmcnt(4)
	v_mfma_f32_16x16x32_bf16 v[124:127], v[142:145], v[174:177], v[124:127]
	v_mfma_f32_16x16x32_bf16 v[120:123], v[142:145], v[182:185], v[120:123]
	v_mfma_f32_16x16x32_bf16 v[116:119], v[142:145], v[186:189], v[116:119]
	v_mfma_f32_16x16x32_bf16 v[112:115], v[142:145], v[190:193], v[112:115]
	v_mfma_f32_16x16x32_bf16 v[108:111], v[146:149], v[174:177], v[108:111]
	v_mfma_f32_16x16x32_bf16 v[104:107], v[146:149], v[182:185], v[104:107]
	v_mfma_f32_16x16x32_bf16 v[100:103], v[146:149], v[186:189], v[100:103]
	v_mfma_f32_16x16x32_bf16 v[96:99], v[146:149], v[190:193], v[96:99]
	v_mfma_f32_16x16x32_bf16 v[92:95], v[150:153], v[174:177], v[92:95]
	v_mfma_f32_16x16x32_bf16 v[88:91], v[150:153], v[182:185], v[88:91]
	v_mfma_f32_16x16x32_bf16 v[84:87], v[150:153], v[186:189], v[84:87]
	v_mfma_f32_16x16x32_bf16 v[80:83], v[150:153], v[190:193], v[80:83]
	v_mfma_f32_16x16x32_bf16 v[76:79], v[154:157], v[174:177], v[76:79]
	v_mfma_f32_16x16x32_bf16 v[72:75], v[154:157], v[182:185], v[72:75]
	v_mfma_f32_16x16x32_bf16 v[68:71], v[154:157], v[186:189], v[68:71]
	v_mfma_f32_16x16x32_bf16 v[64:67], v[154:157], v[190:193], v[64:67]
	ds_read_b128 v[142:145], v213
	ds_read_b128 v[146:149], v213 offset:2048
	ds_read_b128 v[150:153], v213 offset:4096
	ds_read_b128 v[154:157], v213 offset:6144
	ds_read_b128 v[194:197], v215 offset:32768
	ds_read_b128 v[198:201], v215 offset:34816
	ds_read_b128 v[202:205], v215 offset:36864
	ds_read_b128 v[206:209], v215 offset:38912
	s_waitcnt lgkmcnt(8)
	v_mfma_f32_16x16x32_bf16 v[60:63], v[158:161], v[174:177], v[60:63]
	v_mfma_f32_16x16x32_bf16 v[56:59], v[158:161], v[182:185], v[56:59]
	v_mfma_f32_16x16x32_bf16 v[52:55], v[158:161], v[186:189], v[52:55]
	v_mfma_f32_16x16x32_bf16 v[48:51], v[158:161], v[190:193], v[48:51]
	v_mfma_f32_16x16x32_bf16 v[44:47], v[162:165], v[174:177], v[44:47]
	v_mfma_f32_16x16x32_bf16 v[40:43], v[162:165], v[182:185], v[40:43]
	v_mfma_f32_16x16x32_bf16 v[36:39], v[162:165], v[186:189], v[36:39]
	v_mfma_f32_16x16x32_bf16 v[32:35], v[162:165], v[190:193], v[32:35]
	v_mfma_f32_16x16x32_bf16 v[28:31], v[166:169], v[174:177], v[28:31]
	v_mfma_f32_16x16x32_bf16 v[20:23], v[166:169], v[182:185], v[20:23]
	v_mfma_f32_16x16x32_bf16 v[16:19], v[166:169], v[186:189], v[16:19]
	v_mfma_f32_16x16x32_bf16 v[8:11], v[166:169], v[190:193], v[8:11]
	v_mfma_f32_16x16x32_bf16 v[4:7], v[170:173], v[174:177], v[4:7]
	v_mfma_f32_16x16x32_bf16 v[0:3], v[170:173], v[182:185], v[0:3]
	v_mfma_f32_16x16x32_bf16 v[24:27], v[170:173], v[186:189], v[24:27]
	v_mfma_f32_16x16x32_bf16 v[12:15], v[170:173], v[190:193], v[12:15]
	ds_read_b128 v[158:161], v213 offset:8192
	ds_read_b128 v[162:165], v213 offset:10240
	ds_read_b128 v[166:169], v213 offset:12288
	ds_read_b128 v[170:173], v213 offset:14336
	s_waitcnt lgkmcnt(4)
	v_mfma_f32_16x16x32_bf16 v[124:127], v[142:145], v[194:197], v[124:127]
	v_mfma_f32_16x16x32_bf16 v[120:123], v[142:145], v[198:201], v[120:123]
	v_mfma_f32_16x16x32_bf16 v[116:119], v[142:145], v[202:205], v[116:119]
	v_mfma_f32_16x16x32_bf16 v[112:115], v[142:145], v[206:209], v[112:115]
	v_mfma_f32_16x16x32_bf16 v[108:111], v[146:149], v[194:197], v[108:111]
	v_mfma_f32_16x16x32_bf16 v[104:107], v[146:149], v[198:201], v[104:107]
	v_mfma_f32_16x16x32_bf16 v[100:103], v[146:149], v[202:205], v[100:103]
	v_mfma_f32_16x16x32_bf16 v[96:99], v[146:149], v[206:209], v[96:99]
	v_mfma_f32_16x16x32_bf16 v[92:95], v[150:153], v[194:197], v[92:95]
	v_mfma_f32_16x16x32_bf16 v[88:91], v[150:153], v[198:201], v[88:91]
	v_mfma_f32_16x16x32_bf16 v[84:87], v[150:153], v[202:205], v[84:87]
	v_mfma_f32_16x16x32_bf16 v[80:83], v[150:153], v[206:209], v[80:83]
	v_mfma_f32_16x16x32_bf16 v[76:79], v[154:157], v[194:197], v[76:79]
	v_mfma_f32_16x16x32_bf16 v[72:75], v[154:157], v[198:201], v[72:75]
	v_mfma_f32_16x16x32_bf16 v[68:71], v[154:157], v[202:205], v[68:71]
	v_mfma_f32_16x16x32_bf16 v[64:67], v[154:157], v[206:209], v[64:67]
	s_add_u32 s50, s50, 0x80
	s_addc_u32 s51, s51, 0
	s_add_i32 s49, s49, 1
	s_branch .Lg1_top
.Lg1_last:
	s_waitcnt lgkmcnt(0)
	s_waitcnt vmcnt(0)
	s_barrier
	v_mfma_f32_16x16x32_bf16 v[60:63], v[158:161], v[194:197], v[60:63]
	v_mfma_f32_16x16x32_bf16 v[56:59], v[158:161], v[198:201], v[56:59]
	s_xor_b32 s59, s59, 0x10000
	ds_read_b128 v[142:145], v212
	ds_read_b128 v[146:149], v212 offset:2048
	ds_read_b128 v[150:153], v212 offset:4096
	ds_read_b128 v[154:157], v212 offset:6144
	ds_read_b128 v[174:177], v214 offset:32768
	ds_read_b128 v[182:185], v214 offset:34816
	ds_read_b128 v[186:189], v214 offset:36864
	ds_read_b128 v[190:193], v214 offset:38912
	v_mfma_f32_16x16x32_bf16 v[52:55], v[158:161], v[202:205], v[52:55]
	v_mfma_f32_16x16x32_bf16 v[48:51], v[158:161], v[206:209], v[48:51]
	v_mfma_f32_16x16x32_bf16 v[44:47], v[162:165], v[194:197], v[44:47]
	v_mfma_f32_16x16x32_bf16 v[40:43], v[162:165], v[198:201], v[40:43]
	v_mfma_f32_16x16x32_bf16 v[36:39], v[162:165], v[202:205], v[36:39]
	v_mfma_f32_16x16x32_bf16 v[32:35], v[162:165], v[206:209], v[32:35]
	v_mfma_f32_16x16x32_bf16 v[28:31], v[166:169], v[194:197], v[28:31]
	v_mfma_f32_16x16x32_bf16 v[20:23], v[166:169], v[198:201], v[20:23]
	v_mfma_f32_16x16x32_bf16 v[16:19], v[166:169], v[202:205], v[16:19]
	v_mfma_f32_16x16x32_bf16 v[8:11], v[166:169], v[206:209], v[8:11]
	v_mfma_f32_16x16x32_bf16 v[4:7], v[170:173], v[194:197], v[4:7]
	v_mfma_f32_16x16x32_bf16 v[0:3], v[170:173], v[198:201], v[0:3]
	v_mfma_f32_16x16x32_bf16 v[24:27], v[170:173], v[202:205], v[24:27]
	v_mfma_f32_16x16x32_bf16 v[12:15], v[170:173], v[206:209], v[12:15]
	ds_read_b128 v[158:161], v212 offset:8192
	ds_read_b128 v[162:165], v212 offset:10240
	ds_read_b128 v[166:169], v212 offset:12288
	ds_read_b128 v[170:173], v212 offset:14336
	s_waitcnt lgkmcnt(4)
	v_mfma_f32_16x16x32_bf16 v[124:127], v[142:145], v[174:177], v[124:127]
	v_mfma_f32_16x16x32_bf16 v[120:123], v[142:145], v[182:185], v[120:123]
	v_mfma_f32_16x16x32_bf16 v[116:119], v[142:145], v[186:189], v[116:119]
	v_mfma_f32_16x16x32_bf16 v[112:115], v[142:145], v[190:193], v[112:115]
	v_mfma_f32_16x16x32_bf16 v[108:111], v[146:149], v[174:177], v[108:111]
	v_mfma_f32_16x16x32_bf16 v[104:107], v[146:149], v[182:185], v[104:107]
	v_mfma_f32_16x16x32_bf16 v[100:103], v[146:149], v[186:189], v[100:103]
	v_mfma_f32_16x16x32_bf16 v[96:99], v[146:149], v[190:193], v[96:99]
	v_mfma_f32_16x16x32_bf16 v[92:95], v[150:153], v[174:177], v[92:95]
	v_mfma_f32_16x16x32_bf16 v[88:91], v[150:153], v[182:185], v[88:91]
	v_mfma_f32_16x16x32_bf16 v[84:87], v[150:153], v[186:189], v[84:87]
	v_mfma_f32_16x16x32_bf16 v[80:83], v[150:153], v[190:193], v[80:83]
	v_mfma_f32_16x16x32_bf16 v[76:79], v[154:157], v[174:177], v[76:79]
	v_mfma_f32_16x16x32_bf16 v[72:75], v[154:157], v[182:185], v[72:75]
	v_mfma_f32_16x16x32_bf16 v[68:71], v[154:157], v[186:189], v[68:71]
	v_mfma_f32_16x16x32_bf16 v[64:67], v[154:157], v[190:193], v[64:67]
	ds_read_b128 v[142:145], v213
	ds_read_b128 v[146:149], v213 offset:2048
	ds_read_b128 v[150:153], v213 offset:4096
	ds_read_b128 v[154:157], v213 offset:6144
	ds_read_b128 v[194:197], v215 offset:32768
	ds_read_b128 v[198:201], v215 offset:34816
	ds_read_b128 v[202:205], v215 offset:36864
	ds_read_b128 v[206:209], v215 offset:38912
	s_waitcnt lgkmcnt(8)
	v_mfma_f32_16x16x32_bf16 v[60:63], v[158:161], v[174:177], v[60:63]
	v_mfma_f32_16x16x32_bf16 v[56:59], v[158:161], v[182:185], v[56:59]
	v_mfma_f32_16x16x32_bf16 v[52:55], v[158:161], v[186:189], v[52:55]
	v_mfma_f32_16x16x32_bf16 v[48:51], v[158:161], v[190:193], v[48:51]
	v_mfma_f32_16x16x32_bf16 v[44:47], v[162:165], v[174:177], v[44:47]
	v_mfma_f32_16x16x32_bf16 v[40:43], v[162:165], v[182:185], v[40:43]
	v_mfma_f32_16x16x32_bf16 v[36:39], v[162:165], v[186:189], v[36:39]
	v_mfma_f32_16x16x32_bf16 v[32:35], v[162:165], v[190:193], v[32:35]
	v_mfma_f32_16x16x32_bf16 v[28:31], v[166:169], v[174:177], v[28:31]
	v_mfma_f32_16x16x32_bf16 v[20:23], v[166:169], v[182:185], v[20:23]
	v_mfma_f32_16x16x32_bf16 v[16:19], v[166:169], v[186:189], v[16:19]
	v_mfma_f32_16x16x32_bf16 v[8:11], v[166:169], v[190:193], v[8:11]
	v_mfma_f32_16x16x32_bf16 v[4:7], v[170:173], v[174:177], v[4:7]
	v_mfma_f32_16x16x32_bf16 v[0:3], v[170:173], v[182:185], v[0:3]
	v_mfma_f32_16x16x32_bf16 v[24:27], v[170:173], v[186:189], v[24:27]
	v_mfma_f32_16x16x32_bf16 v[12:15], v[170:173], v[190:193], v[12:15]
	ds_read_b128 v[158:161], v213 offset:8192
	ds_read_b128 v[162:165], v213 offset:10240
	ds_read_b128 v[166:169], v213 offset:12288
	ds_read_b128 v[170:173], v213 offset:14336
	s_waitcnt lgkmcnt(4)
	v_mfma_f32_16x16x32_bf16 v[124:127], v[142:145], v[194:197], v[124:127]
	v_mfma_f32_16x16x32_bf16 v[120:123], v[142:145], v[198:201], v[120:123]
	v_mfma_f32_16x16x32_bf16 v[116:119], v[142:145], v[202:205], v[116:119]
	v_mfma_f32_16x16x32_bf16 v[112:115], v[142:145], v[206:209], v[112:115]
	v_mfma_f32_16x16x32_bf16 v[108:111], v[146:149], v[194:197], v[108:111]
	v_mfma_f32_16x16x32_bf16 v[104:107], v[146:149], v[198:201], v[104:107]
	v_mfma_f32_16x16x32_bf16 v[100:103], v[146:149], v[202:205], v[100:103]
	v_mfma_f32_16x16x32_bf16 v[96:99], v[146:149], v[206:209], v[96:99]
	v_mfma_f32_16x16x32_bf16 v[92:95], v[150:153], v[194:197], v[92:95]
	v_mfma_f32_16x16x32_bf16 v[88:91], v[150:153], v[198:201], v[88:91]
	v_mfma_f32_16x16x32_bf16 v[84:87], v[150:153], v[202:205], v[84:87]
	v_mfma_f32_16x16x32_bf16 v[80:83], v[150:153], v[206:209], v[80:83]
	v_mfma_f32_16x16x32_bf16 v[76:79], v[154:157], v[194:197], v[76:79]
	v_mfma_f32_16x16x32_bf16 v[72:75], v[154:157], v[198:201], v[72:75]
	v_mfma_f32_16x16x32_bf16 v[68:71], v[154:157], v[202:205], v[68:71]
	v_mfma_f32_16x16x32_bf16 v[64:67], v[154:157], v[206:209], v[64:67]
	s_add_u32 s50, s50, 0x80
	s_addc_u32 s51, s51, 0
	s_add_i32 s49, s49, 1
	s_waitcnt lgkmcnt(0)
	s_waitcnt vmcnt(0)
	s_barrier
	v_mfma_f32_16x16x32_bf16 v[60:63], v[158:161], v[194:197], v[60:63]
	v_mfma_f32_16x16x32_bf16 v[56:59], v[158:161], v[198:201], v[56:59]
	v_mfma_f32_16x16x32_bf16 v[52:55], v[158:161], v[202:205], v[52:55]
	v_mfma_f32_16x16x32_bf16 v[48:51], v[158:161], v[206:209], v[48:51]
	v_mfma_f32_16x16x32_bf16 v[44:47], v[162:165], v[194:197], v[44:47]
	v_mfma_f32_16x16x32_bf16 v[40:43], v[162:165], v[198:201], v[40:43]
	v_mfma_f32_16x16x32_bf16 v[36:39], v[162:165], v[202:205], v[36:39]
	v_mfma_f32_16x16x32_bf16 v[32:35], v[162:165], v[206:209], v[32:35]
	v_mfma_f32_16x16x32_bf16 v[28:31], v[166:169], v[194:197], v[28:31]
	v_mfma_f32_16x16x32_bf16 v[20:23], v[166:169], v[198:201], v[20:23]
	v_mfma_f32_16x16x32_bf16 v[16:19], v[166:169], v[202:205], v[16:19]
	v_mfma_f32_16x16x32_bf16 v[8:11], v[166:169], v[206:209], v[8:11]
	v_mfma_f32_16x16x32_bf16 v[4:7], v[170:173], v[194:197], v[4:7]
	v_mfma_f32_16x16x32_bf16 v[0:3], v[170:173], v[198:201], v[0:3]
	v_mfma_f32_16x16x32_bf16 v[24:27], v[170:173], v[202:205], v[24:27]
	v_mfma_f32_16x16x32_bf16 v[12:15], v[170:173], v[206:209], v[12:15]
	s_nop 7
	s_nop 7
	s_sub_u32 s50, s50, s34
	s_subb_u32 s51, s51, s35
	s_mov_b32 s59, 0x100000
	s_mov_b32 s60, 0x100000
	s_mov_b64 s[52:53], 0
	s_mov_b64 vcc, exec
	s_branch .LBB0_262

.Lg2_top:
	s_waitcnt lgkmcnt(0)
	s_waitcnt vmcnt(0)
	s_barrier
	v_mfma_f32_16x16x32_bf16 v[60:63], v[162:165], v[198:201], v[60:63]
	v_mfma_f32_16x16x32_bf16 v[56:59], v[162:165], v[202:205], v[56:59]
	s_xor_b32 s62, s62, 0x10000
	s_mov_b32 m0, s62
	s_add_u32 s50, s48, s12
	s_addc_u32 s51, s49, s13
	global_load_lds_dwordx4 v178, s[50:51]
	s_add_u32 m0, s62, 0x2000
	s_add_u32 s50, s48, s14
	s_addc_u32 s51, s49, s15
	global_load_lds_dwordx4 v178, s[50:51]
	ds_read_b128 v[146:149], v180
	ds_read_b128 v[150:153], v180 offset:2048
	ds_read_b128 v[154:157], v180 offset:4096
	ds_read_b128 v[158:161], v180 offset:6144
	ds_read_b128 v[182:185], v215 offset:32768
	ds_read_b128 v[186:189], v215 offset:34816
	ds_read_b128 v[190:193], v215 offset:36864
	ds_read_b128 v[194:197], v215 offset:38912
	v_mfma_f32_16x16x32_bf16 v[52:55], v[162:165], v[206:209], v[52:55]
	v_mfma_f32_16x16x32_bf16 v[44:47], v[162:165], v[210:213], v[44:47]
	s_add_u32 m0, s62, 0x4000
	s_add_u32 s50, s48, s16
	s_addc_u32 s51, s49, s17
	global_load_lds_dwordx4 v178, s[50:51]
	v_mfma_f32_16x16x32_bf16 v[36:39], v[166:169], v[198:201], v[36:39]
	v_mfma_f32_16x16x32_bf16 v[32:35], v[166:169], v[202:205], v[32:35]
	s_add_u32 m0, s62, 0x6000
	s_add_u32 s50, s48, s18
	s_addc_u32 s51, s49, s19
	global_load_lds_dwordx4 v178, s[50:51]
	v_mfma_f32_16x16x32_bf16 v[28:31], v[166:169], v[206:209], v[28:31]
	v_mfma_f32_16x16x32_bf16 v[24:27], v[166:169], v[210:213], v[24:27]
	s_add_u32 m0, s62, 0x8000
	s_add_u32 s50, s48, s22
	s_addc_u32 s51, s49, s23
	global_load_lds_dwordx4 v179, s[50:51]
	v_mfma_f32_16x16x32_bf16 v[20:23], v[170:173], v[198:201], v[20:23]
	v_mfma_f32_16x16x32_bf16 v[16:19], v[170:173], v[202:205], v[16:19]
	s_add_u32 m0, s62, 0xa000
	s_add_u32 s50, s48, s36
	s_addc_u32 s51, s49, s37
	global_load_lds_dwordx4 v179, s[50:51]
	v_mfma_f32_16x16x32_bf16 v[12:15], v[170:173], v[206:209], v[12:15]
	v_mfma_f32_16x16x32_bf16 v[8:11], v[170:173], v[210:213], v[8:11]
	s_add_u32 m0, s62, 0xc000
	s_add_u32 s50, s48, s40
	s_addc_u32 s51, s49, s41
	global_load_lds_dwordx4 v179, s[50:51]
	v_mfma_f32_16x16x32_bf16 v[4:7], v[174:177], v[198:201], v[4:7]
	v_mfma_f32_16x16x32_bf16 v[0:3], v[174:177], v[202:205], v[0:3]
	s_add_u32 m0, s62, 0xe000
	s_add_u32 s50, s48, s42
	s_addc_u32 s51, s49, s43
	global_load_lds_dwordx4 v179, s[50:51]
	v_mfma_f32_16x16x32_bf16 v[48:51], v[174:177], v[206:209], v[48:51]
	v_mfma_f32_16x16x32_bf16 v[40:43], v[174:177], v[210:213], v[40:43]
.Lg2_entry:
	ds_read_b128 v[162:165], v180 offset:8192
	ds_read_b128 v[166:169], v180 offset:10240
	ds_read_b128 v[170:173], v180 offset:12288
	ds_read_b128 v[174:177], v180 offset:14336
	s_waitcnt lgkmcnt(4)
	v_mfma_f32_16x16x32_bf16 v[124:127], v[146:149], v[182:185], v[124:127]
	v_mfma_f32_16x16x32_bf16 v[120:123], v[146:149], v[186:189], v[120:123]
	v_mfma_f32_16x16x32_bf16 v[116:119], v[146:149], v[190:193], v[116:119]
	v_mfma_f32_16x16x32_bf16 v[112:115], v[146:149], v[194:197], v[112:115]
	v_mfma_f32_16x16x32_bf16 v[108:111], v[150:153], v[182:185], v[108:111]
	v_mfma_f32_16x16x32_bf16 v[104:107], v[150:153], v[186:189], v[104:107]
	v_mfma_f32_16x16x32_bf16 v[100:103], v[150:153], v[190:193], v[100:103]
	v_mfma_f32_16x16x32_bf16 v[96:99], v[150:153], v[194:197], v[96:99]
	v_mfma_f32_16x16x32_bf16 v[92:95], v[154:157], v[182:185], v[92:95]
	v_mfma_f32_16x16x32_bf16 v[88:91], v[154:157], v[186:189], v[88:91]
	v_mfma_f32_16x16x32_bf16 v[84:87], v[154:157], v[190:193], v[84:87]
	v_mfma_f32_16x16x32_bf16 v[80:83], v[154:157], v[194:197], v[80:83]
	v_mfma_f32_16x16x32_bf16 v[76:79], v[158:161], v[182:185], v[76:79]
	v_mfma_f32_16x16x32_bf16 v[72:75], v[158:161], v[186:189], v[72:75]
	v_mfma_f32_16x16x32_bf16 v[68:71], v[158:161], v[190:193], v[68:71]
	v_mfma_f32_16x16x32_bf16 v[64:67], v[158:161], v[194:197], v[64:67]
	ds_read_b128 v[146:149], v214
	ds_read_b128 v[150:153], v214 offset:2048
	ds_read_b128 v[154:157], v214 offset:4096
	ds_read_b128 v[158:161], v214 offset:6144
	ds_read_b128 v[198:201], v216 offset:32768
	ds_read_b128 v[202:205], v216 offset:34816
	ds_read_b128 v[206:209], v216 offset:36864
	ds_read_b128 v[210:213], v216 offset:38912
	s_waitcnt lgkmcnt(8)
	v_mfma_f32_16x16x32_bf16 v[60:63], v[162:165], v[182:185], v[60:63]
	v_mfma_f32_16x16x32_bf16 v[56:59], v[162:165], v[186:189], v[56:59]
	v_mfma_f32_16x16x32_bf16 v[52:55], v[162:165], v[190:193], v[52:55]
	v_mfma_f32_16x16x32_bf16 v[44:47], v[162:165], v[194:197], v[44:47]
	v_mfma_f32_16x16x32_bf16 v[36:39], v[166:169], v[182:185], v[36:39]
	v_mfma_f32_16x16x32_bf16 v[32:35], v[166:169], v[186:189], v[32:35]
	v_mfma_f32_16x16x32_bf16 v[28:31], v[166:169], v[190:193], v[28:31]
	v_mfma_f32_16x16x32_bf16 v[24:27], v[166:169], v[194:197], v[24:27]
	v_mfma_f32_16x16x32_bf16 v[20:23], v[170:173], v[182:185], v[20:23]
	v_mfma_f32_16x16x32_bf16 v[16:19], v[170:173], v[186:189], v[16:19]
	v_mfma_f32_16x16x32_bf16 v[12:15], v[170:173], v[190:193], v[12:15]
	v_mfma_f32_16x16x32_bf16 v[8:11], v[170:173], v[194:197], v[8:11]
	v_mfma_f32_16x16x32_bf16 v[4:7], v[174:177], v[182:185], v[4:7]
	v_mfma_f32_16x16x32_bf16 v[0:3], v[174:177], v[186:189], v[0:3]
	v_mfma_f32_16x16x32_bf16 v[48:51], v[174:177], v[190:193], v[48:51]
	v_mfma_f32_16x16x32_bf16 v[40:43], v[174:177], v[194:197], v[40:43]
	ds_read_b128 v[162:165], v214 offset:8192
	ds_read_b128 v[166:169], v214 offset:10240
	ds_read_b128 v[170:173], v214 offset:12288
	ds_read_b128 v[174:177], v214 offset:14336
	s_waitcnt lgkmcnt(4)
	v_mfma_f32_16x16x32_bf16 v[124:127], v[146:149], v[198:201], v[124:127]
	v_mfma_f32_16x16x32_bf16 v[120:123], v[146:149], v[202:205], v[120:123]
	v_mfma_f32_16x16x32_bf16 v[116:119], v[146:149], v[206:209], v[116:119]
	v_mfma_f32_16x16x32_bf16 v[112:115], v[146:149], v[210:213], v[112:115]
	v_mfma_f32_16x16x32_bf16 v[108:111], v[150:153], v[198:201], v[108:111]
	v_mfma_f32_16x16x32_bf16 v[104:107], v[150:153], v[202:205], v[104:107]
	v_mfma_f32_16x16x32_bf16 v[100:103], v[150:153], v[206:209], v[100:103]
	v_mfma_f32_16x16x32_bf16 v[96:99], v[150:153], v[210:213], v[96:99]
	v_mfma_f32_16x16x32_bf16 v[92:95], v[154:157], v[198:201], v[92:95]
	v_mfma_f32_16x16x32_bf16 v[88:91], v[154:157], v[202:205], v[88:91]
	v_mfma_f32_16x16x32_bf16 v[84:87], v[154:157], v[206:209], v[84:87]
	v_mfma_f32_16x16x32_bf16 v[80:83], v[154:157], v[210:213], v[80:83]
	v_mfma_f32_16x16x32_bf16 v[76:79], v[158:161], v[198:201], v[76:79]
	v_mfma_f32_16x16x32_bf16 v[72:75], v[158:161], v[202:205], v[72:75]
	v_mfma_f32_16x16x32_bf16 v[68:71], v[158:161], v[206:209], v[68:71]
	v_mfma_f32_16x16x32_bf16 v[64:67], v[158:161], v[210:213], v[64:67]
	s_add_u32 s48, s48, 0x80
	s_addc_u32 s49, s49, 0
	s_add_i32 s47, s47, 1
	s_cmp_lt_u32 s47, 15
	s_cbranch_scc0 .Lg2_last
	s_waitcnt lgkmcnt(0)
	s_waitcnt vmcnt(0)
	s_barrier
	v_mfma_f32_16x16x32_bf16 v[60:63], v[162:165], v[198:201], v[60:63]
	v_mfma_f32_16x16x32_bf16 v[56:59], v[162:165], v[202:205], v[56:59]
	s_xor_b32 s62, s62, 0x10000
	s_mov_b32 m0, s62
	s_add_u32 s50, s48, s12
	s_addc_u32 s51, s49, s13
	global_load_lds_dwordx4 v178, s[50:51]
	s_add_u32 m0, s62, 0x2000
	s_add_u32 s50, s48, s14
	s_addc_u32 s51, s49, s15
	global_load_lds_dwordx4 v178, s[50:51]
	ds_read_b128 v[146:149], v217
	ds_read_b128 v[150:153], v217 offset:2048
	ds_read_b128 v[154:157], v217 offset:4096
	ds_read_b128 v[158:161], v217 offset:6144
	ds_read_b128 v[182:185], v219 offset:32768
	ds_read_b128 v[186:189], v219 offset:34816
	ds_read_b128 v[190:193], v219 offset:36864
	ds_read_b128 v[194:197], v219 offset:38912
	v_mfma_f32_16x16x32_bf16 v[52:55], v[162:165], v[206:209], v[52:55]
	v_mfma_f32_16x16x32_bf16 v[44:47], v[162:165], v[210:213], v[44:47]
	s_add_u32 m0, s62, 0x4000
	s_add_u32 s50, s48, s16
	s_addc_u32 s51, s49, s17
	global_load_lds_dwordx4 v178, s[50:51]
	v_mfma_f32_16x16x32_bf16 v[36:39], v[166:169], v[198:201], v[36:39]
	v_mfma_f32_16x16x32_bf16 v[32:35], v[166:169], v[202:205], v[32:35]
	s_add_u32 m0, s62, 0x6000
	s_add_u32 s50, s48, s18
	s_addc_u32 s51, s49, s19
	global_load_lds_dwordx4 v178, s[50:51]
	v_mfma_f32_16x16x32_bf16 v[28:31], v[166:169], v[206:209], v[28:31]
	v_mfma_f32_16x16x32_bf16 v[24:27], v[166:169], v[210:213], v[24:27]
	s_add_u32 m0, s62, 0x8000
	s_add_u32 s50, s48, s22
	s_addc_u32 s51, s49, s23
	global_load_lds_dwordx4 v179, s[50:51]
	v_mfma_f32_16x16x32_bf16 v[20:23], v[170:173], v[198:201], v[20:23]
	v_mfma_f32_16x16x32_bf16 v[16:19], v[170:173], v[202:205], v[16:19]
	s_add_u32 m0, s62, 0xa000
	s_add_u32 s50, s48, s36
	s_addc_u32 s51, s49, s37
	global_load_lds_dwordx4 v179, s[50:51]
	v_mfma_f32_16x16x32_bf16 v[12:15], v[170:173], v[206:209], v[12:15]
	v_mfma_f32_16x16x32_bf16 v[8:11], v[170:173], v[210:213], v[8:11]
	s_add_u32 m0, s62, 0xc000
	s_add_u32 s50, s48, s40
	s_addc_u32 s51, s49, s41
	global_load_lds_dwordx4 v179, s[50:51]
	v_mfma_f32_16x16x32_bf16 v[4:7], v[174:177], v[198:201], v[4:7]
	v_mfma_f32_16x16x32_bf16 v[0:3], v[174:177], v[202:205], v[0:3]
	s_add_u32 m0, s62, 0xe000
	s_add_u32 s50, s48, s42
	s_addc_u32 s51, s49, s43
	global_load_lds_dwordx4 v179, s[50:51]
	v_mfma_f32_16x16x32_bf16 v[48:51], v[174:177], v[206:209], v[48:51]
	v_mfma_f32_16x16x32_bf16 v[40:43], v[174:177], v[210:213], v[40:43]
	ds_read_b128 v[162:165], v217 offset:8192
	ds_read_b128 v[166:169], v217 offset:10240
	ds_read_b128 v[170:173], v217 offset:12288
	ds_read_b128 v[174:177], v217 offset:14336
	s_waitcnt lgkmcnt(4)
	v_mfma_f32_16x16x32_bf16 v[124:127], v[146:149], v[182:185], v[124:127]
	v_mfma_f32_16x16x32_bf16 v[120:123], v[146:149], v[186:189], v[120:123]
	v_mfma_f32_16x16x32_bf16 v[116:119], v[146:149], v[190:193], v[116:119]
	v_mfma_f32_16x16x32_bf16 v[112:115], v[146:149], v[194:197], v[112:115]
	v_mfma_f32_16x16x32_bf16 v[108:111], v[150:153], v[182:185], v[108:111]
	v_mfma_f32_16x16x32_bf16 v[104:107], v[150:153], v[186:189], v[104:107]
	v_mfma_f32_16x16x32_bf16 v[100:103], v[150:153], v[190:193], v[100:103]
	v_mfma_f32_16x16x32_bf16 v[96:99], v[150:153], v[194:197], v[96:99]
	v_mfma_f32_16x16x32_bf16 v[92:95], v[154:157], v[182:185], v[92:95]
	v_mfma_f32_16x16x32_bf16 v[88:91], v[154:157], v[186:189], v[88:91]
	v_mfma_f32_16x16x32_bf16 v[84:87], v[154:157], v[190:193], v[84:87]
	v_mfma_f32_16x16x32_bf16 v[80:83], v[154:157], v[194:197], v[80:83]
	v_mfma_f32_16x16x32_bf16 v[76:79], v[158:161], v[182:185], v[76:79]
	v_mfma_f32_16x16x32_bf16 v[72:75], v[158:161], v[186:189], v[72:75]
	v_mfma_f32_16x16x32_bf16 v[68:71], v[158:161], v[190:193], v[68:71]
	v_mfma_f32_16x16x32_bf16 v[64:67], v[158:161], v[194:197], v[64:67]
	ds_read_b128 v[146:149], v218
	ds_read_b128 v[150:153], v218 offset:2048
	ds_read_b128 v[154:157], v218 offset:4096
	ds_read_b128 v[158:161], v218 offset:6144
	ds_read_b128 v[198:201], v220 offset:32768
	ds_read_b128 v[202:205], v220 offset:34816
	ds_read_b128 v[206:209], v220 offset:36864
	ds_read_b128 v[210:213], v220 offset:38912
	s_waitcnt lgkmcnt(8)
	v_mfma_f32_16x16x32_bf16 v[60:63], v[162:165], v[182:185], v[60:63]
	v_mfma_f32_16x16x32_bf16 v[56:59], v[162:165], v[186:189], v[56:59]
	v_mfma_f32_16x16x32_bf16 v[52:55], v[162:165], v[190:193], v[52:55]
	v_mfma_f32_16x16x32_bf16 v[44:47], v[162:165], v[194:197], v[44:47]
	v_mfma_f32_16x16x32_bf16 v[36:39], v[166:169], v[182:185], v[36:39]
	v_mfma_f32_16x16x32_bf16 v[32:35], v[166:169], v[186:189], v[32:35]
	v_mfma_f32_16x16x32_bf16 v[28:31], v[166:169], v[190:193], v[28:31]
	v_mfma_f32_16x16x32_bf16 v[24:27], v[166:169], v[194:197], v[24:27]
	v_mfma_f32_16x16x32_bf16 v[20:23], v[170:173], v[182:185], v[20:23]
	v_mfma_f32_16x16x32_bf16 v[16:19], v[170:173], v[186:189], v[16:19]
	v_mfma_f32_16x16x32_bf16 v[12:15], v[170:173], v[190:193], v[12:15]
	v_mfma_f32_16x16x32_bf16 v[8:11], v[170:173], v[194:197], v[8:11]
	v_mfma_f32_16x16x32_bf16 v[4:7], v[174:177], v[182:185], v[4:7]
	v_mfma_f32_16x16x32_bf16 v[0:3], v[174:177], v[186:189], v[0:3]
	v_mfma_f32_16x16x32_bf16 v[48:51], v[174:177], v[190:193], v[48:51]
	v_mfma_f32_16x16x32_bf16 v[40:43], v[174:177], v[194:197], v[40:43]
	ds_read_b128 v[162:165], v218 offset:8192
	ds_read_b128 v[166:169], v218 offset:10240
	ds_read_b128 v[170:173], v218 offset:12288
	ds_read_b128 v[174:177], v218 offset:14336
	s_waitcnt lgkmcnt(4)
	v_mfma_f32_16x16x32_bf16 v[124:127], v[146:149], v[198:201], v[124:127]
	v_mfma_f32_16x16x32_bf16 v[120:123], v[146:149], v[202:205], v[120:123]
	v_mfma_f32_16x16x32_bf16 v[116:119], v[146:149], v[206:209], v[116:119]
	v_mfma_f32_16x16x32_bf16 v[112:115], v[146:149], v[210:213], v[112:115]
	v_mfma_f32_16x16x32_bf16 v[108:111], v[150:153], v[198:201], v[108:111]
	v_mfma_f32_16x16x32_bf16 v[104:107], v[150:153], v[202:205], v[104:107]
	v_mfma_f32_16x16x32_bf16 v[100:103], v[150:153], v[206:209], v[100:103]
	v_mfma_f32_16x16x32_bf16 v[96:99], v[150:153], v[210:213], v[96:99]
	v_mfma_f32_16x16x32_bf16 v[92:95], v[154:157], v[198:201], v[92:95]
	v_mfma_f32_16x16x32_bf16 v[88:91], v[154:157], v[202:205], v[88:91]
	v_mfma_f32_16x16x32_bf16 v[84:87], v[154:157], v[206:209], v[84:87]
	v_mfma_f32_16x16x32_bf16 v[80:83], v[154:157], v[210:213], v[80:83]
	v_mfma_f32_16x16x32_bf16 v[76:79], v[158:161], v[198:201], v[76:79]
	v_mfma_f32_16x16x32_bf16 v[72:75], v[158:161], v[202:205], v[72:75]
	v_mfma_f32_16x16x32_bf16 v[68:71], v[158:161], v[206:209], v[68:71]
	v_mfma_f32_16x16x32_bf16 v[64:67], v[158:161], v[210:213], v[64:67]
	s_add_u32 s48, s48, 0x80
	s_addc_u32 s49, s49, 0
	s_add_i32 s47, s47, 1
	s_branch .Lg2_top
.Lg2_last:
	s_waitcnt lgkmcnt(0)
	s_waitcnt vmcnt(0)
	s_barrier
	v_mfma_f32_16x16x32_bf16 v[60:63], v[162:165], v[198:201], v[60:63]
	v_mfma_f32_16x16x32_bf16 v[56:59], v[162:165], v[202:205], v[56:59]
	s_xor_b32 s62, s62, 0x10000
	ds_read_b128 v[146:149], v217
	ds_read_b128 v[150:153], v217 offset:2048
	ds_read_b128 v[154:157], v217 offset:4096
	ds_read_b128 v[158:161], v217 offset:6144
	ds_read_b128 v[182:185], v219 offset:32768
	ds_read_b128 v[186:189], v219 offset:34816
	ds_read_b128 v[190:193], v219 offset:36864
	ds_read_b128 v[194:197], v219 offset:38912
	v_mfma_f32_16x16x32_bf16 v[52:55], v[162:165], v[206:209], v[52:55]
	v_mfma_f32_16x16x32_bf16 v[44:47], v[162:165], v[210:213], v[44:47]
	v_mfma_f32_16x16x32_bf16 v[36:39], v[166:169], v[198:201], v[36:39]
	v_mfma_f32_16x16x32_bf16 v[32:35], v[166:169], v[202:205], v[32:35]
	v_mfma_f32_16x16x32_bf16 v[28:31], v[166:169], v[206:209], v[28:31]
	v_mfma_f32_16x16x32_bf16 v[24:27], v[166:169], v[210:213], v[24:27]
	v_mfma_f32_16x16x32_bf16 v[20:23], v[170:173], v[198:201], v[20:23]
	v_mfma_f32_16x16x32_bf16 v[16:19], v[170:173], v[202:205], v[16:19]
	v_mfma_f32_16x16x32_bf16 v[12:15], v[170:173], v[206:209], v[12:15]
	v_mfma_f32_16x16x32_bf16 v[8:11], v[170:173], v[210:213], v[8:11]
	v_mfma_f32_16x16x32_bf16 v[4:7], v[174:177], v[198:201], v[4:7]
	v_mfma_f32_16x16x32_bf16 v[0:3], v[174:177], v[202:205], v[0:3]
	v_mfma_f32_16x16x32_bf16 v[48:51], v[174:177], v[206:209], v[48:51]
	v_mfma_f32_16x16x32_bf16 v[40:43], v[174:177], v[210:213], v[40:43]
	ds_read_b128 v[162:165], v217 offset:8192
	ds_read_b128 v[166:169], v217 offset:10240
	ds_read_b128 v[170:173], v217 offset:12288
	ds_read_b128 v[174:177], v217 offset:14336
	s_waitcnt lgkmcnt(4)
	v_mfma_f32_16x16x32_bf16 v[124:127], v[146:149], v[182:185], v[124:127]
	v_mfma_f32_16x16x32_bf16 v[120:123], v[146:149], v[186:189], v[120:123]
	v_mfma_f32_16x16x32_bf16 v[116:119], v[146:149], v[190:193], v[116:119]
	v_mfma_f32_16x16x32_bf16 v[112:115], v[146:149], v[194:197], v[112:115]
	v_mfma_f32_16x16x32_bf16 v[108:111], v[150:153], v[182:185], v[108:111]
	v_mfma_f32_16x16x32_bf16 v[104:107], v[150:153], v[186:189], v[104:107]
	v_mfma_f32_16x16x32_bf16 v[100:103], v[150:153], v[190:193], v[100:103]
	v_mfma_f32_16x16x32_bf16 v[96:99], v[150:153], v[194:197], v[96:99]
	v_mfma_f32_16x16x32_bf16 v[92:95], v[154:157], v[182:185], v[92:95]
	v_mfma_f32_16x16x32_bf16 v[88:91], v[154:157], v[186:189], v[88:91]
	v_mfma_f32_16x16x32_bf16 v[84:87], v[154:157], v[190:193], v[84:87]
	v_mfma_f32_16x16x32_bf16 v[80:83], v[154:157], v[194:197], v[80:83]
	v_mfma_f32_16x16x32_bf16 v[76:79], v[158:161], v[182:185], v[76:79]
	v_mfma_f32_16x16x32_bf16 v[72:75], v[158:161], v[186:189], v[72:75]
	v_mfma_f32_16x16x32_bf16 v[68:71], v[158:161], v[190:193], v[68:71]
	v_mfma_f32_16x16x32_bf16 v[64:67], v[158:161], v[194:197], v[64:67]
	ds_read_b128 v[146:149], v218
	ds_read_b128 v[150:153], v218 offset:2048
	ds_read_b128 v[154:157], v218 offset:4096
	ds_read_b128 v[158:161], v218 offset:6144
	ds_read_b128 v[198:201], v220 offset:32768
	ds_read_b128 v[202:205], v220 offset:34816
	ds_read_b128 v[206:209], v220 offset:36864
	ds_read_b128 v[210:213], v220 offset:38912
	s_waitcnt lgkmcnt(8)
	v_mfma_f32_16x16x32_bf16 v[60:63], v[162:165], v[182:185], v[60:63]
	v_mfma_f32_16x16x32_bf16 v[56:59], v[162:165], v[186:189], v[56:59]
	v_mfma_f32_16x16x32_bf16 v[52:55], v[162:165], v[190:193], v[52:55]
	v_mfma_f32_16x16x32_bf16 v[44:47], v[162:165], v[194:197], v[44:47]
	v_mfma_f32_16x16x32_bf16 v[36:39], v[166:169], v[182:185], v[36:39]
	v_mfma_f32_16x16x32_bf16 v[32:35], v[166:169], v[186:189], v[32:35]
	v_mfma_f32_16x16x32_bf16 v[28:31], v[166:169], v[190:193], v[28:31]
	v_mfma_f32_16x16x32_bf16 v[24:27], v[166:169], v[194:197], v[24:27]
	v_mfma_f32_16x16x32_bf16 v[20:23], v[170:173], v[182:185], v[20:23]
	v_mfma_f32_16x16x32_bf16 v[16:19], v[170:173], v[186:189], v[16:19]
	v_mfma_f32_16x16x32_bf16 v[12:15], v[170:173], v[190:193], v[12:15]
	v_mfma_f32_16x16x32_bf16 v[8:11], v[170:173], v[194:197], v[8:11]
	v_mfma_f32_16x16x32_bf16 v[4:7], v[174:177], v[182:185], v[4:7]
	v_mfma_f32_16x16x32_bf16 v[0:3], v[174:177], v[186:189], v[0:3]
	v_mfma_f32_16x16x32_bf16 v[48:51], v[174:177], v[190:193], v[48:51]
	v_mfma_f32_16x16x32_bf16 v[40:43], v[174:177], v[194:197], v[40:43]
	ds_read_b128 v[162:165], v218 offset:8192
	ds_read_b128 v[166:169], v218 offset:10240
	ds_read_b128 v[170:173], v218 offset:12288
	ds_read_b128 v[174:177], v218 offset:14336
	s_waitcnt lgkmcnt(4)
	v_mfma_f32_16x16x32_bf16 v[124:127], v[146:149], v[198:201], v[124:127]
	v_mfma_f32_16x16x32_bf16 v[120:123], v[146:149], v[202:205], v[120:123]
	v_mfma_f32_16x16x32_bf16 v[116:119], v[146:149], v[206:209], v[116:119]
	v_mfma_f32_16x16x32_bf16 v[112:115], v[146:149], v[210:213], v[112:115]
	v_mfma_f32_16x16x32_bf16 v[108:111], v[150:153], v[198:201], v[108:111]
	v_mfma_f32_16x16x32_bf16 v[104:107], v[150:153], v[202:205], v[104:107]
	v_mfma_f32_16x16x32_bf16 v[100:103], v[150:153], v[206:209], v[100:103]
	v_mfma_f32_16x16x32_bf16 v[96:99], v[150:153], v[210:213], v[96:99]
	v_mfma_f32_16x16x32_bf16 v[92:95], v[154:157], v[198:201], v[92:95]
	v_mfma_f32_16x16x32_bf16 v[88:91], v[154:157], v[202:205], v[88:91]
	v_mfma_f32_16x16x32_bf16 v[84:87], v[154:157], v[206:209], v[84:87]
	v_mfma_f32_16x16x32_bf16 v[80:83], v[154:157], v[210:213], v[80:83]
	v_mfma_f32_16x16x32_bf16 v[76:79], v[158:161], v[198:201], v[76:79]
	v_mfma_f32_16x16x32_bf16 v[72:75], v[158:161], v[202:205], v[72:75]
	v_mfma_f32_16x16x32_bf16 v[68:71], v[158:161], v[206:209], v[68:71]
	v_mfma_f32_16x16x32_bf16 v[64:67], v[158:161], v[210:213], v[64:67]
	s_add_u32 s48, s48, 0x80
	s_addc_u32 s49, s49, 0
	s_add_i32 s47, s47, 1
	s_waitcnt lgkmcnt(0)
	s_waitcnt vmcnt(0)
	s_barrier
	v_mfma_f32_16x16x32_bf16 v[60:63], v[162:165], v[198:201], v[60:63]
	v_mfma_f32_16x16x32_bf16 v[56:59], v[162:165], v[202:205], v[56:59]
	v_mfma_f32_16x16x32_bf16 v[52:55], v[162:165], v[206:209], v[52:55]
	v_mfma_f32_16x16x32_bf16 v[44:47], v[162:165], v[210:213], v[44:47]
	v_mfma_f32_16x16x32_bf16 v[36:39], v[166:169], v[198:201], v[36:39]
	v_mfma_f32_16x16x32_bf16 v[32:35], v[166:169], v[202:205], v[32:35]
	v_mfma_f32_16x16x32_bf16 v[28:31], v[166:169], v[206:209], v[28:31]
	v_mfma_f32_16x16x32_bf16 v[24:27], v[166:169], v[210:213], v[24:27]
	v_mfma_f32_16x16x32_bf16 v[20:23], v[170:173], v[198:201], v[20:23]
	v_mfma_f32_16x16x32_bf16 v[16:19], v[170:173], v[202:205], v[16:19]
	v_mfma_f32_16x16x32_bf16 v[12:15], v[170:173], v[206:209], v[12:15]
	v_mfma_f32_16x16x32_bf16 v[8:11], v[170:173], v[210:213], v[8:11]
	v_mfma_f32_16x16x32_bf16 v[4:7], v[174:177], v[198:201], v[4:7]
	v_mfma_f32_16x16x32_bf16 v[0:3], v[174:177], v[202:205], v[0:3]
	v_mfma_f32_16x16x32_bf16 v[48:51], v[174:177], v[206:209], v[48:51]
	v_mfma_f32_16x16x32_bf16 v[40:43], v[174:177], v[210:213], v[40:43]
	s_nop 7
	s_nop 7
	s_sub_u32 s48, s48, s34
	s_subb_u32 s49, s49, s35
	s_mov_b32 s62, 0x80000
	s_mov_b32 s63, 0x80000
	s_mov_b64 s[50:51], 0
	s_mov_b64 vcc, exec
	s_branch .LBB0_458

.Lg5_top:
	s_waitcnt lgkmcnt(0)
	s_waitcnt vmcnt(0)
	s_barrier
	v_mfma_f32_16x16x32_bf16 v[60:63], v[194:197], v[226:229], v[60:63]
	v_mfma_f32_16x16x32_bf16 v[56:59], v[194:197], v[230:233], v[56:59]
	s_xor_b32 s87, s87, 0x10000
	s_mov_b32 m0, s87
	s_add_u32 s70, s68, 0x4000080
	s_addc_u32 s71, s69, 0
	global_load_lds_dwordx4 v242, s[70:71]
	s_add_u32 m0, s87, 0x2000
	s_add_u32 s70, s68, 0x4020080
	s_addc_u32 s71, s69, 0
	global_load_lds_dwordx4 v242, s[70:71]
	ds_read_b128 v[176:179], v180
	ds_read_b128 v[182:185], v180 offset:2048
	ds_read_b128 v[186:189], v180 offset:4096
	ds_read_b128 v[190:193], v180 offset:6144
	ds_read_b128 v[210:213], v245 offset:32768
	ds_read_b128 v[214:217], v245 offset:34816
	ds_read_b128 v[218:221], v245 offset:36864
	ds_read_b128 v[222:225], v245 offset:38912
	v_mfma_f32_16x16x32_bf16 v[52:55], v[194:197], v[234:237], v[52:55]
	v_mfma_f32_16x16x32_bf16 v[48:51], v[194:197], v[238:241], v[48:51]
	s_add_u32 m0, s87, 0x4000
	s_add_u32 s70, s68, 0x4040080
	s_addc_u32 s71, s69, 0
	global_load_lds_dwordx4 v242, s[70:71]
	v_mfma_f32_16x16x32_bf16 v[44:47], v[198:201], v[226:229], v[44:47]
	v_mfma_f32_16x16x32_bf16 v[40:43], v[198:201], v[230:233], v[40:43]
	s_add_u32 m0, s87, 0x6000
	s_add_u32 s70, s68, s14
	s_addc_u32 s71, s69, s15
	global_load_lds_dwordx4 v242, s[70:71]
	v_mfma_f32_16x16x32_bf16 v[36:39], v[198:201], v[234:237], v[36:39]
	v_mfma_f32_16x16x32_bf16 v[32:35], v[198:201], v[238:241], v[32:35]
	s_add_u32 m0, s87, 0x8000
	s_add_u32 s70, s68, s16
	s_addc_u32 s71, s69, s17
	global_load_lds_dwordx4 v243, s[70:71]
	v_mfma_f32_16x16x32_bf16 v[28:31], v[202:205], v[226:229], v[28:31]
	v_mfma_f32_16x16x32_bf16 v[24:27], v[202:205], v[230:233], v[24:27]
	s_add_u32 m0, s87, 0xa000
	s_add_u32 s70, s68, s18
	s_addc_u32 s71, s69, s19
	global_load_lds_dwordx4 v243, s[70:71]
	v_mfma_f32_16x16x32_bf16 v[20:23], v[202:205], v[234:237], v[20:23]
	v_mfma_f32_16x16x32_bf16 v[16:19], v[202:205], v[238:241], v[16:19]
	s_add_u32 m0, s87, 0xc000
	s_add_u32 s70, s68, s22
	s_addc_u32 s71, s69, s23
	global_load_lds_dwordx4 v243, s[70:71]
	v_mfma_f32_16x16x32_bf16 v[8:11], v[206:209], v[226:229], v[8:11]
	v_mfma_f32_16x16x32_bf16 v[0:3], v[206:209], v[230:233], v[0:3]
	s_add_u32 m0, s87, 0xe000
	s_add_u32 s70, s68, s36
	s_addc_u32 s71, s69, s37
	global_load_lds_dwordx4 v243, s[70:71]
	v_mfma_f32_16x16x32_bf16 v[12:15], v[206:209], v[234:237], v[12:15]
	v_mfma_f32_16x16x32_bf16 v[4:7], v[206:209], v[238:241], v[4:7]
.Lg5_entry:
	ds_read_b128 v[194:197], v180 offset:8192
	ds_read_b128 v[198:201], v180 offset:10240
	ds_read_b128 v[202:205], v180 offset:12288
	ds_read_b128 v[206:209], v180 offset:14336
	s_waitcnt lgkmcnt(4)
	v_mfma_f32_16x16x32_bf16 v[124:127], v[176:179], v[210:213], v[124:127]
	v_mfma_f32_16x16x32_bf16 v[120:123], v[176:179], v[214:217], v[120:123]
	v_mfma_f32_16x16x32_bf16 v[116:119], v[176:179], v[218:221], v[116:119]
	v_mfma_f32_16x16x32_bf16 v[112:115], v[176:179], v[222:225], v[112:115]
	v_mfma_f32_16x16x32_bf16 v[108:111], v[182:185], v[210:213], v[108:111]
	v_mfma_f32_16x16x32_bf16 v[104:107], v[182:185], v[214:217], v[104:107]
	v_mfma_f32_16x16x32_bf16 v[100:103], v[182:185], v[218:221], v[100:103]
	v_mfma_f32_16x16x32_bf16 v[96:99], v[182:185], v[222:225], v[96:99]
	v_mfma_f32_16x16x32_bf16 v[92:95], v[186:189], v[210:213], v[92:95]
	v_mfma_f32_16x16x32_bf16 v[88:91], v[186:189], v[214:217], v[88:91]
	v_mfma_f32_16x16x32_bf16 v[84:87], v[186:189], v[218:221], v[84:87]
	v_mfma_f32_16x16x32_bf16 v[80:83], v[186:189], v[222:225], v[80:83]
	v_mfma_f32_16x16x32_bf16 v[76:79], v[190:193], v[210:213], v[76:79]
	v_mfma_f32_16x16x32_bf16 v[72:75], v[190:193], v[214:217], v[72:75]
	v_mfma_f32_16x16x32_bf16 v[68:71], v[190:193], v[218:221], v[68:71]
	v_mfma_f32_16x16x32_bf16 v[64:67], v[190:193], v[222:225], v[64:67]
	ds_read_b128 v[176:179], v244
	ds_read_b128 v[182:185], v244 offset:2048
	ds_read_b128 v[186:189], v244 offset:4096
	ds_read_b128 v[190:193], v244 offset:6144
	ds_read_b128 v[226:229], v246 offset:32768
	ds_read_b128 v[230:233], v246 offset:34816
	ds_read_b128 v[234:237], v246 offset:36864
	ds_read_b128 v[238:241], v246 offset:38912
	s_waitcnt lgkmcnt(8)
	v_mfma_f32_16x16x32_bf16 v[60:63], v[194:197], v[210:213], v[60:63]
	v_mfma_f32_16x16x32_bf16 v[56:59], v[194:197], v[214:217], v[56:59]
	v_mfma_f32_16x16x32_bf16 v[52:55], v[194:197], v[218:221], v[52:55]
	v_mfma_f32_16x16x32_bf16 v[48:51], v[194:197], v[222:225], v[48:51]
	v_mfma_f32_16x16x32_bf16 v[44:47], v[198:201], v[210:213], v[44:47]
	v_mfma_f32_16x16x32_bf16 v[40:43], v[198:201], v[214:217], v[40:43]
	v_mfma_f32_16x16x32_bf16 v[36:39], v[198:201], v[218:221], v[36:39]
	v_mfma_f32_16x16x32_bf16 v[32:35], v[198:201], v[222:225], v[32:35]
	v_mfma_f32_16x16x32_bf16 v[28:31], v[202:205], v[210:213], v[28:31]
	v_mfma_f32_16x16x32_bf16 v[24:27], v[202:205], v[214:217], v[24:27]
	v_mfma_f32_16x16x32_bf16 v[20:23], v[202:205], v[218:221], v[20:23]
	v_mfma_f32_16x16x32_bf16 v[16:19], v[202:205], v[222:225], v[16:19]
	v_mfma_f32_16x16x32_bf16 v[8:11], v[206:209], v[210:213], v[8:11]
	v_mfma_f32_16x16x32_bf16 v[0:3], v[206:209], v[214:217], v[0:3]
	v_mfma_f32_16x16x32_bf16 v[12:15], v[206:209], v[218:221], v[12:15]
	v_mfma_f32_16x16x32_bf16 v[4:7], v[206:209], v[222:225], v[4:7]
	ds_read_b128 v[194:197], v244 offset:8192
	ds_read_b128 v[198:201], v244 offset:10240
	ds_read_b128 v[202:205], v244 offset:12288
	ds_read_b128 v[206:209], v244 offset:14336
	s_waitcnt lgkmcnt(4)
	v_mfma_f32_16x16x32_bf16 v[124:127], v[176:179], v[226:229], v[124:127]
	v_mfma_f32_16x16x32_bf16 v[120:123], v[176:179], v[230:233], v[120:123]
	v_mfma_f32_16x16x32_bf16 v[116:119], v[176:179], v[234:237], v[116:119]
	v_mfma_f32_16x16x32_bf16 v[112:115], v[176:179], v[238:241], v[112:115]
	v_mfma_f32_16x16x32_bf16 v[108:111], v[182:185], v[226:229], v[108:111]
	v_mfma_f32_16x16x32_bf16 v[104:107], v[182:185], v[230:233], v[104:107]
	v_mfma_f32_16x16x32_bf16 v[100:103], v[182:185], v[234:237], v[100:103]
	v_mfma_f32_16x16x32_bf16 v[96:99], v[182:185], v[238:241], v[96:99]
	v_mfma_f32_16x16x32_bf16 v[92:95], v[186:189], v[226:229], v[92:95]
	v_mfma_f32_16x16x32_bf16 v[88:91], v[186:189], v[230:233], v[88:91]
	v_mfma_f32_16x16x32_bf16 v[84:87], v[186:189], v[234:237], v[84:87]
	v_mfma_f32_16x16x32_bf16 v[80:83], v[186:189], v[238:241], v[80:83]
	v_mfma_f32_16x16x32_bf16 v[76:79], v[190:193], v[226:229], v[76:79]
	v_mfma_f32_16x16x32_bf16 v[72:75], v[190:193], v[230:233], v[72:75]
	v_mfma_f32_16x16x32_bf16 v[68:71], v[190:193], v[234:237], v[68:71]
	v_mfma_f32_16x16x32_bf16 v[64:67], v[190:193], v[238:241], v[64:67]
	s_add_u32 s68, s68, 0x80
	s_addc_u32 s69, s69, 0
	s_add_i32 s86, s86, 1
	s_cmp_lt_u32 s86, 15
	s_cbranch_scc0 .Lg5_last
	s_waitcnt lgkmcnt(0)
	s_waitcnt vmcnt(0)
	s_barrier
	v_mfma_f32_16x16x32_bf16 v[60:63], v[194:197], v[226:229], v[60:63]
	v_mfma_f32_16x16x32_bf16 v[56:59], v[194:197], v[230:233], v[56:59]
	s_xor_b32 s87, s87, 0x10000
	s_mov_b32 m0, s87
	s_add_u32 s70, s68, 0x4000080
	s_addc_u32 s71, s69, 0
	global_load_lds_dwordx4 v242, s[70:71]
	s_add_u32 m0, s87, 0x2000
	s_add_u32 s70, s68, 0x4020080
	s_addc_u32 s71, s69, 0
	global_load_lds_dwordx4 v242, s[70:71]
	ds_read_b128 v[176:179], v247
	ds_read_b128 v[182:185], v247 offset:2048
	ds_read_b128 v[186:189], v247 offset:4096
	ds_read_b128 v[190:193], v247 offset:6144
	ds_read_b128 v[210:213], v249 offset:32768
	ds_read_b128 v[214:217], v249 offset:34816
	ds_read_b128 v[218:221], v249 offset:36864
	ds_read_b128 v[222:225], v249 offset:38912
	v_mfma_f32_16x16x32_bf16 v[52:55], v[194:197], v[234:237], v[52:55]
	v_mfma_f32_16x16x32_bf16 v[48:51], v[194:197], v[238:241], v[48:51]
	s_add_u32 m0, s87, 0x4000
	s_add_u32 s70, s68, 0x4040080
	s_addc_u32 s71, s69, 0
	global_load_lds_dwordx4 v242, s[70:71]
	v_mfma_f32_16x16x32_bf16 v[44:47], v[198:201], v[226:229], v[44:47]
	v_mfma_f32_16x16x32_bf16 v[40:43], v[198:201], v[230:233], v[40:43]
	s_add_u32 m0, s87, 0x6000
	s_add_u32 s70, s68, s14
	s_addc_u32 s71, s69, s15
	global_load_lds_dwordx4 v242, s[70:71]
	v_mfma_f32_16x16x32_bf16 v[36:39], v[198:201], v[234:237], v[36:39]
	v_mfma_f32_16x16x32_bf16 v[32:35], v[198:201], v[238:241], v[32:35]
	s_add_u32 m0, s87, 0x8000
	s_add_u32 s70, s68, s16
	s_addc_u32 s71, s69, s17
	global_load_lds_dwordx4 v243, s[70:71]
	v_mfma_f32_16x16x32_bf16 v[28:31], v[202:205], v[226:229], v[28:31]
	v_mfma_f32_16x16x32_bf16 v[24:27], v[202:205], v[230:233], v[24:27]
	s_add_u32 m0, s87, 0xa000
	s_add_u32 s70, s68, s18
	s_addc_u32 s71, s69, s19
	global_load_lds_dwordx4 v243, s[70:71]
	v_mfma_f32_16x16x32_bf16 v[20:23], v[202:205], v[234:237], v[20:23]
	v_mfma_f32_16x16x32_bf16 v[16:19], v[202:205], v[238:241], v[16:19]
	s_add_u32 m0, s87, 0xc000
	s_add_u32 s70, s68, s22
	s_addc_u32 s71, s69, s23
	global_load_lds_dwordx4 v243, s[70:71]
	v_mfma_f32_16x16x32_bf16 v[8:11], v[206:209], v[226:229], v[8:11]
	v_mfma_f32_16x16x32_bf16 v[0:3], v[206:209], v[230:233], v[0:3]
	s_add_u32 m0, s87, 0xe000
	s_add_u32 s70, s68, s36
	s_addc_u32 s71, s69, s37
	global_load_lds_dwordx4 v243, s[70:71]
	v_mfma_f32_16x16x32_bf16 v[12:15], v[206:209], v[234:237], v[12:15]
	v_mfma_f32_16x16x32_bf16 v[4:7], v[206:209], v[238:241], v[4:7]
	ds_read_b128 v[194:197], v247 offset:8192
	ds_read_b128 v[198:201], v247 offset:10240
	ds_read_b128 v[202:205], v247 offset:12288
	ds_read_b128 v[206:209], v247 offset:14336
	s_waitcnt lgkmcnt(4)
	v_mfma_f32_16x16x32_bf16 v[124:127], v[176:179], v[210:213], v[124:127]
	v_mfma_f32_16x16x32_bf16 v[120:123], v[176:179], v[214:217], v[120:123]
	v_mfma_f32_16x16x32_bf16 v[116:119], v[176:179], v[218:221], v[116:119]
	v_mfma_f32_16x16x32_bf16 v[112:115], v[176:179], v[222:225], v[112:115]
	v_mfma_f32_16x16x32_bf16 v[108:111], v[182:185], v[210:213], v[108:111]
	v_mfma_f32_16x16x32_bf16 v[104:107], v[182:185], v[214:217], v[104:107]
	v_mfma_f32_16x16x32_bf16 v[100:103], v[182:185], v[218:221], v[100:103]
	v_mfma_f32_16x16x32_bf16 v[96:99], v[182:185], v[222:225], v[96:99]
	v_mfma_f32_16x16x32_bf16 v[92:95], v[186:189], v[210:213], v[92:95]
	v_mfma_f32_16x16x32_bf16 v[88:91], v[186:189], v[214:217], v[88:91]
	v_mfma_f32_16x16x32_bf16 v[84:87], v[186:189], v[218:221], v[84:87]
	v_mfma_f32_16x16x32_bf16 v[80:83], v[186:189], v[222:225], v[80:83]
	v_mfma_f32_16x16x32_bf16 v[76:79], v[190:193], v[210:213], v[76:79]
	v_mfma_f32_16x16x32_bf16 v[72:75], v[190:193], v[214:217], v[72:75]
	v_mfma_f32_16x16x32_bf16 v[68:71], v[190:193], v[218:221], v[68:71]
	v_mfma_f32_16x16x32_bf16 v[64:67], v[190:193], v[222:225], v[64:67]
	ds_read_b128 v[176:179], v248
	ds_read_b128 v[182:185], v248 offset:2048
	ds_read_b128 v[186:189], v248 offset:4096
	ds_read_b128 v[190:193], v248 offset:6144
	ds_read_b128 v[226:229], v250 offset:32768
	ds_read_b128 v[230:233], v250 offset:34816
	ds_read_b128 v[234:237], v250 offset:36864
	ds_read_b128 v[238:241], v250 offset:38912
	s_waitcnt lgkmcnt(8)
	v_mfma_f32_16x16x32_bf16 v[60:63], v[194:197], v[210:213], v[60:63]
	v_mfma_f32_16x16x32_bf16 v[56:59], v[194:197], v[214:217], v[56:59]
	v_mfma_f32_16x16x32_bf16 v[52:55], v[194:197], v[218:221], v[52:55]
	v_mfma_f32_16x16x32_bf16 v[48:51], v[194:197], v[222:225], v[48:51]
	v_mfma_f32_16x16x32_bf16 v[44:47], v[198:201], v[210:213], v[44:47]
	v_mfma_f32_16x16x32_bf16 v[40:43], v[198:201], v[214:217], v[40:43]
	v_mfma_f32_16x16x32_bf16 v[36:39], v[198:201], v[218:221], v[36:39]
	v_mfma_f32_16x16x32_bf16 v[32:35], v[198:201], v[222:225], v[32:35]
	v_mfma_f32_16x16x32_bf16 v[28:31], v[202:205], v[210:213], v[28:31]
	v_mfma_f32_16x16x32_bf16 v[24:27], v[202:205], v[214:217], v[24:27]
	v_mfma_f32_16x16x32_bf16 v[20:23], v[202:205], v[218:221], v[20:23]
	v_mfma_f32_16x16x32_bf16 v[16:19], v[202:205], v[222:225], v[16:19]
	v_mfma_f32_16x16x32_bf16 v[8:11], v[206:209], v[210:213], v[8:11]
	v_mfma_f32_16x16x32_bf16 v[0:3], v[206:209], v[214:217], v[0:3]
	v_mfma_f32_16x16x32_bf16 v[12:15], v[206:209], v[218:221], v[12:15]
	v_mfma_f32_16x16x32_bf16 v[4:7], v[206:209], v[222:225], v[4:7]
	ds_read_b128 v[194:197], v248 offset:8192
	ds_read_b128 v[198:201], v248 offset:10240
	ds_read_b128 v[202:205], v248 offset:12288
	ds_read_b128 v[206:209], v248 offset:14336
	s_waitcnt lgkmcnt(4)
	v_mfma_f32_16x16x32_bf16 v[124:127], v[176:179], v[226:229], v[124:127]
	v_mfma_f32_16x16x32_bf16 v[120:123], v[176:179], v[230:233], v[120:123]
	v_mfma_f32_16x16x32_bf16 v[116:119], v[176:179], v[234:237], v[116:119]
	v_mfma_f32_16x16x32_bf16 v[112:115], v[176:179], v[238:241], v[112:115]
	v_mfma_f32_16x16x32_bf16 v[108:111], v[182:185], v[226:229], v[108:111]
	v_mfma_f32_16x16x32_bf16 v[104:107], v[182:185], v[230:233], v[104:107]
	v_mfma_f32_16x16x32_bf16 v[100:103], v[182:185], v[234:237], v[100:103]
	v_mfma_f32_16x16x32_bf16 v[96:99], v[182:185], v[238:241], v[96:99]
	v_mfma_f32_16x16x32_bf16 v[92:95], v[186:189], v[226:229], v[92:95]
	v_mfma_f32_16x16x32_bf16 v[88:91], v[186:189], v[230:233], v[88:91]
	v_mfma_f32_16x16x32_bf16 v[84:87], v[186:189], v[234:237], v[84:87]
	v_mfma_f32_16x16x32_bf16 v[80:83], v[186:189], v[238:241], v[80:83]
	v_mfma_f32_16x16x32_bf16 v[76:79], v[190:193], v[226:229], v[76:79]
	v_mfma_f32_16x16x32_bf16 v[72:75], v[190:193], v[230:233], v[72:75]
	v_mfma_f32_16x16x32_bf16 v[68:71], v[190:193], v[234:237], v[68:71]
	v_mfma_f32_16x16x32_bf16 v[64:67], v[190:193], v[238:241], v[64:67]
	s_add_u32 s68, s68, 0x80
	s_addc_u32 s69, s69, 0
	s_add_i32 s86, s86, 1
	s_branch .Lg5_top
.Lg5_last:
	s_waitcnt lgkmcnt(0)
	s_waitcnt vmcnt(0)
	s_barrier
	v_mfma_f32_16x16x32_bf16 v[60:63], v[194:197], v[226:229], v[60:63]
	v_mfma_f32_16x16x32_bf16 v[56:59], v[194:197], v[230:233], v[56:59]
	s_xor_b32 s87, s87, 0x10000
	ds_read_b128 v[176:179], v247
	ds_read_b128 v[182:185], v247 offset:2048
	ds_read_b128 v[186:189], v247 offset:4096
	ds_read_b128 v[190:193], v247 offset:6144
	ds_read_b128 v[210:213], v249 offset:32768
	ds_read_b128 v[214:217], v249 offset:34816
	ds_read_b128 v[218:221], v249 offset:36864
	ds_read_b128 v[222:225], v249 offset:38912
	v_mfma_f32_16x16x32_bf16 v[52:55], v[194:197], v[234:237], v[52:55]
	v_mfma_f32_16x16x32_bf16 v[48:51], v[194:197], v[238:241], v[48:51]
	v_mfma_f32_16x16x32_bf16 v[44:47], v[198:201], v[226:229], v[44:47]
	v_mfma_f32_16x16x32_bf16 v[40:43], v[198:201], v[230:233], v[40:43]
	v_mfma_f32_16x16x32_bf16 v[36:39], v[198:201], v[234:237], v[36:39]
	v_mfma_f32_16x16x32_bf16 v[32:35], v[198:201], v[238:241], v[32:35]
	v_mfma_f32_16x16x32_bf16 v[28:31], v[202:205], v[226:229], v[28:31]
	v_mfma_f32_16x16x32_bf16 v[24:27], v[202:205], v[230:233], v[24:27]
	v_mfma_f32_16x16x32_bf16 v[20:23], v[202:205], v[234:237], v[20:23]
	v_mfma_f32_16x16x32_bf16 v[16:19], v[202:205], v[238:241], v[16:19]
	v_mfma_f32_16x16x32_bf16 v[8:11], v[206:209], v[226:229], v[8:11]
	v_mfma_f32_16x16x32_bf16 v[0:3], v[206:209], v[230:233], v[0:3]
	v_mfma_f32_16x16x32_bf16 v[12:15], v[206:209], v[234:237], v[12:15]
	v_mfma_f32_16x16x32_bf16 v[4:7], v[206:209], v[238:241], v[4:7]
	ds_read_b128 v[194:197], v247 offset:8192
	ds_read_b128 v[198:201], v247 offset:10240
	ds_read_b128 v[202:205], v247 offset:12288
	ds_read_b128 v[206:209], v247 offset:14336
	s_waitcnt lgkmcnt(4)
	v_mfma_f32_16x16x32_bf16 v[124:127], v[176:179], v[210:213], v[124:127]
	v_mfma_f32_16x16x32_bf16 v[120:123], v[176:179], v[214:217], v[120:123]
	v_mfma_f32_16x16x32_bf16 v[116:119], v[176:179], v[218:221], v[116:119]
	v_mfma_f32_16x16x32_bf16 v[112:115], v[176:179], v[222:225], v[112:115]
	v_mfma_f32_16x16x32_bf16 v[108:111], v[182:185], v[210:213], v[108:111]
	v_mfma_f32_16x16x32_bf16 v[104:107], v[182:185], v[214:217], v[104:107]
	v_mfma_f32_16x16x32_bf16 v[100:103], v[182:185], v[218:221], v[100:103]
	v_mfma_f32_16x16x32_bf16 v[96:99], v[182:185], v[222:225], v[96:99]
	v_mfma_f32_16x16x32_bf16 v[92:95], v[186:189], v[210:213], v[92:95]
	v_mfma_f32_16x16x32_bf16 v[88:91], v[186:189], v[214:217], v[88:91]
	v_mfma_f32_16x16x32_bf16 v[84:87], v[186:189], v[218:221], v[84:87]
	v_mfma_f32_16x16x32_bf16 v[80:83], v[186:189], v[222:225], v[80:83]
	v_mfma_f32_16x16x32_bf16 v[76:79], v[190:193], v[210:213], v[76:79]
	v_mfma_f32_16x16x32_bf16 v[72:75], v[190:193], v[214:217], v[72:75]
	v_mfma_f32_16x16x32_bf16 v[68:71], v[190:193], v[218:221], v[68:71]
	v_mfma_f32_16x16x32_bf16 v[64:67], v[190:193], v[222:225], v[64:67]
	ds_read_b128 v[176:179], v248
	ds_read_b128 v[182:185], v248 offset:2048
	ds_read_b128 v[186:189], v248 offset:4096
	ds_read_b128 v[190:193], v248 offset:6144
	ds_read_b128 v[226:229], v250 offset:32768
	ds_read_b128 v[230:233], v250 offset:34816
	ds_read_b128 v[234:237], v250 offset:36864
	ds_read_b128 v[238:241], v250 offset:38912
	s_waitcnt lgkmcnt(8)
	v_mfma_f32_16x16x32_bf16 v[60:63], v[194:197], v[210:213], v[60:63]
	v_mfma_f32_16x16x32_bf16 v[56:59], v[194:197], v[214:217], v[56:59]
	v_mfma_f32_16x16x32_bf16 v[52:55], v[194:197], v[218:221], v[52:55]
	v_mfma_f32_16x16x32_bf16 v[48:51], v[194:197], v[222:225], v[48:51]
	v_mfma_f32_16x16x32_bf16 v[44:47], v[198:201], v[210:213], v[44:47]
	v_mfma_f32_16x16x32_bf16 v[40:43], v[198:201], v[214:217], v[40:43]
	v_mfma_f32_16x16x32_bf16 v[36:39], v[198:201], v[218:221], v[36:39]
	v_mfma_f32_16x16x32_bf16 v[32:35], v[198:201], v[222:225], v[32:35]
	v_mfma_f32_16x16x32_bf16 v[28:31], v[202:205], v[210:213], v[28:31]
	v_mfma_f32_16x16x32_bf16 v[24:27], v[202:205], v[214:217], v[24:27]
	v_mfma_f32_16x16x32_bf16 v[20:23], v[202:205], v[218:221], v[20:23]
	v_mfma_f32_16x16x32_bf16 v[16:19], v[202:205], v[222:225], v[16:19]
	v_mfma_f32_16x16x32_bf16 v[8:11], v[206:209], v[210:213], v[8:11]
	v_mfma_f32_16x16x32_bf16 v[0:3], v[206:209], v[214:217], v[0:3]
	v_mfma_f32_16x16x32_bf16 v[12:15], v[206:209], v[218:221], v[12:15]
	v_mfma_f32_16x16x32_bf16 v[4:7], v[206:209], v[222:225], v[4:7]
	ds_read_b128 v[194:197], v248 offset:8192
	ds_read_b128 v[198:201], v248 offset:10240
	ds_read_b128 v[202:205], v248 offset:12288
	ds_read_b128 v[206:209], v248 offset:14336
	s_waitcnt lgkmcnt(4)
	v_mfma_f32_16x16x32_bf16 v[124:127], v[176:179], v[226:229], v[124:127]
	v_mfma_f32_16x16x32_bf16 v[120:123], v[176:179], v[230:233], v[120:123]
	v_mfma_f32_16x16x32_bf16 v[116:119], v[176:179], v[234:237], v[116:119]
	v_mfma_f32_16x16x32_bf16 v[112:115], v[176:179], v[238:241], v[112:115]
	v_mfma_f32_16x16x32_bf16 v[108:111], v[182:185], v[226:229], v[108:111]
	v_mfma_f32_16x16x32_bf16 v[104:107], v[182:185], v[230:233], v[104:107]
	v_mfma_f32_16x16x32_bf16 v[100:103], v[182:185], v[234:237], v[100:103]
	v_mfma_f32_16x16x32_bf16 v[96:99], v[182:185], v[238:241], v[96:99]
	v_mfma_f32_16x16x32_bf16 v[92:95], v[186:189], v[226:229], v[92:95]
	v_mfma_f32_16x16x32_bf16 v[88:91], v[186:189], v[230:233], v[88:91]
	v_mfma_f32_16x16x32_bf16 v[84:87], v[186:189], v[234:237], v[84:87]
	v_mfma_f32_16x16x32_bf16 v[80:83], v[186:189], v[238:241], v[80:83]
	v_mfma_f32_16x16x32_bf16 v[76:79], v[190:193], v[226:229], v[76:79]
	v_mfma_f32_16x16x32_bf16 v[72:75], v[190:193], v[230:233], v[72:75]
	v_mfma_f32_16x16x32_bf16 v[68:71], v[190:193], v[234:237], v[68:71]
	v_mfma_f32_16x16x32_bf16 v[64:67], v[190:193], v[238:241], v[64:67]
	s_add_u32 s68, s68, 0x80
	s_addc_u32 s69, s69, 0
	s_add_i32 s86, s86, 1
	s_waitcnt lgkmcnt(0)
	s_waitcnt vmcnt(0)
	s_barrier
	v_mfma_f32_16x16x32_bf16 v[60:63], v[194:197], v[226:229], v[60:63]
	v_mfma_f32_16x16x32_bf16 v[56:59], v[194:197], v[230:233], v[56:59]
	v_mfma_f32_16x16x32_bf16 v[52:55], v[194:197], v[234:237], v[52:55]
	v_mfma_f32_16x16x32_bf16 v[48:51], v[194:197], v[238:241], v[48:51]
	v_mfma_f32_16x16x32_bf16 v[44:47], v[198:201], v[226:229], v[44:47]
	v_mfma_f32_16x16x32_bf16 v[40:43], v[198:201], v[230:233], v[40:43]
	v_mfma_f32_16x16x32_bf16 v[36:39], v[198:201], v[234:237], v[36:39]
	v_mfma_f32_16x16x32_bf16 v[32:35], v[198:201], v[238:241], v[32:35]
	v_mfma_f32_16x16x32_bf16 v[28:31], v[202:205], v[226:229], v[28:31]
	v_mfma_f32_16x16x32_bf16 v[24:27], v[202:205], v[230:233], v[24:27]
	v_mfma_f32_16x16x32_bf16 v[20:23], v[202:205], v[234:237], v[20:23]
	v_mfma_f32_16x16x32_bf16 v[16:19], v[202:205], v[238:241], v[16:19]
	v_mfma_f32_16x16x32_bf16 v[8:11], v[206:209], v[226:229], v[8:11]
	v_mfma_f32_16x16x32_bf16 v[0:3], v[206:209], v[230:233], v[0:3]
	v_mfma_f32_16x16x32_bf16 v[12:15], v[206:209], v[234:237], v[12:15]
	v_mfma_f32_16x16x32_bf16 v[4:7], v[206:209], v[238:241], v[4:7]
	s_nop 7
	s_nop 7
	s_sub_u32 s68, s68, s34
	s_subb_u32 s69, s69, s35
	s_mov_b32 s87, 0x80000
	s_mov_b32 s87, 0x80000
	s_mov_b64 s[70:71], 0
	s_mov_b64 vcc, exec
	s_branch .LBB0_666

.Lg6_top:
	s_waitcnt lgkmcnt(0)
	s_waitcnt vmcnt(0)
	s_barrier
	v_mfma_f32_16x16x32_bf16 v[60:63], v[198:201], v[230:233], v[60:63]
	v_mfma_f32_16x16x32_bf16 v[56:59], v[198:201], v[234:237], v[56:59]
	v_xor_b32_e32 v180, 0x10000, v180
	v_xor_b32_e32 v249, 0x10000, v249
	v_xor_b32_e32 v248, 0x10000, v248
	v_xor_b32_e32 v250, 0x10000, v250
	s_xor_b32 s69, s69, 0x10000
	s_mov_b32 m0, s69
	s_add_u32 s66, s64, s44
	s_addc_u32 s67, s65, s45
	global_load_lds_dwordx4 v246, s[66:67]
	s_add_u32 m0, s69, 0x2000
	s_add_u32 s66, s64, s46
	s_addc_u32 s67, s65, s47
	global_load_lds_dwordx4 v246, s[66:67]
	ds_read_b128 v[182:185], v180
	ds_read_b128 v[186:189], v180 offset:2048
	ds_read_b128 v[190:193], v180 offset:4096
	ds_read_b128 v[194:197], v180 offset:6144
	ds_read_b128 v[214:217], v249 offset:32768
	ds_read_b128 v[218:221], v249 offset:34816
	ds_read_b128 v[222:225], v249 offset:36864
	ds_read_b128 v[226:229], v249 offset:38912
	v_mfma_f32_16x16x32_bf16 v[52:55], v[198:201], v[238:241], v[52:55]
	v_mfma_f32_16x16x32_bf16 v[48:51], v[198:201], v[242:245], v[48:51]
	s_add_u32 m0, s69, 0x4000
	s_add_u32 s66, s64, s48
	s_addc_u32 s67, s65, s49
	global_load_lds_dwordx4 v246, s[66:67]
	v_mfma_f32_16x16x32_bf16 v[44:47], v[202:205], v[230:233], v[44:47]
	v_mfma_f32_16x16x32_bf16 v[40:43], v[202:205], v[234:237], v[40:43]
	s_add_u32 m0, s69, 0x6000
	s_add_u32 s66, s64, s50
	s_addc_u32 s67, s65, s51
	global_load_lds_dwordx4 v246, s[66:67]
	v_mfma_f32_16x16x32_bf16 v[36:39], v[202:205], v[238:241], v[36:39]
	v_mfma_f32_16x16x32_bf16 v[32:35], v[202:205], v[242:245], v[32:35]
	s_add_u32 m0, s69, 0x8000
	s_add_u32 s66, s64, s52
	s_addc_u32 s67, s65, s53
	global_load_lds_dwordx4 v247, s[66:67]
	v_mfma_f32_16x16x32_bf16 v[28:31], v[206:209], v[230:233], v[28:31]
	v_mfma_f32_16x16x32_bf16 v[24:27], v[206:209], v[234:237], v[24:27]
	s_add_u32 m0, s69, 0xa000
	s_add_u32 s66, s64, s54
	s_addc_u32 s67, s65, s55
	global_load_lds_dwordx4 v247, s[66:67]
	v_mfma_f32_16x16x32_bf16 v[20:23], v[206:209], v[238:241], v[20:23]
	v_mfma_f32_16x16x32_bf16 v[16:19], v[206:209], v[242:245], v[16:19]
	s_add_u32 m0, s69, 0xc000
	s_add_u32 s66, s64, s60
	s_addc_u32 s67, s65, s61
	global_load_lds_dwordx4 v247, s[66:67]
	v_mfma_f32_16x16x32_bf16 v[12:15], v[210:213], v[230:233], v[12:15]
	v_mfma_f32_16x16x32_bf16 v[0:3], v[210:213], v[234:237], v[0:3]
	s_add_u32 m0, s69, 0xe000
	s_add_u32 s66, s64, s62
	s_addc_u32 s67, s65, s63
	global_load_lds_dwordx4 v247, s[66:67]
	v_mfma_f32_16x16x32_bf16 v[8:11], v[210:213], v[238:241], v[8:11]
	v_mfma_f32_16x16x32_bf16 v[4:7], v[210:213], v[242:245], v[4:7]
.Lg6_entry:
	ds_read_b128 v[198:201], v180 offset:8192
	ds_read_b128 v[202:205], v180 offset:10240
	ds_read_b128 v[206:209], v180 offset:12288
	ds_read_b128 v[210:213], v180 offset:14336
	s_waitcnt lgkmcnt(4)
	v_mfma_f32_16x16x32_bf16 v[124:127], v[182:185], v[214:217], v[124:127]
	v_mfma_f32_16x16x32_bf16 v[120:123], v[182:185], v[218:221], v[120:123]
	v_mfma_f32_16x16x32_bf16 v[116:119], v[182:185], v[222:225], v[116:119]
	v_mfma_f32_16x16x32_bf16 v[112:115], v[182:185], v[226:229], v[112:115]
	v_mfma_f32_16x16x32_bf16 v[108:111], v[186:189], v[214:217], v[108:111]
	v_mfma_f32_16x16x32_bf16 v[104:107], v[186:189], v[218:221], v[104:107]
	v_mfma_f32_16x16x32_bf16 v[100:103], v[186:189], v[222:225], v[100:103]
	v_mfma_f32_16x16x32_bf16 v[96:99], v[186:189], v[226:229], v[96:99]
	v_mfma_f32_16x16x32_bf16 v[92:95], v[190:193], v[214:217], v[92:95]
	v_mfma_f32_16x16x32_bf16 v[88:91], v[190:193], v[218:221], v[88:91]
	v_mfma_f32_16x16x32_bf16 v[84:87], v[190:193], v[222:225], v[84:87]
	v_mfma_f32_16x16x32_bf16 v[80:83], v[190:193], v[226:229], v[80:83]
	v_mfma_f32_16x16x32_bf16 v[76:79], v[194:197], v[214:217], v[76:79]
	v_mfma_f32_16x16x32_bf16 v[72:75], v[194:197], v[218:221], v[72:75]
	v_mfma_f32_16x16x32_bf16 v[68:71], v[194:197], v[222:225], v[68:71]
	v_mfma_f32_16x16x32_bf16 v[64:67], v[194:197], v[226:229], v[64:67]
	ds_read_b128 v[182:185], v248
	ds_read_b128 v[186:189], v248 offset:2048
	ds_read_b128 v[190:193], v248 offset:4096
	ds_read_b128 v[194:197], v248 offset:6144
	ds_read_b128 v[230:233], v250 offset:32768
	ds_read_b128 v[234:237], v250 offset:34816
	ds_read_b128 v[238:241], v250 offset:36864
	ds_read_b128 v[242:245], v250 offset:38912
	s_waitcnt lgkmcnt(8)
	v_mfma_f32_16x16x32_bf16 v[60:63], v[198:201], v[214:217], v[60:63]
	v_mfma_f32_16x16x32_bf16 v[56:59], v[198:201], v[218:221], v[56:59]
	v_mfma_f32_16x16x32_bf16 v[52:55], v[198:201], v[222:225], v[52:55]
	v_mfma_f32_16x16x32_bf16 v[48:51], v[198:201], v[226:229], v[48:51]
	v_mfma_f32_16x16x32_bf16 v[44:47], v[202:205], v[214:217], v[44:47]
	v_mfma_f32_16x16x32_bf16 v[40:43], v[202:205], v[218:221], v[40:43]
	v_mfma_f32_16x16x32_bf16 v[36:39], v[202:205], v[222:225], v[36:39]
	v_mfma_f32_16x16x32_bf16 v[32:35], v[202:205], v[226:229], v[32:35]
	v_mfma_f32_16x16x32_bf16 v[28:31], v[206:209], v[214:217], v[28:31]
	v_mfma_f32_16x16x32_bf16 v[24:27], v[206:209], v[218:221], v[24:27]
	v_mfma_f32_16x16x32_bf16 v[20:23], v[206:209], v[222:225], v[20:23]
	v_mfma_f32_16x16x32_bf16 v[16:19], v[206:209], v[226:229], v[16:19]
	v_mfma_f32_16x16x32_bf16 v[12:15], v[210:213], v[214:217], v[12:15]
	v_mfma_f32_16x16x32_bf16 v[0:3], v[210:213], v[218:221], v[0:3]
	v_mfma_f32_16x16x32_bf16 v[8:11], v[210:213], v[222:225], v[8:11]
	v_mfma_f32_16x16x32_bf16 v[4:7], v[210:213], v[226:229], v[4:7]
	ds_read_b128 v[198:201], v248 offset:8192
	ds_read_b128 v[202:205], v248 offset:10240
	ds_read_b128 v[206:209], v248 offset:12288
	ds_read_b128 v[210:213], v248 offset:14336
	s_waitcnt lgkmcnt(4)
	v_mfma_f32_16x16x32_bf16 v[124:127], v[182:185], v[230:233], v[124:127]
	v_mfma_f32_16x16x32_bf16 v[120:123], v[182:185], v[234:237], v[120:123]
	v_mfma_f32_16x16x32_bf16 v[116:119], v[182:185], v[238:241], v[116:119]
	v_mfma_f32_16x16x32_bf16 v[112:115], v[182:185], v[242:245], v[112:115]
	v_mfma_f32_16x16x32_bf16 v[108:111], v[186:189], v[230:233], v[108:111]
	v_mfma_f32_16x16x32_bf16 v[104:107], v[186:189], v[234:237], v[104:107]
	v_mfma_f32_16x16x32_bf16 v[100:103], v[186:189], v[238:241], v[100:103]
	v_mfma_f32_16x16x32_bf16 v[96:99], v[186:189], v[242:245], v[96:99]
	v_mfma_f32_16x16x32_bf16 v[92:95], v[190:193], v[230:233], v[92:95]
	v_mfma_f32_16x16x32_bf16 v[88:91], v[190:193], v[234:237], v[88:91]
	v_mfma_f32_16x16x32_bf16 v[84:87], v[190:193], v[238:241], v[84:87]
	v_mfma_f32_16x16x32_bf16 v[80:83], v[190:193], v[242:245], v[80:83]
	v_mfma_f32_16x16x32_bf16 v[76:79], v[194:197], v[230:233], v[76:79]
	v_mfma_f32_16x16x32_bf16 v[72:75], v[194:197], v[234:237], v[72:75]
	v_mfma_f32_16x16x32_bf16 v[68:71], v[194:197], v[238:241], v[68:71]
	v_mfma_f32_16x16x32_bf16 v[64:67], v[194:197], v[242:245], v[64:67]
	s_add_u32 s64, s64, 0x80
	s_addc_u32 s65, s65, 0
	s_add_i32 s68, s68, 1
	s_cmp_lt_u32 s68, 31
	s_cbranch_scc1 .Lg6_top
	s_waitcnt lgkmcnt(0)
	s_waitcnt vmcnt(0)
	s_barrier
	v_mfma_f32_16x16x32_bf16 v[60:63], v[198:201], v[230:233], v[60:63]
	v_mfma_f32_16x16x32_bf16 v[56:59], v[198:201], v[234:237], v[56:59]
	v_xor_b32_e32 v180, 0x10000, v180
	v_xor_b32_e32 v249, 0x10000, v249
	v_xor_b32_e32 v248, 0x10000, v248
	v_xor_b32_e32 v250, 0x10000, v250
	s_xor_b32 s69, s69, 0x10000
	ds_read_b128 v[182:185], v180
	ds_read_b128 v[186:189], v180 offset:2048
	ds_read_b128 v[190:193], v180 offset:4096
	ds_read_b128 v[194:197], v180 offset:6144
	ds_read_b128 v[214:217], v249 offset:32768
	ds_read_b128 v[218:221], v249 offset:34816
	ds_read_b128 v[222:225], v249 offset:36864
	ds_read_b128 v[226:229], v249 offset:38912
	v_mfma_f32_16x16x32_bf16 v[52:55], v[198:201], v[238:241], v[52:55]
	v_mfma_f32_16x16x32_bf16 v[48:51], v[198:201], v[242:245], v[48:51]
	v_mfma_f32_16x16x32_bf16 v[44:47], v[202:205], v[230:233], v[44:47]
	v_mfma_f32_16x16x32_bf16 v[40:43], v[202:205], v[234:237], v[40:43]
	v_mfma_f32_16x16x32_bf16 v[36:39], v[202:205], v[238:241], v[36:39]
	v_mfma_f32_16x16x32_bf16 v[32:35], v[202:205], v[242:245], v[32:35]
	v_mfma_f32_16x16x32_bf16 v[28:31], v[206:209], v[230:233], v[28:31]
	v_mfma_f32_16x16x32_bf16 v[24:27], v[206:209], v[234:237], v[24:27]
	v_mfma_f32_16x16x32_bf16 v[20:23], v[206:209], v[238:241], v[20:23]
	v_mfma_f32_16x16x32_bf16 v[16:19], v[206:209], v[242:245], v[16:19]
	v_mfma_f32_16x16x32_bf16 v[12:15], v[210:213], v[230:233], v[12:15]
	v_mfma_f32_16x16x32_bf16 v[0:3], v[210:213], v[234:237], v[0:3]
	v_mfma_f32_16x16x32_bf16 v[8:11], v[210:213], v[238:241], v[8:11]
	v_mfma_f32_16x16x32_bf16 v[4:7], v[210:213], v[242:245], v[4:7]
	ds_read_b128 v[198:201], v180 offset:8192
	ds_read_b128 v[202:205], v180 offset:10240
	ds_read_b128 v[206:209], v180 offset:12288
	ds_read_b128 v[210:213], v180 offset:14336
	s_waitcnt lgkmcnt(4)
	v_mfma_f32_16x16x32_bf16 v[124:127], v[182:185], v[214:217], v[124:127]
	v_mfma_f32_16x16x32_bf16 v[120:123], v[182:185], v[218:221], v[120:123]
	v_mfma_f32_16x16x32_bf16 v[116:119], v[182:185], v[222:225], v[116:119]
	v_mfma_f32_16x16x32_bf16 v[112:115], v[182:185], v[226:229], v[112:115]
	v_mfma_f32_16x16x32_bf16 v[108:111], v[186:189], v[214:217], v[108:111]
	v_mfma_f32_16x16x32_bf16 v[104:107], v[186:189], v[218:221], v[104:107]
	v_mfma_f32_16x16x32_bf16 v[100:103], v[186:189], v[222:225], v[100:103]
	v_mfma_f32_16x16x32_bf16 v[96:99], v[186:189], v[226:229], v[96:99]
	v_mfma_f32_16x16x32_bf16 v[92:95], v[190:193], v[214:217], v[92:95]
	v_mfma_f32_16x16x32_bf16 v[88:91], v[190:193], v[218:221], v[88:91]
	v_mfma_f32_16x16x32_bf16 v[84:87], v[190:193], v[222:225], v[84:87]
	v_mfma_f32_16x16x32_bf16 v[80:83], v[190:193], v[226:229], v[80:83]
	v_mfma_f32_16x16x32_bf16 v[76:79], v[194:197], v[214:217], v[76:79]
	v_mfma_f32_16x16x32_bf16 v[72:75], v[194:197], v[218:221], v[72:75]
	v_mfma_f32_16x16x32_bf16 v[68:71], v[194:197], v[222:225], v[68:71]
	v_mfma_f32_16x16x32_bf16 v[64:67], v[194:197], v[226:229], v[64:67]
	ds_read_b128 v[182:185], v248
	ds_read_b128 v[186:189], v248 offset:2048
	ds_read_b128 v[190:193], v248 offset:4096
	ds_read_b128 v[194:197], v248 offset:6144
	ds_read_b128 v[230:233], v250 offset:32768
	ds_read_b128 v[234:237], v250 offset:34816
	ds_read_b128 v[238:241], v250 offset:36864
	ds_read_b128 v[242:245], v250 offset:38912
	s_waitcnt lgkmcnt(8)
	v_mfma_f32_16x16x32_bf16 v[60:63], v[198:201], v[214:217], v[60:63]
	v_mfma_f32_16x16x32_bf16 v[56:59], v[198:201], v[218:221], v[56:59]
	v_mfma_f32_16x16x32_bf16 v[52:55], v[198:201], v[222:225], v[52:55]
	v_mfma_f32_16x16x32_bf16 v[48:51], v[198:201], v[226:229], v[48:51]
	v_mfma_f32_16x16x32_bf16 v[44:47], v[202:205], v[214:217], v[44:47]
	v_mfma_f32_16x16x32_bf16 v[40:43], v[202:205], v[218:221], v[40:43]
	v_mfma_f32_16x16x32_bf16 v[36:39], v[202:205], v[222:225], v[36:39]
	v_mfma_f32_16x16x32_bf16 v[32:35], v[202:205], v[226:229], v[32:35]
	v_mfma_f32_16x16x32_bf16 v[28:31], v[206:209], v[214:217], v[28:31]
	v_mfma_f32_16x16x32_bf16 v[24:27], v[206:209], v[218:221], v[24:27]
	v_mfma_f32_16x16x32_bf16 v[20:23], v[206:209], v[222:225], v[20:23]
	v_mfma_f32_16x16x32_bf16 v[16:19], v[206:209], v[226:229], v[16:19]
	v_mfma_f32_16x16x32_bf16 v[12:15], v[210:213], v[214:217], v[12:15]
	v_mfma_f32_16x16x32_bf16 v[0:3], v[210:213], v[218:221], v[0:3]
	v_mfma_f32_16x16x32_bf16 v[8:11], v[210:213], v[222:225], v[8:11]
	v_mfma_f32_16x16x32_bf16 v[4:7], v[210:213], v[226:229], v[4:7]
	ds_read_b128 v[198:201], v248 offset:8192
	ds_read_b128 v[202:205], v248 offset:10240
	ds_read_b128 v[206:209], v248 offset:12288
	ds_read_b128 v[210:213], v248 offset:14336
	s_waitcnt lgkmcnt(4)
	v_mfma_f32_16x16x32_bf16 v[124:127], v[182:185], v[230:233], v[124:127]
	v_mfma_f32_16x16x32_bf16 v[120:123], v[182:185], v[234:237], v[120:123]
	v_mfma_f32_16x16x32_bf16 v[116:119], v[182:185], v[238:241], v[116:119]
	v_mfma_f32_16x16x32_bf16 v[112:115], v[182:185], v[242:245], v[112:115]
	v_mfma_f32_16x16x32_bf16 v[108:111], v[186:189], v[230:233], v[108:111]
	v_mfma_f32_16x16x32_bf16 v[104:107], v[186:189], v[234:237], v[104:107]
	v_mfma_f32_16x16x32_bf16 v[100:103], v[186:189], v[238:241], v[100:103]
	v_mfma_f32_16x16x32_bf16 v[96:99], v[186:189], v[242:245], v[96:99]
	v_mfma_f32_16x16x32_bf16 v[92:95], v[190:193], v[230:233], v[92:95]
	v_mfma_f32_16x16x32_bf16 v[88:91], v[190:193], v[234:237], v[88:91]
	v_mfma_f32_16x16x32_bf16 v[84:87], v[190:193], v[238:241], v[84:87]
	v_mfma_f32_16x16x32_bf16 v[80:83], v[190:193], v[242:245], v[80:83]
	v_mfma_f32_16x16x32_bf16 v[76:79], v[194:197], v[230:233], v[76:79]
	v_mfma_f32_16x16x32_bf16 v[72:75], v[194:197], v[234:237], v[72:75]
	v_mfma_f32_16x16x32_bf16 v[68:71], v[194:197], v[238:241], v[68:71]
	v_mfma_f32_16x16x32_bf16 v[64:67], v[194:197], v[242:245], v[64:67]
	s_add_u32 s64, s64, 0x80
	s_addc_u32 s65, s65, 0
	s_add_i32 s68, s68, 1
	s_waitcnt lgkmcnt(0)
	s_waitcnt vmcnt(0)
	s_barrier
	v_mfma_f32_16x16x32_bf16 v[60:63], v[198:201], v[230:233], v[60:63]
	v_mfma_f32_16x16x32_bf16 v[56:59], v[198:201], v[234:237], v[56:59]
	v_mfma_f32_16x16x32_bf16 v[52:55], v[198:201], v[238:241], v[52:55]
	v_mfma_f32_16x16x32_bf16 v[48:51], v[198:201], v[242:245], v[48:51]
	v_mfma_f32_16x16x32_bf16 v[44:47], v[202:205], v[230:233], v[44:47]
	v_mfma_f32_16x16x32_bf16 v[40:43], v[202:205], v[234:237], v[40:43]
	v_mfma_f32_16x16x32_bf16 v[36:39], v[202:205], v[238:241], v[36:39]
	v_mfma_f32_16x16x32_bf16 v[32:35], v[202:205], v[242:245], v[32:35]
	v_mfma_f32_16x16x32_bf16 v[28:31], v[206:209], v[230:233], v[28:31]
	v_mfma_f32_16x16x32_bf16 v[24:27], v[206:209], v[234:237], v[24:27]
	v_mfma_f32_16x16x32_bf16 v[20:23], v[206:209], v[238:241], v[20:23]
	v_mfma_f32_16x16x32_bf16 v[16:19], v[206:209], v[242:245], v[16:19]
	v_mfma_f32_16x16x32_bf16 v[12:15], v[210:213], v[230:233], v[12:15]
	v_mfma_f32_16x16x32_bf16 v[0:3], v[210:213], v[234:237], v[0:3]
	v_mfma_f32_16x16x32_bf16 v[8:11], v[210:213], v[238:241], v[8:11]
	v_mfma_f32_16x16x32_bf16 v[4:7], v[210:213], v[242:245], v[4:7]
	s_nop 7
	s_nop 7
	s_sub_u32 s64, s64, s34
	s_subb_u32 s65, s65, s35
	s_mov_b32 s69, 0x100000
	s_mov_b32 s70, 0x100000
	s_mov_b64 s[66:67], 0
	s_mov_b64 vcc, exec
	s_branch .LBB0_674

.Lg7_top:
	s_waitcnt lgkmcnt(0)
	s_waitcnt vmcnt(0)
	s_barrier
	v_mfma_f32_16x16x32_bf16 v[60:63], v[158:161], v[194:197], v[60:63]
	v_mfma_f32_16x16x32_bf16 v[56:59], v[158:161], v[198:201], v[56:59]
	s_xor_b32 s61, s61, 0x10000
	s_mov_b32 m0, s61
	s_add_u32 s50, s48, s14
	s_addc_u32 s51, s49, s15
	global_load_lds_dwordx4 v178, s[50:51]
	s_add_u32 m0, s61, 0x2000
	s_add_u32 s50, s48, s16
	s_addc_u32 s51, s49, s17
	global_load_lds_dwordx4 v178, s[50:51]
	ds_read_b128 v[142:145], v141
	ds_read_b128 v[146:149], v141 offset:2048
	ds_read_b128 v[150:153], v141 offset:4096
	ds_read_b128 v[154:157], v141 offset:6144
	ds_read_b128 v[174:177], v210 offset:32768
	ds_read_b128 v[182:185], v210 offset:34816
	ds_read_b128 v[186:189], v210 offset:36864
	ds_read_b128 v[190:193], v210 offset:38912
	v_mfma_f32_16x16x32_bf16 v[52:55], v[158:161], v[202:205], v[52:55]
	v_mfma_f32_16x16x32_bf16 v[48:51], v[158:161], v[206:209], v[48:51]
	s_add_u32 m0, s61, 0x4000
	s_add_u32 s50, s48, s18
	s_addc_u32 s51, s49, s19
	global_load_lds_dwordx4 v178, s[50:51]
	v_mfma_f32_16x16x32_bf16 v[44:47], v[162:165], v[194:197], v[44:47]
	v_mfma_f32_16x16x32_bf16 v[32:35], v[162:165], v[198:201], v[32:35]
	s_add_u32 m0, s61, 0x6000
	s_add_u32 s50, s48, s22
	s_addc_u32 s51, s49, s23
	global_load_lds_dwordx4 v178, s[50:51]
	v_mfma_f32_16x16x32_bf16 v[28:31], v[162:165], v[202:205], v[28:31]
	v_mfma_f32_16x16x32_bf16 v[24:27], v[162:165], v[206:209], v[24:27]
	s_add_u32 m0, s61, 0x8000
	s_add_u32 s50, s48, s36
	s_addc_u32 s51, s49, s37
	global_load_lds_dwordx4 v179, s[50:51]
	v_mfma_f32_16x16x32_bf16 v[20:23], v[166:169], v[194:197], v[20:23]
	v_mfma_f32_16x16x32_bf16 v[16:19], v[166:169], v[198:201], v[16:19]
	s_add_u32 m0, s61, 0xa000
	s_add_u32 s50, s48, s40
	s_addc_u32 s51, s49, s41
	global_load_lds_dwordx4 v179, s[50:51]
	v_mfma_f32_16x16x32_bf16 v[12:15], v[166:169], v[202:205], v[12:15]
	v_mfma_f32_16x16x32_bf16 v[8:11], v[166:169], v[206:209], v[8:11]
	s_add_u32 m0, s61, 0xc000
	s_add_u32 s50, s48, s42
	s_addc_u32 s51, s49, s43
	global_load_lds_dwordx4 v179, s[50:51]
	v_mfma_f32_16x16x32_bf16 v[4:7], v[170:173], v[194:197], v[4:7]
	v_mfma_f32_16x16x32_bf16 v[0:3], v[170:173], v[198:201], v[0:3]
	s_add_u32 m0, s61, 0xe000
	s_add_u32 s50, s48, s44
	s_addc_u32 s51, s49, s45
	global_load_lds_dwordx4 v179, s[50:51]
	v_mfma_f32_16x16x32_bf16 v[40:43], v[170:173], v[202:205], v[40:43]
	v_mfma_f32_16x16x32_bf16 v[36:39], v[170:173], v[206:209], v[36:39]
.Lg7_entry:
	ds_read_b128 v[158:161], v141 offset:8192
	ds_read_b128 v[162:165], v141 offset:10240
	ds_read_b128 v[166:169], v141 offset:12288
	ds_read_b128 v[170:173], v141 offset:14336
	s_waitcnt lgkmcnt(4)
	v_mfma_f32_16x16x32_bf16 v[124:127], v[142:145], v[174:177], v[124:127]
	v_mfma_f32_16x16x32_bf16 v[120:123], v[142:145], v[182:185], v[120:123]
	v_mfma_f32_16x16x32_bf16 v[116:119], v[142:145], v[186:189], v[116:119]
	v_mfma_f32_16x16x32_bf16 v[112:115], v[142:145], v[190:193], v[112:115]
	v_mfma_f32_16x16x32_bf16 v[108:111], v[146:149], v[174:177], v[108:111]
	v_mfma_f32_16x16x32_bf16 v[104:107], v[146:149], v[182:185], v[104:107]
	v_mfma_f32_16x16x32_bf16 v[100:103], v[146:149], v[186:189], v[100:103]
	v_mfma_f32_16x16x32_bf16 v[96:99], v[146:149], v[190:193], v[96:99]
	v_mfma_f32_16x16x32_bf16 v[92:95], v[150:153], v[174:177], v[92:95]
	v_mfma_f32_16x16x32_bf16 v[88:91], v[150:153], v[182:185], v[88:91]
	v_mfma_f32_16x16x32_bf16 v[84:87], v[150:153], v[186:189], v[84:87]
	v_mfma_f32_16x16x32_bf16 v[80:83], v[150:153], v[190:193], v[80:83]
	v_mfma_f32_16x16x32_bf16 v[76:79], v[154:157], v[174:177], v[76:79]
	v_mfma_f32_16x16x32_bf16 v[72:75], v[154:157], v[182:185], v[72:75]
	v_mfma_f32_16x16x32_bf16 v[68:71], v[154:157], v[186:189], v[68:71]
	v_mfma_f32_16x16x32_bf16 v[64:67], v[154:157], v[190:193], v[64:67]
	ds_read_b128 v[142:145], v180
	ds_read_b128 v[146:149], v180 offset:2048
	ds_read_b128 v[150:153], v180 offset:4096
	ds_read_b128 v[154:157], v180 offset:6144
	ds_read_b128 v[194:197], v211 offset:32768
	ds_read_b128 v[198:201], v211 offset:34816
	ds_read_b128 v[202:205], v211 offset:36864
	ds_read_b128 v[206:209], v211 offset:38912
	s_waitcnt lgkmcnt(8)
	v_mfma_f32_16x16x32_bf16 v[60:63], v[158:161], v[174:177], v[60:63]
	v_mfma_f32_16x16x32_bf16 v[56:59], v[158:161], v[182:185], v[56:59]
	v_mfma_f32_16x16x32_bf16 v[52:55], v[158:161], v[186:189], v[52:55]
	v_mfma_f32_16x16x32_bf16 v[48:51], v[158:161], v[190:193], v[48:51]
	v_mfma_f32_16x16x32_bf16 v[44:47], v[162:165], v[174:177], v[44:47]
	v_mfma_f32_16x16x32_bf16 v[32:35], v[162:165], v[182:185], v[32:35]
	v_mfma_f32_16x16x32_bf16 v[28:31], v[162:165], v[186:189], v[28:31]
	v_mfma_f32_16x16x32_bf16 v[24:27], v[162:165], v[190:193], v[24:27]
	v_mfma_f32_16x16x32_bf16 v[20:23], v[166:169], v[174:177], v[20:23]
	v_mfma_f32_16x16x32_bf16 v[16:19], v[166:169], v[182:185], v[16:19]
	v_mfma_f32_16x16x32_bf16 v[12:15], v[166:169], v[186:189], v[12:15]
	v_mfma_f32_16x16x32_bf16 v[8:11], v[166:169], v[190:193], v[8:11]
	v_mfma_f32_16x16x32_bf16 v[4:7], v[170:173], v[174:177], v[4:7]
	v_mfma_f32_16x16x32_bf16 v[0:3], v[170:173], v[182:185], v[0:3]
	v_mfma_f32_16x16x32_bf16 v[40:43], v[170:173], v[186:189], v[40:43]
	v_mfma_f32_16x16x32_bf16 v[36:39], v[170:173], v[190:193], v[36:39]
	ds_read_b128 v[158:161], v180 offset:8192
	ds_read_b128 v[162:165], v180 offset:10240
	ds_read_b128 v[166:169], v180 offset:12288
	ds_read_b128 v[170:173], v180 offset:14336
	s_waitcnt lgkmcnt(4)
	v_mfma_f32_16x16x32_bf16 v[124:127], v[142:145], v[194:197], v[124:127]
	v_mfma_f32_16x16x32_bf16 v[120:123], v[142:145], v[198:201], v[120:123]
	v_mfma_f32_16x16x32_bf16 v[116:119], v[142:145], v[202:205], v[116:119]
	v_mfma_f32_16x16x32_bf16 v[112:115], v[142:145], v[206:209], v[112:115]
	v_mfma_f32_16x16x32_bf16 v[108:111], v[146:149], v[194:197], v[108:111]
	v_mfma_f32_16x16x32_bf16 v[104:107], v[146:149], v[198:201], v[104:107]
	v_mfma_f32_16x16x32_bf16 v[100:103], v[146:149], v[202:205], v[100:103]
	v_mfma_f32_16x16x32_bf16 v[96:99], v[146:149], v[206:209], v[96:99]
	v_mfma_f32_16x16x32_bf16 v[92:95], v[150:153], v[194:197], v[92:95]
	v_mfma_f32_16x16x32_bf16 v[88:91], v[150:153], v[198:201], v[88:91]
	v_mfma_f32_16x16x32_bf16 v[84:87], v[150:153], v[202:205], v[84:87]
	v_mfma_f32_16x16x32_bf16 v[80:83], v[150:153], v[206:209], v[80:83]
	v_mfma_f32_16x16x32_bf16 v[76:79], v[154:157], v[194:197], v[76:79]
	v_mfma_f32_16x16x32_bf16 v[72:75], v[154:157], v[198:201], v[72:75]
	v_mfma_f32_16x16x32_bf16 v[68:71], v[154:157], v[202:205], v[68:71]
	v_mfma_f32_16x16x32_bf16 v[64:67], v[154:157], v[206:209], v[64:67]
	s_add_u32 s48, s48, 0x80
	s_addc_u32 s49, s49, 0
	s_add_i32 s47, s47, 1
	s_cmp_lt_u32 s47, 31
	s_cbranch_scc0 .Lg7_last
	s_waitcnt lgkmcnt(0)
	s_waitcnt vmcnt(0)
	s_barrier
	v_mfma_f32_16x16x32_bf16 v[60:63], v[158:161], v[194:197], v[60:63]
	v_mfma_f32_16x16x32_bf16 v[56:59], v[158:161], v[198:201], v[56:59]
	s_xor_b32 s61, s61, 0x10000
	s_mov_b32 m0, s61
	s_add_u32 s50, s48, s14
	s_addc_u32 s51, s49, s15
	global_load_lds_dwordx4 v178, s[50:51]
	s_add_u32 m0, s61, 0x2000
	s_add_u32 s50, s48, s16
	s_addc_u32 s51, s49, s17
	global_load_lds_dwordx4 v178, s[50:51]
	ds_read_b128 v[142:145], v212
	ds_read_b128 v[146:149], v212 offset:2048
	ds_read_b128 v[150:153], v212 offset:4096
	ds_read_b128 v[154:157], v212 offset:6144
	ds_read_b128 v[174:177], v214 offset:32768
	ds_read_b128 v[182:185], v214 offset:34816
	ds_read_b128 v[186:189], v214 offset:36864
	ds_read_b128 v[190:193], v214 offset:38912
	v_mfma_f32_16x16x32_bf16 v[52:55], v[158:161], v[202:205], v[52:55]
	v_mfma_f32_16x16x32_bf16 v[48:51], v[158:161], v[206:209], v[48:51]
	s_add_u32 m0, s61, 0x4000
	s_add_u32 s50, s48, s18
	s_addc_u32 s51, s49, s19
	global_load_lds_dwordx4 v178, s[50:51]
	v_mfma_f32_16x16x32_bf16 v[44:47], v[162:165], v[194:197], v[44:47]
	v_mfma_f32_16x16x32_bf16 v[32:35], v[162:165], v[198:201], v[32:35]
	s_add_u32 m0, s61, 0x6000
	s_add_u32 s50, s48, s22
	s_addc_u32 s51, s49, s23
	global_load_lds_dwordx4 v178, s[50:51]
	v_mfma_f32_16x16x32_bf16 v[28:31], v[162:165], v[202:205], v[28:31]
	v_mfma_f32_16x16x32_bf16 v[24:27], v[162:165], v[206:209], v[24:27]
	s_add_u32 m0, s61, 0x8000
	s_add_u32 s50, s48, s36
	s_addc_u32 s51, s49, s37
	global_load_lds_dwordx4 v179, s[50:51]
	v_mfma_f32_16x16x32_bf16 v[20:23], v[166:169], v[194:197], v[20:23]
	v_mfma_f32_16x16x32_bf16 v[16:19], v[166:169], v[198:201], v[16:19]
	s_add_u32 m0, s61, 0xa000
	s_add_u32 s50, s48, s40
	s_addc_u32 s51, s49, s41
	global_load_lds_dwordx4 v179, s[50:51]
	v_mfma_f32_16x16x32_bf16 v[12:15], v[166:169], v[202:205], v[12:15]
	v_mfma_f32_16x16x32_bf16 v[8:11], v[166:169], v[206:209], v[8:11]
	s_add_u32 m0, s61, 0xc000
	s_add_u32 s50, s48, s42
	s_addc_u32 s51, s49, s43
	global_load_lds_dwordx4 v179, s[50:51]
	v_mfma_f32_16x16x32_bf16 v[4:7], v[170:173], v[194:197], v[4:7]
	v_mfma_f32_16x16x32_bf16 v[0:3], v[170:173], v[198:201], v[0:3]
	s_add_u32 m0, s61, 0xe000
	s_add_u32 s50, s48, s44
	s_addc_u32 s51, s49, s45
	global_load_lds_dwordx4 v179, s[50:51]
	v_mfma_f32_16x16x32_bf16 v[40:43], v[170:173], v[202:205], v[40:43]
	v_mfma_f32_16x16x32_bf16 v[36:39], v[170:173], v[206:209], v[36:39]
	ds_read_b128 v[158:161], v212 offset:8192
	ds_read_b128 v[162:165], v212 offset:10240
	ds_read_b128 v[166:169], v212 offset:12288
	ds_read_b128 v[170:173], v212 offset:14336
	s_waitcnt lgkmcnt(4)
	v_mfma_f32_16x16x32_bf16 v[124:127], v[142:145], v[174:177], v[124:127]
	v_mfma_f32_16x16x32_bf16 v[120:123], v[142:145], v[182:185], v[120:123]
	v_mfma_f32_16x16x32_bf16 v[116:119], v[142:145], v[186:189], v[116:119]
	v_mfma_f32_16x16x32_bf16 v[112:115], v[142:145], v[190:193], v[112:115]
	v_mfma_f32_16x16x32_bf16 v[108:111], v[146:149], v[174:177], v[108:111]
	v_mfma_f32_16x16x32_bf16 v[104:107], v[146:149], v[182:185], v[104:107]
	v_mfma_f32_16x16x32_bf16 v[100:103], v[146:149], v[186:189], v[100:103]
	v_mfma_f32_16x16x32_bf16 v[96:99], v[146:149], v[190:193], v[96:99]
	v_mfma_f32_16x16x32_bf16 v[92:95], v[150:153], v[174:177], v[92:95]
	v_mfma_f32_16x16x32_bf16 v[88:91], v[150:153], v[182:185], v[88:91]
	v_mfma_f32_16x16x32_bf16 v[84:87], v[150:153], v[186:189], v[84:87]
	v_mfma_f32_16x16x32_bf16 v[80:83], v[150:153], v[190:193], v[80:83]
	v_mfma_f32_16x16x32_bf16 v[76:79], v[154:157], v[174:177], v[76:79]
	v_mfma_f32_16x16x32_bf16 v[72:75], v[154:157], v[182:185], v[72:75]
	v_mfma_f32_16x16x32_bf16 v[68:71], v[154:157], v[186:189], v[68:71]
	v_mfma_f32_16x16x32_bf16 v[64:67], v[154:157], v[190:193], v[64:67]
	ds_read_b128 v[142:145], v213
	ds_read_b128 v[146:149], v213 offset:2048
	ds_read_b128 v[150:153], v213 offset:4096
	ds_read_b128 v[154:157], v213 offset:6144
	ds_read_b128 v[194:197], v215 offset:32768
	ds_read_b128 v[198:201], v215 offset:34816
	ds_read_b128 v[202:205], v215 offset:36864
	ds_read_b128 v[206:209], v215 offset:38912
	s_waitcnt lgkmcnt(8)
	v_mfma_f32_16x16x32_bf16 v[60:63], v[158:161], v[174:177], v[60:63]
	v_mfma_f32_16x16x32_bf16 v[56:59], v[158:161], v[182:185], v[56:59]
	v_mfma_f32_16x16x32_bf16 v[52:55], v[158:161], v[186:189], v[52:55]
	v_mfma_f32_16x16x32_bf16 v[48:51], v[158:161], v[190:193], v[48:51]
	v_mfma_f32_16x16x32_bf16 v[44:47], v[162:165], v[174:177], v[44:47]
	v_mfma_f32_16x16x32_bf16 v[32:35], v[162:165], v[182:185], v[32:35]
	v_mfma_f32_16x16x32_bf16 v[28:31], v[162:165], v[186:189], v[28:31]
	v_mfma_f32_16x16x32_bf16 v[24:27], v[162:165], v[190:193], v[24:27]
	v_mfma_f32_16x16x32_bf16 v[20:23], v[166:169], v[174:177], v[20:23]
	v_mfma_f32_16x16x32_bf16 v[16:19], v[166:169], v[182:185], v[16:19]
	v_mfma_f32_16x16x32_bf16 v[12:15], v[166:169], v[186:189], v[12:15]
	v_mfma_f32_16x16x32_bf16 v[8:11], v[166:169], v[190:193], v[8:11]
	v_mfma_f32_16x16x32_bf16 v[4:7], v[170:173], v[174:177], v[4:7]
	v_mfma_f32_16x16x32_bf16 v[0:3], v[170:173], v[182:185], v[0:3]
	v_mfma_f32_16x16x32_bf16 v[40:43], v[170:173], v[186:189], v[40:43]
	v_mfma_f32_16x16x32_bf16 v[36:39], v[170:173], v[190:193], v[36:39]
	ds_read_b128 v[158:161], v213 offset:8192
	ds_read_b128 v[162:165], v213 offset:10240
	ds_read_b128 v[166:169], v213 offset:12288
	ds_read_b128 v[170:173], v213 offset:14336
	s_waitcnt lgkmcnt(4)
	v_mfma_f32_16x16x32_bf16 v[124:127], v[142:145], v[194:197], v[124:127]
	v_mfma_f32_16x16x32_bf16 v[120:123], v[142:145], v[198:201], v[120:123]
	v_mfma_f32_16x16x32_bf16 v[116:119], v[142:145], v[202:205], v[116:119]
	v_mfma_f32_16x16x32_bf16 v[112:115], v[142:145], v[206:209], v[112:115]
	v_mfma_f32_16x16x32_bf16 v[108:111], v[146:149], v[194:197], v[108:111]
	v_mfma_f32_16x16x32_bf16 v[104:107], v[146:149], v[198:201], v[104:107]
	v_mfma_f32_16x16x32_bf16 v[100:103], v[146:149], v[202:205], v[100:103]
	v_mfma_f32_16x16x32_bf16 v[96:99], v[146:149], v[206:209], v[96:99]
	v_mfma_f32_16x16x32_bf16 v[92:95], v[150:153], v[194:197], v[92:95]
	v_mfma_f32_16x16x32_bf16 v[88:91], v[150:153], v[198:201], v[88:91]
	v_mfma_f32_16x16x32_bf16 v[84:87], v[150:153], v[202:205], v[84:87]
	v_mfma_f32_16x16x32_bf16 v[80:83], v[150:153], v[206:209], v[80:83]
	v_mfma_f32_16x16x32_bf16 v[76:79], v[154:157], v[194:197], v[76:79]
	v_mfma_f32_16x16x32_bf16 v[72:75], v[154:157], v[198:201], v[72:75]
	v_mfma_f32_16x16x32_bf16 v[68:71], v[154:157], v[202:205], v[68:71]
	v_mfma_f32_16x16x32_bf16 v[64:67], v[154:157], v[206:209], v[64:67]
	s_add_u32 s48, s48, 0x80
	s_addc_u32 s49, s49, 0
	s_add_i32 s47, s47, 1
	s_branch .Lg7_top
.Lg7_last:
	s_waitcnt lgkmcnt(0)
	s_waitcnt vmcnt(0)
	s_barrier
	v_mfma_f32_16x16x32_bf16 v[60:63], v[158:161], v[194:197], v[60:63]
	v_mfma_f32_16x16x32_bf16 v[56:59], v[158:161], v[198:201], v[56:59]
	s_xor_b32 s61, s61, 0x10000
	ds_read_b128 v[142:145], v212
	ds_read_b128 v[146:149], v212 offset:2048
	ds_read_b128 v[150:153], v212 offset:4096
	ds_read_b128 v[154:157], v212 offset:6144
	ds_read_b128 v[174:177], v214 offset:32768
	ds_read_b128 v[182:185], v214 offset:34816
	ds_read_b128 v[186:189], v214 offset:36864
	ds_read_b128 v[190:193], v214 offset:38912
	v_mfma_f32_16x16x32_bf16 v[52:55], v[158:161], v[202:205], v[52:55]
	v_mfma_f32_16x16x32_bf16 v[48:51], v[158:161], v[206:209], v[48:51]
	v_mfma_f32_16x16x32_bf16 v[44:47], v[162:165], v[194:197], v[44:47]
	v_mfma_f32_16x16x32_bf16 v[32:35], v[162:165], v[198:201], v[32:35]
	v_mfma_f32_16x16x32_bf16 v[28:31], v[162:165], v[202:205], v[28:31]
	v_mfma_f32_16x16x32_bf16 v[24:27], v[162:165], v[206:209], v[24:27]
	v_mfma_f32_16x16x32_bf16 v[20:23], v[166:169], v[194:197], v[20:23]
	v_mfma_f32_16x16x32_bf16 v[16:19], v[166:169], v[198:201], v[16:19]
	v_mfma_f32_16x16x32_bf16 v[12:15], v[166:169], v[202:205], v[12:15]
	v_mfma_f32_16x16x32_bf16 v[8:11], v[166:169], v[206:209], v[8:11]
	v_mfma_f32_16x16x32_bf16 v[4:7], v[170:173], v[194:197], v[4:7]
	v_mfma_f32_16x16x32_bf16 v[0:3], v[170:173], v[198:201], v[0:3]
	v_mfma_f32_16x16x32_bf16 v[40:43], v[170:173], v[202:205], v[40:43]
	v_mfma_f32_16x16x32_bf16 v[36:39], v[170:173], v[206:209], v[36:39]
	ds_read_b128 v[158:161], v212 offset:8192
	ds_read_b128 v[162:165], v212 offset:10240
	ds_read_b128 v[166:169], v212 offset:12288
	ds_read_b128 v[170:173], v212 offset:14336
	s_waitcnt lgkmcnt(4)
	v_mfma_f32_16x16x32_bf16 v[124:127], v[142:145], v[174:177], v[124:127]
	v_mfma_f32_16x16x32_bf16 v[120:123], v[142:145], v[182:185], v[120:123]
	v_mfma_f32_16x16x32_bf16 v[116:119], v[142:145], v[186:189], v[116:119]
	v_mfma_f32_16x16x32_bf16 v[112:115], v[142:145], v[190:193], v[112:115]
	v_mfma_f32_16x16x32_bf16 v[108:111], v[146:149], v[174:177], v[108:111]
	v_mfma_f32_16x16x32_bf16 v[104:107], v[146:149], v[182:185], v[104:107]
	v_mfma_f32_16x16x32_bf16 v[100:103], v[146:149], v[186:189], v[100:103]
	v_mfma_f32_16x16x32_bf16 v[96:99], v[146:149], v[190:193], v[96:99]
	v_mfma_f32_16x16x32_bf16 v[92:95], v[150:153], v[174:177], v[92:95]
	v_mfma_f32_16x16x32_bf16 v[88:91], v[150:153], v[182:185], v[88:91]
	v_mfma_f32_16x16x32_bf16 v[84:87], v[150:153], v[186:189], v[84:87]
	v_mfma_f32_16x16x32_bf16 v[80:83], v[150:153], v[190:193], v[80:83]
	v_mfma_f32_16x16x32_bf16 v[76:79], v[154:157], v[174:177], v[76:79]
	v_mfma_f32_16x16x32_bf16 v[72:75], v[154:157], v[182:185], v[72:75]
	v_mfma_f32_16x16x32_bf16 v[68:71], v[154:157], v[186:189], v[68:71]
	v_mfma_f32_16x16x32_bf16 v[64:67], v[154:157], v[190:193], v[64:67]
	ds_read_b128 v[142:145], v213
	ds_read_b128 v[146:149], v213 offset:2048
	ds_read_b128 v[150:153], v213 offset:4096
	ds_read_b128 v[154:157], v213 offset:6144
	ds_read_b128 v[194:197], v215 offset:32768
	ds_read_b128 v[198:201], v215 offset:34816
	ds_read_b128 v[202:205], v215 offset:36864
	ds_read_b128 v[206:209], v215 offset:38912
	s_waitcnt lgkmcnt(8)
	v_mfma_f32_16x16x32_bf16 v[60:63], v[158:161], v[174:177], v[60:63]
	v_mfma_f32_16x16x32_bf16 v[56:59], v[158:161], v[182:185], v[56:59]
	v_mfma_f32_16x16x32_bf16 v[52:55], v[158:161], v[186:189], v[52:55]
	v_mfma_f32_16x16x32_bf16 v[48:51], v[158:161], v[190:193], v[48:51]
	v_mfma_f32_16x16x32_bf16 v[44:47], v[162:165], v[174:177], v[44:47]
	v_mfma_f32_16x16x32_bf16 v[32:35], v[162:165], v[182:185], v[32:35]
	v_mfma_f32_16x16x32_bf16 v[28:31], v[162:165], v[186:189], v[28:31]
	v_mfma_f32_16x16x32_bf16 v[24:27], v[162:165], v[190:193], v[24:27]
	v_mfma_f32_16x16x32_bf16 v[20:23], v[166:169], v[174:177], v[20:23]
	v_mfma_f32_16x16x32_bf16 v[16:19], v[166:169], v[182:185], v[16:19]
	v_mfma_f32_16x16x32_bf16 v[12:15], v[166:169], v[186:189], v[12:15]
	v_mfma_f32_16x16x32_bf16 v[8:11], v[166:169], v[190:193], v[8:11]
	v_mfma_f32_16x16x32_bf16 v[4:7], v[170:173], v[174:177], v[4:7]
	v_mfma_f32_16x16x32_bf16 v[0:3], v[170:173], v[182:185], v[0:3]
	v_mfma_f32_16x16x32_bf16 v[40:43], v[170:173], v[186:189], v[40:43]
	v_mfma_f32_16x16x32_bf16 v[36:39], v[170:173], v[190:193], v[36:39]
	ds_read_b128 v[158:161], v213 offset:8192
	ds_read_b128 v[162:165], v213 offset:10240
	ds_read_b128 v[166:169], v213 offset:12288
	ds_read_b128 v[170:173], v213 offset:14336
	s_waitcnt lgkmcnt(4)
	v_mfma_f32_16x16x32_bf16 v[124:127], v[142:145], v[194:197], v[124:127]
	v_mfma_f32_16x16x32_bf16 v[120:123], v[142:145], v[198:201], v[120:123]
	v_mfma_f32_16x16x32_bf16 v[116:119], v[142:145], v[202:205], v[116:119]
	v_mfma_f32_16x16x32_bf16 v[112:115], v[142:145], v[206:209], v[112:115]
	v_mfma_f32_16x16x32_bf16 v[108:111], v[146:149], v[194:197], v[108:111]
	v_mfma_f32_16x16x32_bf16 v[104:107], v[146:149], v[198:201], v[104:107]
	v_mfma_f32_16x16x32_bf16 v[100:103], v[146:149], v[202:205], v[100:103]
	v_mfma_f32_16x16x32_bf16 v[96:99], v[146:149], v[206:209], v[96:99]
	v_mfma_f32_16x16x32_bf16 v[92:95], v[150:153], v[194:197], v[92:95]
	v_mfma_f32_16x16x32_bf16 v[88:91], v[150:153], v[198:201], v[88:91]
	v_mfma_f32_16x16x32_bf16 v[84:87], v[150:153], v[202:205], v[84:87]
	v_mfma_f32_16x16x32_bf16 v[80:83], v[150:153], v[206:209], v[80:83]
	v_mfma_f32_16x16x32_bf16 v[76:79], v[154:157], v[194:197], v[76:79]
	v_mfma_f32_16x16x32_bf16 v[72:75], v[154:157], v[198:201], v[72:75]
	v_mfma_f32_16x16x32_bf16 v[68:71], v[154:157], v[202:205], v[68:71]
	v_mfma_f32_16x16x32_bf16 v[64:67], v[154:157], v[206:209], v[64:67]
	s_add_u32 s48, s48, 0x80
	s_addc_u32 s49, s49, 0
	s_add_i32 s47, s47, 1
	s_waitcnt lgkmcnt(0)
	s_waitcnt vmcnt(0)
	s_barrier
	v_mfma_f32_16x16x32_bf16 v[60:63], v[158:161], v[194:197], v[60:63]
	v_mfma_f32_16x16x32_bf16 v[56:59], v[158:161], v[198:201], v[56:59]
	v_mfma_f32_16x16x32_bf16 v[52:55], v[158:161], v[202:205], v[52:55]
	v_mfma_f32_16x16x32_bf16 v[48:51], v[158:161], v[206:209], v[48:51]
	v_mfma_f32_16x16x32_bf16 v[44:47], v[162:165], v[194:197], v[44:47]
	v_mfma_f32_16x16x32_bf16 v[32:35], v[162:165], v[198:201], v[32:35]
	v_mfma_f32_16x16x32_bf16 v[28:31], v[162:165], v[202:205], v[28:31]
	v_mfma_f32_16x16x32_bf16 v[24:27], v[162:165], v[206:209], v[24:27]
	v_mfma_f32_16x16x32_bf16 v[20:23], v[166:169], v[194:197], v[20:23]
	v_mfma_f32_16x16x32_bf16 v[16:19], v[166:169], v[198:201], v[16:19]
	v_mfma_f32_16x16x32_bf16 v[12:15], v[166:169], v[202:205], v[12:15]
	v_mfma_f32_16x16x32_bf16 v[8:11], v[166:169], v[206:209], v[8:11]
	v_mfma_f32_16x16x32_bf16 v[4:7], v[170:173], v[194:197], v[4:7]
	v_mfma_f32_16x16x32_bf16 v[0:3], v[170:173], v[198:201], v[0:3]
	v_mfma_f32_16x16x32_bf16 v[40:43], v[170:173], v[202:205], v[40:43]
	v_mfma_f32_16x16x32_bf16 v[36:39], v[170:173], v[206:209], v[36:39]
	s_nop 7
	s_nop 7
	s_sub_u32 s48, s48, s34
	s_subb_u32 s49, s49, s35
	s_mov_b32 s61, 0x100000
	s_mov_b32 s62, 0x100000
	s_mov_b64 s[50:51], 0
	s_mov_b64 vcc, exec
	s_branch .LBB0_745

.Lg8_top:
	s_waitcnt lgkmcnt(0)
	s_waitcnt vmcnt(0)
	s_barrier
	v_mfma_f32_16x16x32_bf16 v[60:63], v[170:173], v[206:209], v[60:63]
	v_mfma_f32_16x16x32_bf16 v[56:59], v[170:173], v[210:213], v[56:59]
	s_xor_b32 s59, s59, 0x10000
	s_mov_b32 m0, s59
	s_add_u32 s62, s60, s22
	s_addc_u32 s63, s61, s23
	global_load_lds_dwordx4 v178, s[62:63]
	s_add_u32 m0, s59, 0x2000
	s_add_u32 s62, s60, s36
	s_addc_u32 s63, s61, s37
	global_load_lds_dwordx4 v178, s[62:63]
	ds_read_b128 v[154:157], v180
	ds_read_b128 v[158:161], v180 offset:2048
	ds_read_b128 v[162:165], v180 offset:4096
	ds_read_b128 v[166:169], v180 offset:6144
	ds_read_b128 v[190:193], v223 offset:32768
	ds_read_b128 v[194:197], v223 offset:34816
	ds_read_b128 v[198:201], v223 offset:36864
	ds_read_b128 v[202:205], v223 offset:38912
	v_mfma_f32_16x16x32_bf16 v[52:55], v[170:173], v[214:217], v[52:55]
	v_mfma_f32_16x16x32_bf16 v[44:47], v[170:173], v[218:221], v[44:47]
	s_add_u32 m0, s59, 0x4000
	s_add_u32 s62, s60, s38
	s_addc_u32 s63, s61, s39
	global_load_lds_dwordx4 v178, s[62:63]
	v_mfma_f32_16x16x32_bf16 v[36:39], v[174:177], v[206:209], v[36:39]
	v_mfma_f32_16x16x32_bf16 v[32:35], v[174:177], v[210:213], v[32:35]
	s_add_u32 m0, s59, 0x6000
	s_add_u32 s62, s60, s40
	s_addc_u32 s63, s61, s41
	global_load_lds_dwordx4 v178, s[62:63]
	v_mfma_f32_16x16x32_bf16 v[28:31], v[174:177], v[214:217], v[28:31]
	v_mfma_f32_16x16x32_bf16 v[24:27], v[174:177], v[218:221], v[24:27]
	s_add_u32 m0, s59, 0x8000
	s_add_u32 s62, s60, s42
	s_addc_u32 s63, s61, s43
	global_load_lds_dwordx4 v179, s[62:63]
	v_mfma_f32_16x16x32_bf16 v[20:23], v[182:185], v[206:209], v[20:23]
	v_mfma_f32_16x16x32_bf16 v[16:19], v[182:185], v[210:213], v[16:19]
	s_add_u32 m0, s59, 0xa000
	s_add_u32 s62, s60, s44
	s_addc_u32 s63, s61, s45
	global_load_lds_dwordx4 v179, s[62:63]
	v_mfma_f32_16x16x32_bf16 v[12:15], v[182:185], v[214:217], v[12:15]
	v_mfma_f32_16x16x32_bf16 v[8:11], v[182:185], v[218:221], v[8:11]
	s_add_u32 m0, s59, 0xc000
	s_add_u32 s62, s60, s46
	s_addc_u32 s63, s61, s47
	global_load_lds_dwordx4 v179, s[62:63]
	v_mfma_f32_16x16x32_bf16 v[4:7], v[186:189], v[206:209], v[4:7]
	v_mfma_f32_16x16x32_bf16 v[0:3], v[186:189], v[210:213], v[0:3]
	s_add_u32 m0, s59, 0xe000
	s_add_u32 s62, s60, s48
	s_addc_u32 s63, s61, s49
	global_load_lds_dwordx4 v179, s[62:63]
	v_mfma_f32_16x16x32_bf16 v[48:51], v[186:189], v[214:217], v[48:51]
	v_mfma_f32_16x16x32_bf16 v[40:43], v[186:189], v[218:221], v[40:43]
.Lg8_entry:
	ds_read_b128 v[170:173], v180 offset:8192
	ds_read_b128 v[174:177], v180 offset:10240
	ds_read_b128 v[182:185], v180 offset:12288
	ds_read_b128 v[186:189], v180 offset:14336
	s_waitcnt lgkmcnt(4)
	v_mfma_f32_16x16x32_bf16 v[124:127], v[154:157], v[190:193], v[124:127]
	v_mfma_f32_16x16x32_bf16 v[120:123], v[154:157], v[194:197], v[120:123]
	v_mfma_f32_16x16x32_bf16 v[116:119], v[154:157], v[198:201], v[116:119]
	v_mfma_f32_16x16x32_bf16 v[112:115], v[154:157], v[202:205], v[112:115]
	v_mfma_f32_16x16x32_bf16 v[108:111], v[158:161], v[190:193], v[108:111]
	v_mfma_f32_16x16x32_bf16 v[104:107], v[158:161], v[194:197], v[104:107]
	v_mfma_f32_16x16x32_bf16 v[100:103], v[158:161], v[198:201], v[100:103]
	v_mfma_f32_16x16x32_bf16 v[96:99], v[158:161], v[202:205], v[96:99]
	v_mfma_f32_16x16x32_bf16 v[92:95], v[162:165], v[190:193], v[92:95]
	v_mfma_f32_16x16x32_bf16 v[88:91], v[162:165], v[194:197], v[88:91]
	v_mfma_f32_16x16x32_bf16 v[84:87], v[162:165], v[198:201], v[84:87]
	v_mfma_f32_16x16x32_bf16 v[80:83], v[162:165], v[202:205], v[80:83]
	v_mfma_f32_16x16x32_bf16 v[76:79], v[166:169], v[190:193], v[76:79]
	v_mfma_f32_16x16x32_bf16 v[72:75], v[166:169], v[194:197], v[72:75]
	v_mfma_f32_16x16x32_bf16 v[68:71], v[166:169], v[198:201], v[68:71]
	v_mfma_f32_16x16x32_bf16 v[64:67], v[166:169], v[202:205], v[64:67]
	ds_read_b128 v[154:157], v222
	ds_read_b128 v[158:161], v222 offset:2048
	ds_read_b128 v[162:165], v222 offset:4096
	ds_read_b128 v[166:169], v222 offset:6144
	ds_read_b128 v[206:209], v224 offset:32768
	ds_read_b128 v[210:213], v224 offset:34816
	ds_read_b128 v[214:217], v224 offset:36864
	ds_read_b128 v[218:221], v224 offset:38912
	s_waitcnt lgkmcnt(8)
	v_mfma_f32_16x16x32_bf16 v[60:63], v[170:173], v[190:193], v[60:63]
	v_mfma_f32_16x16x32_bf16 v[56:59], v[170:173], v[194:197], v[56:59]
	v_mfma_f32_16x16x32_bf16 v[52:55], v[170:173], v[198:201], v[52:55]
	v_mfma_f32_16x16x32_bf16 v[44:47], v[170:173], v[202:205], v[44:47]
	v_mfma_f32_16x16x32_bf16 v[36:39], v[174:177], v[190:193], v[36:39]
	v_mfma_f32_16x16x32_bf16 v[32:35], v[174:177], v[194:197], v[32:35]
	v_mfma_f32_16x16x32_bf16 v[28:31], v[174:177], v[198:201], v[28:31]
	v_mfma_f32_16x16x32_bf16 v[24:27], v[174:177], v[202:205], v[24:27]
	v_mfma_f32_16x16x32_bf16 v[20:23], v[182:185], v[190:193], v[20:23]
	v_mfma_f32_16x16x32_bf16 v[16:19], v[182:185], v[194:197], v[16:19]
	v_mfma_f32_16x16x32_bf16 v[12:15], v[182:185], v[198:201], v[12:15]
	v_mfma_f32_16x16x32_bf16 v[8:11], v[182:185], v[202:205], v[8:11]
	v_mfma_f32_16x16x32_bf16 v[4:7], v[186:189], v[190:193], v[4:7]
	v_mfma_f32_16x16x32_bf16 v[0:3], v[186:189], v[194:197], v[0:3]
	v_mfma_f32_16x16x32_bf16 v[48:51], v[186:189], v[198:201], v[48:51]
	v_mfma_f32_16x16x32_bf16 v[40:43], v[186:189], v[202:205], v[40:43]
	ds_read_b128 v[170:173], v222 offset:8192
	ds_read_b128 v[174:177], v222 offset:10240
	ds_read_b128 v[182:185], v222 offset:12288
	ds_read_b128 v[186:189], v222 offset:14336
	s_waitcnt lgkmcnt(4)
	v_mfma_f32_16x16x32_bf16 v[124:127], v[154:157], v[206:209], v[124:127]
	v_mfma_f32_16x16x32_bf16 v[120:123], v[154:157], v[210:213], v[120:123]
	v_mfma_f32_16x16x32_bf16 v[116:119], v[154:157], v[214:217], v[116:119]
	v_mfma_f32_16x16x32_bf16 v[112:115], v[154:157], v[218:221], v[112:115]
	v_mfma_f32_16x16x32_bf16 v[108:111], v[158:161], v[206:209], v[108:111]
	v_mfma_f32_16x16x32_bf16 v[104:107], v[158:161], v[210:213], v[104:107]
	v_mfma_f32_16x16x32_bf16 v[100:103], v[158:161], v[214:217], v[100:103]
	v_mfma_f32_16x16x32_bf16 v[96:99], v[158:161], v[218:221], v[96:99]
	v_mfma_f32_16x16x32_bf16 v[92:95], v[162:165], v[206:209], v[92:95]
	v_mfma_f32_16x16x32_bf16 v[88:91], v[162:165], v[210:213], v[88:91]
	v_mfma_f32_16x16x32_bf16 v[84:87], v[162:165], v[214:217], v[84:87]
	v_mfma_f32_16x16x32_bf16 v[80:83], v[162:165], v[218:221], v[80:83]
	v_mfma_f32_16x16x32_bf16 v[76:79], v[166:169], v[206:209], v[76:79]
	v_mfma_f32_16x16x32_bf16 v[72:75], v[166:169], v[210:213], v[72:75]
	v_mfma_f32_16x16x32_bf16 v[68:71], v[166:169], v[214:217], v[68:71]
	v_mfma_f32_16x16x32_bf16 v[64:67], v[166:169], v[218:221], v[64:67]
	s_add_u32 s60, s60, 0x80
	s_addc_u32 s61, s61, 0
	s_add_i32 s57, s57, 1
	s_cmp_lt_u32 s57, 15
	s_cbranch_scc0 .Lg8_last
	s_waitcnt lgkmcnt(0)
	s_waitcnt vmcnt(0)
	s_barrier
	v_mfma_f32_16x16x32_bf16 v[60:63], v[170:173], v[206:209], v[60:63]
	v_mfma_f32_16x16x32_bf16 v[56:59], v[170:173], v[210:213], v[56:59]
	s_xor_b32 s59, s59, 0x10000
	s_mov_b32 m0, s59
	s_add_u32 s62, s60, s22
	s_addc_u32 s63, s61, s23
	global_load_lds_dwordx4 v178, s[62:63]
	s_add_u32 m0, s59, 0x2000
	s_add_u32 s62, s60, s36
	s_addc_u32 s63, s61, s37
	global_load_lds_dwordx4 v178, s[62:63]
	ds_read_b128 v[154:157], v225
	ds_read_b128 v[158:161], v225 offset:2048
	ds_read_b128 v[162:165], v225 offset:4096
	ds_read_b128 v[166:169], v225 offset:6144
	ds_read_b128 v[190:193], v227 offset:32768
	ds_read_b128 v[194:197], v227 offset:34816
	ds_read_b128 v[198:201], v227 offset:36864
	ds_read_b128 v[202:205], v227 offset:38912
	v_mfma_f32_16x16x32_bf16 v[52:55], v[170:173], v[214:217], v[52:55]
	v_mfma_f32_16x16x32_bf16 v[44:47], v[170:173], v[218:221], v[44:47]
	s_add_u32 m0, s59, 0x4000
	s_add_u32 s62, s60, s38
	s_addc_u32 s63, s61, s39
	global_load_lds_dwordx4 v178, s[62:63]
	v_mfma_f32_16x16x32_bf16 v[36:39], v[174:177], v[206:209], v[36:39]
	v_mfma_f32_16x16x32_bf16 v[32:35], v[174:177], v[210:213], v[32:35]
	s_add_u32 m0, s59, 0x6000
	s_add_u32 s62, s60, s40
	s_addc_u32 s63, s61, s41
	global_load_lds_dwordx4 v178, s[62:63]
	v_mfma_f32_16x16x32_bf16 v[28:31], v[174:177], v[214:217], v[28:31]
	v_mfma_f32_16x16x32_bf16 v[24:27], v[174:177], v[218:221], v[24:27]
	s_add_u32 m0, s59, 0x8000
	s_add_u32 s62, s60, s42
	s_addc_u32 s63, s61, s43
	global_load_lds_dwordx4 v179, s[62:63]
	v_mfma_f32_16x16x32_bf16 v[20:23], v[182:185], v[206:209], v[20:23]
	v_mfma_f32_16x16x32_bf16 v[16:19], v[182:185], v[210:213], v[16:19]
	s_add_u32 m0, s59, 0xa000
	s_add_u32 s62, s60, s44
	s_addc_u32 s63, s61, s45
	global_load_lds_dwordx4 v179, s[62:63]
	v_mfma_f32_16x16x32_bf16 v[12:15], v[182:185], v[214:217], v[12:15]
	v_mfma_f32_16x16x32_bf16 v[8:11], v[182:185], v[218:221], v[8:11]
	s_add_u32 m0, s59, 0xc000
	s_add_u32 s62, s60, s46
	s_addc_u32 s63, s61, s47
	global_load_lds_dwordx4 v179, s[62:63]
	v_mfma_f32_16x16x32_bf16 v[4:7], v[186:189], v[206:209], v[4:7]
	v_mfma_f32_16x16x32_bf16 v[0:3], v[186:189], v[210:213], v[0:3]
	s_add_u32 m0, s59, 0xe000
	s_add_u32 s62, s60, s48
	s_addc_u32 s63, s61, s49
	global_load_lds_dwordx4 v179, s[62:63]
	v_mfma_f32_16x16x32_bf16 v[48:51], v[186:189], v[214:217], v[48:51]
	v_mfma_f32_16x16x32_bf16 v[40:43], v[186:189], v[218:221], v[40:43]
	ds_read_b128 v[170:173], v225 offset:8192
	ds_read_b128 v[174:177], v225 offset:10240
	ds_read_b128 v[182:185], v225 offset:12288
	ds_read_b128 v[186:189], v225 offset:14336
	s_waitcnt lgkmcnt(4)
	v_mfma_f32_16x16x32_bf16 v[124:127], v[154:157], v[190:193], v[124:127]
	v_mfma_f32_16x16x32_bf16 v[120:123], v[154:157], v[194:197], v[120:123]
	v_mfma_f32_16x16x32_bf16 v[116:119], v[154:157], v[198:201], v[116:119]
	v_mfma_f32_16x16x32_bf16 v[112:115], v[154:157], v[202:205], v[112:115]
	v_mfma_f32_16x16x32_bf16 v[108:111], v[158:161], v[190:193], v[108:111]
	v_mfma_f32_16x16x32_bf16 v[104:107], v[158:161], v[194:197], v[104:107]
	v_mfma_f32_16x16x32_bf16 v[100:103], v[158:161], v[198:201], v[100:103]
	v_mfma_f32_16x16x32_bf16 v[96:99], v[158:161], v[202:205], v[96:99]
	v_mfma_f32_16x16x32_bf16 v[92:95], v[162:165], v[190:193], v[92:95]
	v_mfma_f32_16x16x32_bf16 v[88:91], v[162:165], v[194:197], v[88:91]
	v_mfma_f32_16x16x32_bf16 v[84:87], v[162:165], v[198:201], v[84:87]
	v_mfma_f32_16x16x32_bf16 v[80:83], v[162:165], v[202:205], v[80:83]
	v_mfma_f32_16x16x32_bf16 v[76:79], v[166:169], v[190:193], v[76:79]
	v_mfma_f32_16x16x32_bf16 v[72:75], v[166:169], v[194:197], v[72:75]
	v_mfma_f32_16x16x32_bf16 v[68:71], v[166:169], v[198:201], v[68:71]
	v_mfma_f32_16x16x32_bf16 v[64:67], v[166:169], v[202:205], v[64:67]
	ds_read_b128 v[154:157], v226
	ds_read_b128 v[158:161], v226 offset:2048
	ds_read_b128 v[162:165], v226 offset:4096
	ds_read_b128 v[166:169], v226 offset:6144
	ds_read_b128 v[206:209], v228 offset:32768
	ds_read_b128 v[210:213], v228 offset:34816
	ds_read_b128 v[214:217], v228 offset:36864
	ds_read_b128 v[218:221], v228 offset:38912
	s_waitcnt lgkmcnt(8)
	v_mfma_f32_16x16x32_bf16 v[60:63], v[170:173], v[190:193], v[60:63]
	v_mfma_f32_16x16x32_bf16 v[56:59], v[170:173], v[194:197], v[56:59]
	v_mfma_f32_16x16x32_bf16 v[52:55], v[170:173], v[198:201], v[52:55]
	v_mfma_f32_16x16x32_bf16 v[44:47], v[170:173], v[202:205], v[44:47]
	v_mfma_f32_16x16x32_bf16 v[36:39], v[174:177], v[190:193], v[36:39]
	v_mfma_f32_16x16x32_bf16 v[32:35], v[174:177], v[194:197], v[32:35]
	v_mfma_f32_16x16x32_bf16 v[28:31], v[174:177], v[198:201], v[28:31]
	v_mfma_f32_16x16x32_bf16 v[24:27], v[174:177], v[202:205], v[24:27]
	v_mfma_f32_16x16x32_bf16 v[20:23], v[182:185], v[190:193], v[20:23]
	v_mfma_f32_16x16x32_bf16 v[16:19], v[182:185], v[194:197], v[16:19]
	v_mfma_f32_16x16x32_bf16 v[12:15], v[182:185], v[198:201], v[12:15]
	v_mfma_f32_16x16x32_bf16 v[8:11], v[182:185], v[202:205], v[8:11]
	v_mfma_f32_16x16x32_bf16 v[4:7], v[186:189], v[190:193], v[4:7]
	v_mfma_f32_16x16x32_bf16 v[0:3], v[186:189], v[194:197], v[0:3]
	v_mfma_f32_16x16x32_bf16 v[48:51], v[186:189], v[198:201], v[48:51]
	v_mfma_f32_16x16x32_bf16 v[40:43], v[186:189], v[202:205], v[40:43]
	ds_read_b128 v[170:173], v226 offset:8192
	ds_read_b128 v[174:177], v226 offset:10240
	ds_read_b128 v[182:185], v226 offset:12288
	ds_read_b128 v[186:189], v226 offset:14336
	s_waitcnt lgkmcnt(4)
	v_mfma_f32_16x16x32_bf16 v[124:127], v[154:157], v[206:209], v[124:127]
	v_mfma_f32_16x16x32_bf16 v[120:123], v[154:157], v[210:213], v[120:123]
	v_mfma_f32_16x16x32_bf16 v[116:119], v[154:157], v[214:217], v[116:119]
	v_mfma_f32_16x16x32_bf16 v[112:115], v[154:157], v[218:221], v[112:115]
	v_mfma_f32_16x16x32_bf16 v[108:111], v[158:161], v[206:209], v[108:111]
	v_mfma_f32_16x16x32_bf16 v[104:107], v[158:161], v[210:213], v[104:107]
	v_mfma_f32_16x16x32_bf16 v[100:103], v[158:161], v[214:217], v[100:103]
	v_mfma_f32_16x16x32_bf16 v[96:99], v[158:161], v[218:221], v[96:99]
	v_mfma_f32_16x16x32_bf16 v[92:95], v[162:165], v[206:209], v[92:95]
	v_mfma_f32_16x16x32_bf16 v[88:91], v[162:165], v[210:213], v[88:91]
	v_mfma_f32_16x16x32_bf16 v[84:87], v[162:165], v[214:217], v[84:87]
	v_mfma_f32_16x16x32_bf16 v[80:83], v[162:165], v[218:221], v[80:83]
	v_mfma_f32_16x16x32_bf16 v[76:79], v[166:169], v[206:209], v[76:79]
	v_mfma_f32_16x16x32_bf16 v[72:75], v[166:169], v[210:213], v[72:75]
	v_mfma_f32_16x16x32_bf16 v[68:71], v[166:169], v[214:217], v[68:71]
	v_mfma_f32_16x16x32_bf16 v[64:67], v[166:169], v[218:221], v[64:67]
	s_add_u32 s60, s60, 0x80
	s_addc_u32 s61, s61, 0
	s_add_i32 s57, s57, 1
	s_branch .Lg8_top
.Lg8_last:
	s_waitcnt lgkmcnt(0)
	s_waitcnt vmcnt(0)
	s_barrier
	v_mfma_f32_16x16x32_bf16 v[60:63], v[170:173], v[206:209], v[60:63]
	v_mfma_f32_16x16x32_bf16 v[56:59], v[170:173], v[210:213], v[56:59]
	s_xor_b32 s59, s59, 0x10000
	ds_read_b128 v[154:157], v225
	ds_read_b128 v[158:161], v225 offset:2048
	ds_read_b128 v[162:165], v225 offset:4096
	ds_read_b128 v[166:169], v225 offset:6144
	ds_read_b128 v[190:193], v227 offset:32768
	ds_read_b128 v[194:197], v227 offset:34816
	ds_read_b128 v[198:201], v227 offset:36864
	ds_read_b128 v[202:205], v227 offset:38912
	v_mfma_f32_16x16x32_bf16 v[52:55], v[170:173], v[214:217], v[52:55]
	v_mfma_f32_16x16x32_bf16 v[44:47], v[170:173], v[218:221], v[44:47]
	v_mfma_f32_16x16x32_bf16 v[36:39], v[174:177], v[206:209], v[36:39]
	v_mfma_f32_16x16x32_bf16 v[32:35], v[174:177], v[210:213], v[32:35]
	v_mfma_f32_16x16x32_bf16 v[28:31], v[174:177], v[214:217], v[28:31]
	v_mfma_f32_16x16x32_bf16 v[24:27], v[174:177], v[218:221], v[24:27]
	v_mfma_f32_16x16x32_bf16 v[20:23], v[182:185], v[206:209], v[20:23]
	v_mfma_f32_16x16x32_bf16 v[16:19], v[182:185], v[210:213], v[16:19]
	v_mfma_f32_16x16x32_bf16 v[12:15], v[182:185], v[214:217], v[12:15]
	v_mfma_f32_16x16x32_bf16 v[8:11], v[182:185], v[218:221], v[8:11]
	v_mfma_f32_16x16x32_bf16 v[4:7], v[186:189], v[206:209], v[4:7]
	v_mfma_f32_16x16x32_bf16 v[0:3], v[186:189], v[210:213], v[0:3]
	v_mfma_f32_16x16x32_bf16 v[48:51], v[186:189], v[214:217], v[48:51]
	v_mfma_f32_16x16x32_bf16 v[40:43], v[186:189], v[218:221], v[40:43]
	ds_read_b128 v[170:173], v225 offset:8192
	ds_read_b128 v[174:177], v225 offset:10240
	ds_read_b128 v[182:185], v225 offset:12288
	ds_read_b128 v[186:189], v225 offset:14336
	s_waitcnt lgkmcnt(4)
	v_mfma_f32_16x16x32_bf16 v[124:127], v[154:157], v[190:193], v[124:127]
	v_mfma_f32_16x16x32_bf16 v[120:123], v[154:157], v[194:197], v[120:123]
	v_mfma_f32_16x16x32_bf16 v[116:119], v[154:157], v[198:201], v[116:119]
	v_mfma_f32_16x16x32_bf16 v[112:115], v[154:157], v[202:205], v[112:115]
	v_mfma_f32_16x16x32_bf16 v[108:111], v[158:161], v[190:193], v[108:111]
	v_mfma_f32_16x16x32_bf16 v[104:107], v[158:161], v[194:197], v[104:107]
	v_mfma_f32_16x16x32_bf16 v[100:103], v[158:161], v[198:201], v[100:103]
	v_mfma_f32_16x16x32_bf16 v[96:99], v[158:161], v[202:205], v[96:99]
	v_mfma_f32_16x16x32_bf16 v[92:95], v[162:165], v[190:193], v[92:95]
	v_mfma_f32_16x16x32_bf16 v[88:91], v[162:165], v[194:197], v[88:91]
	v_mfma_f32_16x16x32_bf16 v[84:87], v[162:165], v[198:201], v[84:87]
	v_mfma_f32_16x16x32_bf16 v[80:83], v[162:165], v[202:205], v[80:83]
	v_mfma_f32_16x16x32_bf16 v[76:79], v[166:169], v[190:193], v[76:79]
	v_mfma_f32_16x16x32_bf16 v[72:75], v[166:169], v[194:197], v[72:75]
	v_mfma_f32_16x16x32_bf16 v[68:71], v[166:169], v[198:201], v[68:71]
	v_mfma_f32_16x16x32_bf16 v[64:67], v[166:169], v[202:205], v[64:67]
	ds_read_b128 v[154:157], v226
	ds_read_b128 v[158:161], v226 offset:2048
	ds_read_b128 v[162:165], v226 offset:4096
	ds_read_b128 v[166:169], v226 offset:6144
	ds_read_b128 v[206:209], v228 offset:32768
	ds_read_b128 v[210:213], v228 offset:34816
	ds_read_b128 v[214:217], v228 offset:36864
	ds_read_b128 v[218:221], v228 offset:38912
	s_waitcnt lgkmcnt(8)
	v_mfma_f32_16x16x32_bf16 v[60:63], v[170:173], v[190:193], v[60:63]
	v_mfma_f32_16x16x32_bf16 v[56:59], v[170:173], v[194:197], v[56:59]
	v_mfma_f32_16x16x32_bf16 v[52:55], v[170:173], v[198:201], v[52:55]
	v_mfma_f32_16x16x32_bf16 v[44:47], v[170:173], v[202:205], v[44:47]
	v_mfma_f32_16x16x32_bf16 v[36:39], v[174:177], v[190:193], v[36:39]
	v_mfma_f32_16x16x32_bf16 v[32:35], v[174:177], v[194:197], v[32:35]
	v_mfma_f32_16x16x32_bf16 v[28:31], v[174:177], v[198:201], v[28:31]
	v_mfma_f32_16x16x32_bf16 v[24:27], v[174:177], v[202:205], v[24:27]
	v_mfma_f32_16x16x32_bf16 v[20:23], v[182:185], v[190:193], v[20:23]
	v_mfma_f32_16x16x32_bf16 v[16:19], v[182:185], v[194:197], v[16:19]
	v_mfma_f32_16x16x32_bf16 v[12:15], v[182:185], v[198:201], v[12:15]
	v_mfma_f32_16x16x32_bf16 v[8:11], v[182:185], v[202:205], v[8:11]
	v_mfma_f32_16x16x32_bf16 v[4:7], v[186:189], v[190:193], v[4:7]
	v_mfma_f32_16x16x32_bf16 v[0:3], v[186:189], v[194:197], v[0:3]
	v_mfma_f32_16x16x32_bf16 v[48:51], v[186:189], v[198:201], v[48:51]
	v_mfma_f32_16x16x32_bf16 v[40:43], v[186:189], v[202:205], v[40:43]
	ds_read_b128 v[170:173], v226 offset:8192
	ds_read_b128 v[174:177], v226 offset:10240
	ds_read_b128 v[182:185], v226 offset:12288
	ds_read_b128 v[186:189], v226 offset:14336
	s_waitcnt lgkmcnt(4)
	v_mfma_f32_16x16x32_bf16 v[124:127], v[154:157], v[206:209], v[124:127]
	v_mfma_f32_16x16x32_bf16 v[120:123], v[154:157], v[210:213], v[120:123]
	v_mfma_f32_16x16x32_bf16 v[116:119], v[154:157], v[214:217], v[116:119]
	v_mfma_f32_16x16x32_bf16 v[112:115], v[154:157], v[218:221], v[112:115]
	v_mfma_f32_16x16x32_bf16 v[108:111], v[158:161], v[206:209], v[108:111]
	v_mfma_f32_16x16x32_bf16 v[104:107], v[158:161], v[210:213], v[104:107]
	v_mfma_f32_16x16x32_bf16 v[100:103], v[158:161], v[214:217], v[100:103]
	v_mfma_f32_16x16x32_bf16 v[96:99], v[158:161], v[218:221], v[96:99]
	v_mfma_f32_16x16x32_bf16 v[92:95], v[162:165], v[206:209], v[92:95]
	v_mfma_f32_16x16x32_bf16 v[88:91], v[162:165], v[210:213], v[88:91]
	v_mfma_f32_16x16x32_bf16 v[84:87], v[162:165], v[214:217], v[84:87]
	v_mfma_f32_16x16x32_bf16 v[80:83], v[162:165], v[218:221], v[80:83]
	v_mfma_f32_16x16x32_bf16 v[76:79], v[166:169], v[206:209], v[76:79]
	v_mfma_f32_16x16x32_bf16 v[72:75], v[166:169], v[210:213], v[72:75]
	v_mfma_f32_16x16x32_bf16 v[68:71], v[166:169], v[214:217], v[68:71]
	v_mfma_f32_16x16x32_bf16 v[64:67], v[166:169], v[218:221], v[64:67]
	s_add_u32 s60, s60, 0x80
	s_addc_u32 s61, s61, 0
	s_add_i32 s57, s57, 1
	s_waitcnt lgkmcnt(0)
	s_waitcnt vmcnt(0)
	s_barrier
	v_mfma_f32_16x16x32_bf16 v[60:63], v[170:173], v[206:209], v[60:63]
	v_mfma_f32_16x16x32_bf16 v[56:59], v[170:173], v[210:213], v[56:59]
	v_mfma_f32_16x16x32_bf16 v[52:55], v[170:173], v[214:217], v[52:55]
	v_mfma_f32_16x16x32_bf16 v[44:47], v[170:173], v[218:221], v[44:47]
	v_mfma_f32_16x16x32_bf16 v[36:39], v[174:177], v[206:209], v[36:39]
	v_mfma_f32_16x16x32_bf16 v[32:35], v[174:177], v[210:213], v[32:35]
	v_mfma_f32_16x16x32_bf16 v[28:31], v[174:177], v[214:217], v[28:31]
	v_mfma_f32_16x16x32_bf16 v[24:27], v[174:177], v[218:221], v[24:27]
	v_mfma_f32_16x16x32_bf16 v[20:23], v[182:185], v[206:209], v[20:23]
	v_mfma_f32_16x16x32_bf16 v[16:19], v[182:185], v[210:213], v[16:19]
	v_mfma_f32_16x16x32_bf16 v[12:15], v[182:185], v[214:217], v[12:15]
	v_mfma_f32_16x16x32_bf16 v[8:11], v[182:185], v[218:221], v[8:11]
	v_mfma_f32_16x16x32_bf16 v[4:7], v[186:189], v[206:209], v[4:7]
	v_mfma_f32_16x16x32_bf16 v[0:3], v[186:189], v[210:213], v[0:3]
	v_mfma_f32_16x16x32_bf16 v[48:51], v[186:189], v[214:217], v[48:51]
	v_mfma_f32_16x16x32_bf16 v[40:43], v[186:189], v[218:221], v[40:43]
	s_nop 7
	s_nop 7
	s_sub_u32 s60, s60, s34
	s_subb_u32 s61, s61, s35
	s_mov_b32 s59, 0x80000
	s_mov_b32 s65, 0x80000
	s_mov_b64 s[62:63], 0
	s_mov_b64 vcc, exec
	s_branch .LBB0_939

.Lg9_top:
	s_waitcnt lgkmcnt(0)
	s_waitcnt vmcnt(0)
	s_barrier
	v_mfma_f32_16x16x32_bf16 v[60:63], v[158:161], v[194:197], v[60:63]
	v_mfma_f32_16x16x32_bf16 v[56:59], v[158:161], v[198:201], v[56:59]
	s_xor_b32 s59, s59, 0x10000
	s_mov_b32 m0, s59
	s_add_u32 s46, s44, s12
	s_addc_u32 s47, s45, s13
	global_load_lds_dwordx4 v178, s[46:47]
	s_add_u32 m0, s59, 0x2000
	s_add_u32 s46, s44, s14
	s_addc_u32 s47, s45, s15
	global_load_lds_dwordx4 v178, s[46:47]
	ds_read_b128 v[142:145], v141
	ds_read_b128 v[146:149], v141 offset:2048
	ds_read_b128 v[150:153], v141 offset:4096
	ds_read_b128 v[154:157], v141 offset:6144
	ds_read_b128 v[174:177], v210 offset:32768
	ds_read_b128 v[182:185], v210 offset:34816
	ds_read_b128 v[186:189], v210 offset:36864
	ds_read_b128 v[190:193], v210 offset:38912
	v_mfma_f32_16x16x32_bf16 v[52:55], v[158:161], v[202:205], v[52:55]
	v_mfma_f32_16x16x32_bf16 v[48:51], v[158:161], v[206:209], v[48:51]
	s_add_u32 m0, s59, 0x4000
	s_add_u32 s46, s44, s16
	s_addc_u32 s47, s45, s17
	global_load_lds_dwordx4 v178, s[46:47]
	v_mfma_f32_16x16x32_bf16 v[44:47], v[162:165], v[194:197], v[44:47]
	v_mfma_f32_16x16x32_bf16 v[32:35], v[162:165], v[198:201], v[32:35]
	s_add_u32 m0, s59, 0x6000
	s_add_u32 s46, s44, s18
	s_addc_u32 s47, s45, s19
	global_load_lds_dwordx4 v178, s[46:47]
	v_mfma_f32_16x16x32_bf16 v[28:31], v[162:165], v[202:205], v[28:31]
	v_mfma_f32_16x16x32_bf16 v[24:27], v[162:165], v[206:209], v[24:27]
	s_add_u32 m0, s59, 0x8000
	s_add_u32 s46, s44, s22
	s_addc_u32 s47, s45, s23
	global_load_lds_dwordx4 v179, s[46:47]
	v_mfma_f32_16x16x32_bf16 v[20:23], v[166:169], v[194:197], v[20:23]
	v_mfma_f32_16x16x32_bf16 v[16:19], v[166:169], v[198:201], v[16:19]
	s_add_u32 m0, s59, 0xa000
	s_add_u32 s46, s44, s36
	s_addc_u32 s47, s45, s37
	global_load_lds_dwordx4 v179, s[46:47]
	v_mfma_f32_16x16x32_bf16 v[12:15], v[166:169], v[202:205], v[12:15]
	v_mfma_f32_16x16x32_bf16 v[8:11], v[166:169], v[206:209], v[8:11]
	s_add_u32 m0, s59, 0xc000
	s_add_u32 s46, s44, s38
	s_addc_u32 s47, s45, s39
	global_load_lds_dwordx4 v179, s[46:47]
	v_mfma_f32_16x16x32_bf16 v[4:7], v[170:173], v[194:197], v[4:7]
	v_mfma_f32_16x16x32_bf16 v[0:3], v[170:173], v[198:201], v[0:3]
	s_add_u32 m0, s59, 0xe000
	s_add_u32 s46, s44, s40
	s_addc_u32 s47, s45, s41
	global_load_lds_dwordx4 v179, s[46:47]
	v_mfma_f32_16x16x32_bf16 v[40:43], v[170:173], v[202:205], v[40:43]
	v_mfma_f32_16x16x32_bf16 v[36:39], v[170:173], v[206:209], v[36:39]
.Lg9_entry:
	ds_read_b128 v[158:161], v141 offset:8192
	ds_read_b128 v[162:165], v141 offset:10240
	ds_read_b128 v[166:169], v141 offset:12288
	ds_read_b128 v[170:173], v141 offset:14336
	s_waitcnt lgkmcnt(4)
	v_mfma_f32_16x16x32_bf16 v[124:127], v[142:145], v[174:177], v[124:127]
	v_mfma_f32_16x16x32_bf16 v[120:123], v[142:145], v[182:185], v[120:123]
	v_mfma_f32_16x16x32_bf16 v[116:119], v[142:145], v[186:189], v[116:119]
	v_mfma_f32_16x16x32_bf16 v[112:115], v[142:145], v[190:193], v[112:115]
	v_mfma_f32_16x16x32_bf16 v[108:111], v[146:149], v[174:177], v[108:111]
	v_mfma_f32_16x16x32_bf16 v[104:107], v[146:149], v[182:185], v[104:107]
	v_mfma_f32_16x16x32_bf16 v[100:103], v[146:149], v[186:189], v[100:103]
	v_mfma_f32_16x16x32_bf16 v[96:99], v[146:149], v[190:193], v[96:99]
	v_mfma_f32_16x16x32_bf16 v[92:95], v[150:153], v[174:177], v[92:95]
	v_mfma_f32_16x16x32_bf16 v[88:91], v[150:153], v[182:185], v[88:91]
	v_mfma_f32_16x16x32_bf16 v[84:87], v[150:153], v[186:189], v[84:87]
	v_mfma_f32_16x16x32_bf16 v[80:83], v[150:153], v[190:193], v[80:83]
	v_mfma_f32_16x16x32_bf16 v[76:79], v[154:157], v[174:177], v[76:79]
	v_mfma_f32_16x16x32_bf16 v[72:75], v[154:157], v[182:185], v[72:75]
	v_mfma_f32_16x16x32_bf16 v[68:71], v[154:157], v[186:189], v[68:71]
	v_mfma_f32_16x16x32_bf16 v[64:67], v[154:157], v[190:193], v[64:67]
	ds_read_b128 v[142:145], v180
	ds_read_b128 v[146:149], v180 offset:2048
	ds_read_b128 v[150:153], v180 offset:4096
	ds_read_b128 v[154:157], v180 offset:6144
	ds_read_b128 v[194:197], v211 offset:32768
	ds_read_b128 v[198:201], v211 offset:34816
	ds_read_b128 v[202:205], v211 offset:36864
	ds_read_b128 v[206:209], v211 offset:38912
	s_waitcnt lgkmcnt(8)
	v_mfma_f32_16x16x32_bf16 v[60:63], v[158:161], v[174:177], v[60:63]
	v_mfma_f32_16x16x32_bf16 v[56:59], v[158:161], v[182:185], v[56:59]
	v_mfma_f32_16x16x32_bf16 v[52:55], v[158:161], v[186:189], v[52:55]
	v_mfma_f32_16x16x32_bf16 v[48:51], v[158:161], v[190:193], v[48:51]
	v_mfma_f32_16x16x32_bf16 v[44:47], v[162:165], v[174:177], v[44:47]
	v_mfma_f32_16x16x32_bf16 v[32:35], v[162:165], v[182:185], v[32:35]
	v_mfma_f32_16x16x32_bf16 v[28:31], v[162:165], v[186:189], v[28:31]
	v_mfma_f32_16x16x32_bf16 v[24:27], v[162:165], v[190:193], v[24:27]
	v_mfma_f32_16x16x32_bf16 v[20:23], v[166:169], v[174:177], v[20:23]
	v_mfma_f32_16x16x32_bf16 v[16:19], v[166:169], v[182:185], v[16:19]
	v_mfma_f32_16x16x32_bf16 v[12:15], v[166:169], v[186:189], v[12:15]
	v_mfma_f32_16x16x32_bf16 v[8:11], v[166:169], v[190:193], v[8:11]
	v_mfma_f32_16x16x32_bf16 v[4:7], v[170:173], v[174:177], v[4:7]
	v_mfma_f32_16x16x32_bf16 v[0:3], v[170:173], v[182:185], v[0:3]
	v_mfma_f32_16x16x32_bf16 v[40:43], v[170:173], v[186:189], v[40:43]
	v_mfma_f32_16x16x32_bf16 v[36:39], v[170:173], v[190:193], v[36:39]
	ds_read_b128 v[158:161], v180 offset:8192
	ds_read_b128 v[162:165], v180 offset:10240
	ds_read_b128 v[166:169], v180 offset:12288
	ds_read_b128 v[170:173], v180 offset:14336
	s_waitcnt lgkmcnt(4)
	v_mfma_f32_16x16x32_bf16 v[124:127], v[142:145], v[194:197], v[124:127]
	v_mfma_f32_16x16x32_bf16 v[120:123], v[142:145], v[198:201], v[120:123]
	v_mfma_f32_16x16x32_bf16 v[116:119], v[142:145], v[202:205], v[116:119]
	v_mfma_f32_16x16x32_bf16 v[112:115], v[142:145], v[206:209], v[112:115]
	v_mfma_f32_16x16x32_bf16 v[108:111], v[146:149], v[194:197], v[108:111]
	v_mfma_f32_16x16x32_bf16 v[104:107], v[146:149], v[198:201], v[104:107]
	v_mfma_f32_16x16x32_bf16 v[100:103], v[146:149], v[202:205], v[100:103]
	v_mfma_f32_16x16x32_bf16 v[96:99], v[146:149], v[206:209], v[96:99]
	v_mfma_f32_16x16x32_bf16 v[92:95], v[150:153], v[194:197], v[92:95]
	v_mfma_f32_16x16x32_bf16 v[88:91], v[150:153], v[198:201], v[88:91]
	v_mfma_f32_16x16x32_bf16 v[84:87], v[150:153], v[202:205], v[84:87]
	v_mfma_f32_16x16x32_bf16 v[80:83], v[150:153], v[206:209], v[80:83]
	v_mfma_f32_16x16x32_bf16 v[76:79], v[154:157], v[194:197], v[76:79]
	v_mfma_f32_16x16x32_bf16 v[72:75], v[154:157], v[198:201], v[72:75]
	v_mfma_f32_16x16x32_bf16 v[68:71], v[154:157], v[202:205], v[68:71]
	v_mfma_f32_16x16x32_bf16 v[64:67], v[154:157], v[206:209], v[64:67]
	s_add_u32 s44, s44, 0x80
	s_addc_u32 s45, s45, 0
	s_add_i32 s43, s43, 1
	s_cmp_lt_u32 s43, 31
	s_cbranch_scc0 .Lg9_last
	s_waitcnt lgkmcnt(0)
	s_waitcnt vmcnt(0)
	s_barrier
	v_mfma_f32_16x16x32_bf16 v[60:63], v[158:161], v[194:197], v[60:63]
	v_mfma_f32_16x16x32_bf16 v[56:59], v[158:161], v[198:201], v[56:59]
	s_xor_b32 s59, s59, 0x10000
	s_mov_b32 m0, s59
	s_add_u32 s46, s44, s12
	s_addc_u32 s47, s45, s13
	global_load_lds_dwordx4 v178, s[46:47]
	s_add_u32 m0, s59, 0x2000
	s_add_u32 s46, s44, s14
	s_addc_u32 s47, s45, s15
	global_load_lds_dwordx4 v178, s[46:47]
	ds_read_b128 v[142:145], v212
	ds_read_b128 v[146:149], v212 offset:2048
	ds_read_b128 v[150:153], v212 offset:4096
	ds_read_b128 v[154:157], v212 offset:6144
	ds_read_b128 v[174:177], v214 offset:32768
	ds_read_b128 v[182:185], v214 offset:34816
	ds_read_b128 v[186:189], v214 offset:36864
	ds_read_b128 v[190:193], v214 offset:38912
	v_mfma_f32_16x16x32_bf16 v[52:55], v[158:161], v[202:205], v[52:55]
	v_mfma_f32_16x16x32_bf16 v[48:51], v[158:161], v[206:209], v[48:51]
	s_add_u32 m0, s59, 0x4000
	s_add_u32 s46, s44, s16
	s_addc_u32 s47, s45, s17
	global_load_lds_dwordx4 v178, s[46:47]
	v_mfma_f32_16x16x32_bf16 v[44:47], v[162:165], v[194:197], v[44:47]
	v_mfma_f32_16x16x32_bf16 v[32:35], v[162:165], v[198:201], v[32:35]
	s_add_u32 m0, s59, 0x6000
	s_add_u32 s46, s44, s18
	s_addc_u32 s47, s45, s19
	global_load_lds_dwordx4 v178, s[46:47]
	v_mfma_f32_16x16x32_bf16 v[28:31], v[162:165], v[202:205], v[28:31]
	v_mfma_f32_16x16x32_bf16 v[24:27], v[162:165], v[206:209], v[24:27]
	s_add_u32 m0, s59, 0x8000
	s_add_u32 s46, s44, s22
	s_addc_u32 s47, s45, s23
	global_load_lds_dwordx4 v179, s[46:47]
	v_mfma_f32_16x16x32_bf16 v[20:23], v[166:169], v[194:197], v[20:23]
	v_mfma_f32_16x16x32_bf16 v[16:19], v[166:169], v[198:201], v[16:19]
	s_add_u32 m0, s59, 0xa000
	s_add_u32 s46, s44, s36
	s_addc_u32 s47, s45, s37
	global_load_lds_dwordx4 v179, s[46:47]
	v_mfma_f32_16x16x32_bf16 v[12:15], v[166:169], v[202:205], v[12:15]
	v_mfma_f32_16x16x32_bf16 v[8:11], v[166:169], v[206:209], v[8:11]
	s_add_u32 m0, s59, 0xc000
	s_add_u32 s46, s44, s38
	s_addc_u32 s47, s45, s39
	global_load_lds_dwordx4 v179, s[46:47]
	v_mfma_f32_16x16x32_bf16 v[4:7], v[170:173], v[194:197], v[4:7]
	v_mfma_f32_16x16x32_bf16 v[0:3], v[170:173], v[198:201], v[0:3]
	s_add_u32 m0, s59, 0xe000
	s_add_u32 s46, s44, s40
	s_addc_u32 s47, s45, s41
	global_load_lds_dwordx4 v179, s[46:47]
	v_mfma_f32_16x16x32_bf16 v[40:43], v[170:173], v[202:205], v[40:43]
	v_mfma_f32_16x16x32_bf16 v[36:39], v[170:173], v[206:209], v[36:39]
	ds_read_b128 v[158:161], v212 offset:8192
	ds_read_b128 v[162:165], v212 offset:10240
	ds_read_b128 v[166:169], v212 offset:12288
	ds_read_b128 v[170:173], v212 offset:14336
	s_waitcnt lgkmcnt(4)
	v_mfma_f32_16x16x32_bf16 v[124:127], v[142:145], v[174:177], v[124:127]
	v_mfma_f32_16x16x32_bf16 v[120:123], v[142:145], v[182:185], v[120:123]
	v_mfma_f32_16x16x32_bf16 v[116:119], v[142:145], v[186:189], v[116:119]
	v_mfma_f32_16x16x32_bf16 v[112:115], v[142:145], v[190:193], v[112:115]
	v_mfma_f32_16x16x32_bf16 v[108:111], v[146:149], v[174:177], v[108:111]
	v_mfma_f32_16x16x32_bf16 v[104:107], v[146:149], v[182:185], v[104:107]
	v_mfma_f32_16x16x32_bf16 v[100:103], v[146:149], v[186:189], v[100:103]
	v_mfma_f32_16x16x32_bf16 v[96:99], v[146:149], v[190:193], v[96:99]
	v_mfma_f32_16x16x32_bf16 v[92:95], v[150:153], v[174:177], v[92:95]
	v_mfma_f32_16x16x32_bf16 v[88:91], v[150:153], v[182:185], v[88:91]
	v_mfma_f32_16x16x32_bf16 v[84:87], v[150:153], v[186:189], v[84:87]
	v_mfma_f32_16x16x32_bf16 v[80:83], v[150:153], v[190:193], v[80:83]
	v_mfma_f32_16x16x32_bf16 v[76:79], v[154:157], v[174:177], v[76:79]
	v_mfma_f32_16x16x32_bf16 v[72:75], v[154:157], v[182:185], v[72:75]
	v_mfma_f32_16x16x32_bf16 v[68:71], v[154:157], v[186:189], v[68:71]
	v_mfma_f32_16x16x32_bf16 v[64:67], v[154:157], v[190:193], v[64:67]
	ds_read_b128 v[142:145], v213
	ds_read_b128 v[146:149], v213 offset:2048
	ds_read_b128 v[150:153], v213 offset:4096
	ds_read_b128 v[154:157], v213 offset:6144
	ds_read_b128 v[194:197], v215 offset:32768
	ds_read_b128 v[198:201], v215 offset:34816
	ds_read_b128 v[202:205], v215 offset:36864
	ds_read_b128 v[206:209], v215 offset:38912
	s_waitcnt lgkmcnt(8)
	v_mfma_f32_16x16x32_bf16 v[60:63], v[158:161], v[174:177], v[60:63]
	v_mfma_f32_16x16x32_bf16 v[56:59], v[158:161], v[182:185], v[56:59]
	v_mfma_f32_16x16x32_bf16 v[52:55], v[158:161], v[186:189], v[52:55]
	v_mfma_f32_16x16x32_bf16 v[48:51], v[158:161], v[190:193], v[48:51]
	v_mfma_f32_16x16x32_bf16 v[44:47], v[162:165], v[174:177], v[44:47]
	v_mfma_f32_16x16x32_bf16 v[32:35], v[162:165], v[182:185], v[32:35]
	v_mfma_f32_16x16x32_bf16 v[28:31], v[162:165], v[186:189], v[28:31]
	v_mfma_f32_16x16x32_bf16 v[24:27], v[162:165], v[190:193], v[24:27]
	v_mfma_f32_16x16x32_bf16 v[20:23], v[166:169], v[174:177], v[20:23]
	v_mfma_f32_16x16x32_bf16 v[16:19], v[166:169], v[182:185], v[16:19]
	v_mfma_f32_16x16x32_bf16 v[12:15], v[166:169], v[186:189], v[12:15]
	v_mfma_f32_16x16x32_bf16 v[8:11], v[166:169], v[190:193], v[8:11]
	v_mfma_f32_16x16x32_bf16 v[4:7], v[170:173], v[174:177], v[4:7]
	v_mfma_f32_16x16x32_bf16 v[0:3], v[170:173], v[182:185], v[0:3]
	v_mfma_f32_16x16x32_bf16 v[40:43], v[170:173], v[186:189], v[40:43]
	v_mfma_f32_16x16x32_bf16 v[36:39], v[170:173], v[190:193], v[36:39]
	ds_read_b128 v[158:161], v213 offset:8192
	ds_read_b128 v[162:165], v213 offset:10240
	ds_read_b128 v[166:169], v213 offset:12288
	ds_read_b128 v[170:173], v213 offset:14336
	s_waitcnt lgkmcnt(4)
	v_mfma_f32_16x16x32_bf16 v[124:127], v[142:145], v[194:197], v[124:127]
	v_mfma_f32_16x16x32_bf16 v[120:123], v[142:145], v[198:201], v[120:123]
	v_mfma_f32_16x16x32_bf16 v[116:119], v[142:145], v[202:205], v[116:119]
	v_mfma_f32_16x16x32_bf16 v[112:115], v[142:145], v[206:209], v[112:115]
	v_mfma_f32_16x16x32_bf16 v[108:111], v[146:149], v[194:197], v[108:111]
	v_mfma_f32_16x16x32_bf16 v[104:107], v[146:149], v[198:201], v[104:107]
	v_mfma_f32_16x16x32_bf16 v[100:103], v[146:149], v[202:205], v[100:103]
	v_mfma_f32_16x16x32_bf16 v[96:99], v[146:149], v[206:209], v[96:99]
	v_mfma_f32_16x16x32_bf16 v[92:95], v[150:153], v[194:197], v[92:95]
	v_mfma_f32_16x16x32_bf16 v[88:91], v[150:153], v[198:201], v[88:91]
	v_mfma_f32_16x16x32_bf16 v[84:87], v[150:153], v[202:205], v[84:87]
	v_mfma_f32_16x16x32_bf16 v[80:83], v[150:153], v[206:209], v[80:83]
	v_mfma_f32_16x16x32_bf16 v[76:79], v[154:157], v[194:197], v[76:79]
	v_mfma_f32_16x16x32_bf16 v[72:75], v[154:157], v[198:201], v[72:75]
	v_mfma_f32_16x16x32_bf16 v[68:71], v[154:157], v[202:205], v[68:71]
	v_mfma_f32_16x16x32_bf16 v[64:67], v[154:157], v[206:209], v[64:67]
	s_add_u32 s44, s44, 0x80
	s_addc_u32 s45, s45, 0
	s_add_i32 s43, s43, 1
	s_branch .Lg9_top
.Lg9_last:
	s_waitcnt lgkmcnt(0)
	s_waitcnt vmcnt(0)
	s_barrier
	v_mfma_f32_16x16x32_bf16 v[60:63], v[158:161], v[194:197], v[60:63]
	v_mfma_f32_16x16x32_bf16 v[56:59], v[158:161], v[198:201], v[56:59]
	s_xor_b32 s59, s59, 0x10000
	ds_read_b128 v[142:145], v212
	ds_read_b128 v[146:149], v212 offset:2048
	ds_read_b128 v[150:153], v212 offset:4096
	ds_read_b128 v[154:157], v212 offset:6144
	ds_read_b128 v[174:177], v214 offset:32768
	ds_read_b128 v[182:185], v214 offset:34816
	ds_read_b128 v[186:189], v214 offset:36864
	ds_read_b128 v[190:193], v214 offset:38912
	v_mfma_f32_16x16x32_bf16 v[52:55], v[158:161], v[202:205], v[52:55]
	v_mfma_f32_16x16x32_bf16 v[48:51], v[158:161], v[206:209], v[48:51]
	v_mfma_f32_16x16x32_bf16 v[44:47], v[162:165], v[194:197], v[44:47]
	v_mfma_f32_16x16x32_bf16 v[32:35], v[162:165], v[198:201], v[32:35]
	v_mfma_f32_16x16x32_bf16 v[28:31], v[162:165], v[202:205], v[28:31]
	v_mfma_f32_16x16x32_bf16 v[24:27], v[162:165], v[206:209], v[24:27]
	v_mfma_f32_16x16x32_bf16 v[20:23], v[166:169], v[194:197], v[20:23]
	v_mfma_f32_16x16x32_bf16 v[16:19], v[166:169], v[198:201], v[16:19]
	v_mfma_f32_16x16x32_bf16 v[12:15], v[166:169], v[202:205], v[12:15]
	v_mfma_f32_16x16x32_bf16 v[8:11], v[166:169], v[206:209], v[8:11]
	v_mfma_f32_16x16x32_bf16 v[4:7], v[170:173], v[194:197], v[4:7]
	v_mfma_f32_16x16x32_bf16 v[0:3], v[170:173], v[198:201], v[0:3]
	v_mfma_f32_16x16x32_bf16 v[40:43], v[170:173], v[202:205], v[40:43]
	v_mfma_f32_16x16x32_bf16 v[36:39], v[170:173], v[206:209], v[36:39]
	ds_read_b128 v[158:161], v212 offset:8192
	ds_read_b128 v[162:165], v212 offset:10240
	ds_read_b128 v[166:169], v212 offset:12288
	ds_read_b128 v[170:173], v212 offset:14336
	s_waitcnt lgkmcnt(4)
	v_mfma_f32_16x16x32_bf16 v[124:127], v[142:145], v[174:177], v[124:127]
	v_mfma_f32_16x16x32_bf16 v[120:123], v[142:145], v[182:185], v[120:123]
	v_mfma_f32_16x16x32_bf16 v[116:119], v[142:145], v[186:189], v[116:119]
	v_mfma_f32_16x16x32_bf16 v[112:115], v[142:145], v[190:193], v[112:115]
	v_mfma_f32_16x16x32_bf16 v[108:111], v[146:149], v[174:177], v[108:111]
	v_mfma_f32_16x16x32_bf16 v[104:107], v[146:149], v[182:185], v[104:107]
	v_mfma_f32_16x16x32_bf16 v[100:103], v[146:149], v[186:189], v[100:103]
	v_mfma_f32_16x16x32_bf16 v[96:99], v[146:149], v[190:193], v[96:99]
	v_mfma_f32_16x16x32_bf16 v[92:95], v[150:153], v[174:177], v[92:95]
	v_mfma_f32_16x16x32_bf16 v[88:91], v[150:153], v[182:185], v[88:91]
	v_mfma_f32_16x16x32_bf16 v[84:87], v[150:153], v[186:189], v[84:87]
	v_mfma_f32_16x16x32_bf16 v[80:83], v[150:153], v[190:193], v[80:83]
	v_mfma_f32_16x16x32_bf16 v[76:79], v[154:157], v[174:177], v[76:79]
	v_mfma_f32_16x16x32_bf16 v[72:75], v[154:157], v[182:185], v[72:75]
	v_mfma_f32_16x16x32_bf16 v[68:71], v[154:157], v[186:189], v[68:71]
	v_mfma_f32_16x16x32_bf16 v[64:67], v[154:157], v[190:193], v[64:67]
	ds_read_b128 v[142:145], v213
	ds_read_b128 v[146:149], v213 offset:2048
	ds_read_b128 v[150:153], v213 offset:4096
	ds_read_b128 v[154:157], v213 offset:6144
	ds_read_b128 v[194:197], v215 offset:32768
	ds_read_b128 v[198:201], v215 offset:34816
	ds_read_b128 v[202:205], v215 offset:36864
	ds_read_b128 v[206:209], v215 offset:38912
	s_waitcnt lgkmcnt(8)
	v_mfma_f32_16x16x32_bf16 v[60:63], v[158:161], v[174:177], v[60:63]
	v_mfma_f32_16x16x32_bf16 v[56:59], v[158:161], v[182:185], v[56:59]
	v_mfma_f32_16x16x32_bf16 v[52:55], v[158:161], v[186:189], v[52:55]
	v_mfma_f32_16x16x32_bf16 v[48:51], v[158:161], v[190:193], v[48:51]
	v_mfma_f32_16x16x32_bf16 v[44:47], v[162:165], v[174:177], v[44:47]
	v_mfma_f32_16x16x32_bf16 v[32:35], v[162:165], v[182:185], v[32:35]
	v_mfma_f32_16x16x32_bf16 v[28:31], v[162:165], v[186:189], v[28:31]
	v_mfma_f32_16x16x32_bf16 v[24:27], v[162:165], v[190:193], v[24:27]
	v_mfma_f32_16x16x32_bf16 v[20:23], v[166:169], v[174:177], v[20:23]
	v_mfma_f32_16x16x32_bf16 v[16:19], v[166:169], v[182:185], v[16:19]
	v_mfma_f32_16x16x32_bf16 v[12:15], v[166:169], v[186:189], v[12:15]
	v_mfma_f32_16x16x32_bf16 v[8:11], v[166:169], v[190:193], v[8:11]
	v_mfma_f32_16x16x32_bf16 v[4:7], v[170:173], v[174:177], v[4:7]
	v_mfma_f32_16x16x32_bf16 v[0:3], v[170:173], v[182:185], v[0:3]
	v_mfma_f32_16x16x32_bf16 v[40:43], v[170:173], v[186:189], v[40:43]
	v_mfma_f32_16x16x32_bf16 v[36:39], v[170:173], v[190:193], v[36:39]
	ds_read_b128 v[158:161], v213 offset:8192
	ds_read_b128 v[162:165], v213 offset:10240
	ds_read_b128 v[166:169], v213 offset:12288
	ds_read_b128 v[170:173], v213 offset:14336
	s_waitcnt lgkmcnt(4)
	v_mfma_f32_16x16x32_bf16 v[124:127], v[142:145], v[194:197], v[124:127]
	v_mfma_f32_16x16x32_bf16 v[120:123], v[142:145], v[198:201], v[120:123]
	v_mfma_f32_16x16x32_bf16 v[116:119], v[142:145], v[202:205], v[116:119]
	v_mfma_f32_16x16x32_bf16 v[112:115], v[142:145], v[206:209], v[112:115]
	v_mfma_f32_16x16x32_bf16 v[108:111], v[146:149], v[194:197], v[108:111]
	v_mfma_f32_16x16x32_bf16 v[104:107], v[146:149], v[198:201], v[104:107]
	v_mfma_f32_16x16x32_bf16 v[100:103], v[146:149], v[202:205], v[100:103]
	v_mfma_f32_16x16x32_bf16 v[96:99], v[146:149], v[206:209], v[96:99]
	v_mfma_f32_16x16x32_bf16 v[92:95], v[150:153], v[194:197], v[92:95]
	v_mfma_f32_16x16x32_bf16 v[88:91], v[150:153], v[198:201], v[88:91]
	v_mfma_f32_16x16x32_bf16 v[84:87], v[150:153], v[202:205], v[84:87]
	v_mfma_f32_16x16x32_bf16 v[80:83], v[150:153], v[206:209], v[80:83]
	v_mfma_f32_16x16x32_bf16 v[76:79], v[154:157], v[194:197], v[76:79]
	v_mfma_f32_16x16x32_bf16 v[72:75], v[154:157], v[198:201], v[72:75]
	v_mfma_f32_16x16x32_bf16 v[68:71], v[154:157], v[202:205], v[68:71]
	v_mfma_f32_16x16x32_bf16 v[64:67], v[154:157], v[206:209], v[64:67]
	s_add_u32 s44, s44, 0x80
	s_addc_u32 s45, s45, 0
	s_add_i32 s43, s43, 1
	s_waitcnt lgkmcnt(0)
	s_waitcnt vmcnt(0)
	s_barrier
	v_mfma_f32_16x16x32_bf16 v[60:63], v[158:161], v[194:197], v[60:63]
	v_mfma_f32_16x16x32_bf16 v[56:59], v[158:161], v[198:201], v[56:59]
	v_mfma_f32_16x16x32_bf16 v[52:55], v[158:161], v[202:205], v[52:55]
	v_mfma_f32_16x16x32_bf16 v[48:51], v[158:161], v[206:209], v[48:51]
	v_mfma_f32_16x16x32_bf16 v[44:47], v[162:165], v[194:197], v[44:47]
	v_mfma_f32_16x16x32_bf16 v[32:35], v[162:165], v[198:201], v[32:35]
	v_mfma_f32_16x16x32_bf16 v[28:31], v[162:165], v[202:205], v[28:31]
	v_mfma_f32_16x16x32_bf16 v[24:27], v[162:165], v[206:209], v[24:27]
	v_mfma_f32_16x16x32_bf16 v[20:23], v[166:169], v[194:197], v[20:23]
	v_mfma_f32_16x16x32_bf16 v[16:19], v[166:169], v[198:201], v[16:19]
	v_mfma_f32_16x16x32_bf16 v[12:15], v[166:169], v[202:205], v[12:15]
	v_mfma_f32_16x16x32_bf16 v[8:11], v[166:169], v[206:209], v[8:11]
	v_mfma_f32_16x16x32_bf16 v[4:7], v[170:173], v[194:197], v[4:7]
	v_mfma_f32_16x16x32_bf16 v[0:3], v[170:173], v[198:201], v[0:3]
	v_mfma_f32_16x16x32_bf16 v[40:43], v[170:173], v[202:205], v[40:43]
	v_mfma_f32_16x16x32_bf16 v[36:39], v[170:173], v[206:209], v[36:39]
	s_nop 7
	s_nop 7
	s_sub_u32 s44, s44, s34
	s_subb_u32 s45, s45, s35
	s_mov_b32 s59, 0x100000
	s_mov_b32 s60, 0x100000
	s_mov_b64 s[46:47], 0
	s_mov_b64 vcc, exec
	s_branch .LBB0_1330

.Lg10_top:
	s_waitcnt lgkmcnt(0)
	s_waitcnt vmcnt(0)
	s_barrier
	v_mfma_f32_16x16x32_bf16 v[60:63], v[172:175], v[206:209], v[60:63]
	v_mfma_f32_16x16x32_bf16 v[52:55], v[172:175], v[210:213], v[52:55]
	s_xor_b32 s57, s57, 0x10000
	s_mov_b32 m0, s57
	s_add_u32 s46, s44, s14
	s_addc_u32 s47, s45, s15
	global_load_lds_dwordx4 v144, s[46:47]
	s_add_u32 m0, s57, 0x2000
	s_add_u32 s46, s44, s16
	s_addc_u32 s47, s45, s17
	global_load_lds_dwordx4 v144, s[46:47]
	ds_read_b128 v[156:159], v143
	ds_read_b128 v[160:163], v143 offset:2048
	ds_read_b128 v[164:167], v143 offset:4096
	ds_read_b128 v[168:171], v143 offset:6144
	ds_read_b128 v[190:193], v180 offset:32768
	ds_read_b128 v[194:197], v180 offset:34816
	ds_read_b128 v[198:201], v180 offset:36864
	ds_read_b128 v[202:205], v180 offset:38912
	v_mfma_f32_16x16x32_bf16 v[56:59], v[172:175], v[214:217], v[56:59]
	v_mfma_f32_16x16x32_bf16 v[48:51], v[172:175], v[218:221], v[48:51]
	s_add_u32 m0, s57, 0x4000
	s_add_u32 s46, s44, s18
	s_addc_u32 s47, s45, s19
	global_load_lds_dwordx4 v144, s[46:47]
	v_mfma_f32_16x16x32_bf16 v[44:47], v[176:179], v[206:209], v[44:47]
	v_mfma_f32_16x16x32_bf16 v[36:39], v[176:179], v[210:213], v[36:39]
	s_add_u32 m0, s57, 0x6000
	s_add_u32 s46, s44, s22
	s_addc_u32 s47, s45, s23
	global_load_lds_dwordx4 v144, s[46:47]
	v_mfma_f32_16x16x32_bf16 v[40:43], v[176:179], v[214:217], v[40:43]
	v_mfma_f32_16x16x32_bf16 v[32:35], v[176:179], v[218:221], v[32:35]
	s_add_u32 m0, s57, 0x8000
	s_add_u32 s46, s44, s30
	s_addc_u32 s47, s45, s31
	global_load_lds_dwordx4 v145, s[46:47]
	v_mfma_f32_16x16x32_bf16 v[28:31], v[182:185], v[206:209], v[28:31]
	v_mfma_f32_16x16x32_bf16 v[16:19], v[182:185], v[210:213], v[16:19]
	s_add_u32 m0, s57, 0xa000
	s_add_u32 s46, s44, s36
	s_addc_u32 s47, s45, s37
	global_load_lds_dwordx4 v145, s[46:47]
	v_mfma_f32_16x16x32_bf16 v[24:27], v[182:185], v[214:217], v[24:27]
	v_mfma_f32_16x16x32_bf16 v[12:15], v[182:185], v[218:221], v[12:15]
	s_add_u32 m0, s57, 0xc000
	s_add_u32 s46, s44, s38
	s_addc_u32 s47, s45, s39
	global_load_lds_dwordx4 v145, s[46:47]
	v_mfma_f32_16x16x32_bf16 v[4:7], v[186:189], v[206:209], v[4:7]
	v_mfma_f32_16x16x32_bf16 v[0:3], v[186:189], v[210:213], v[0:3]
	s_add_u32 m0, s57, 0xe000
	s_add_u32 s46, s44, s40
	s_addc_u32 s47, s45, s41
	global_load_lds_dwordx4 v145, s[46:47]
	v_mfma_f32_16x16x32_bf16 v[20:23], v[186:189], v[214:217], v[20:23]
	v_mfma_f32_16x16x32_bf16 v[8:11], v[186:189], v[218:221], v[8:11]
.Lg10_entry:
	ds_read_b128 v[172:175], v143 offset:8192
	ds_read_b128 v[176:179], v143 offset:10240
	ds_read_b128 v[182:185], v143 offset:12288
	ds_read_b128 v[186:189], v143 offset:14336
	s_waitcnt lgkmcnt(4)
	v_mfma_f32_16x16x32_bf16 v[124:127], v[156:159], v[190:193], v[124:127]
	v_mfma_f32_16x16x32_bf16 v[116:119], v[156:159], v[194:197], v[116:119]
	v_mfma_f32_16x16x32_bf16 v[120:123], v[156:159], v[198:201], v[120:123]
	v_mfma_f32_16x16x32_bf16 v[112:115], v[156:159], v[202:205], v[112:115]
	v_mfma_f32_16x16x32_bf16 v[108:111], v[160:163], v[190:193], v[108:111]
	v_mfma_f32_16x16x32_bf16 v[100:103], v[160:163], v[194:197], v[100:103]
	v_mfma_f32_16x16x32_bf16 v[104:107], v[160:163], v[198:201], v[104:107]
	v_mfma_f32_16x16x32_bf16 v[96:99], v[160:163], v[202:205], v[96:99]
	v_mfma_f32_16x16x32_bf16 v[92:95], v[164:167], v[190:193], v[92:95]
	v_mfma_f32_16x16x32_bf16 v[84:87], v[164:167], v[194:197], v[84:87]
	v_mfma_f32_16x16x32_bf16 v[88:91], v[164:167], v[198:201], v[88:91]
	v_mfma_f32_16x16x32_bf16 v[80:83], v[164:167], v[202:205], v[80:83]
	v_mfma_f32_16x16x32_bf16 v[76:79], v[168:171], v[190:193], v[76:79]
	v_mfma_f32_16x16x32_bf16 v[68:71], v[168:171], v[194:197], v[68:71]
	v_mfma_f32_16x16x32_bf16 v[72:75], v[168:171], v[198:201], v[72:75]
	v_mfma_f32_16x16x32_bf16 v[64:67], v[168:171], v[202:205], v[64:67]
	ds_read_b128 v[156:159], v155
	ds_read_b128 v[160:163], v155 offset:2048
	ds_read_b128 v[164:167], v155 offset:4096
	ds_read_b128 v[168:171], v155 offset:6144
	ds_read_b128 v[206:209], v222 offset:32768
	ds_read_b128 v[210:213], v222 offset:34816
	ds_read_b128 v[214:217], v222 offset:36864
	ds_read_b128 v[218:221], v222 offset:38912
	s_waitcnt lgkmcnt(8)
	v_mfma_f32_16x16x32_bf16 v[60:63], v[172:175], v[190:193], v[60:63]
	v_mfma_f32_16x16x32_bf16 v[52:55], v[172:175], v[194:197], v[52:55]
	v_mfma_f32_16x16x32_bf16 v[56:59], v[172:175], v[198:201], v[56:59]
	v_mfma_f32_16x16x32_bf16 v[48:51], v[172:175], v[202:205], v[48:51]
	v_mfma_f32_16x16x32_bf16 v[44:47], v[176:179], v[190:193], v[44:47]
	v_mfma_f32_16x16x32_bf16 v[36:39], v[176:179], v[194:197], v[36:39]
	v_mfma_f32_16x16x32_bf16 v[40:43], v[176:179], v[198:201], v[40:43]
	v_mfma_f32_16x16x32_bf16 v[32:35], v[176:179], v[202:205], v[32:35]
	v_mfma_f32_16x16x32_bf16 v[28:31], v[182:185], v[190:193], v[28:31]
	v_mfma_f32_16x16x32_bf16 v[16:19], v[182:185], v[194:197], v[16:19]
	v_mfma_f32_16x16x32_bf16 v[24:27], v[182:185], v[198:201], v[24:27]
	v_mfma_f32_16x16x32_bf16 v[12:15], v[182:185], v[202:205], v[12:15]
	v_mfma_f32_16x16x32_bf16 v[4:7], v[186:189], v[190:193], v[4:7]
	v_mfma_f32_16x16x32_bf16 v[0:3], v[186:189], v[194:197], v[0:3]
	v_mfma_f32_16x16x32_bf16 v[20:23], v[186:189], v[198:201], v[20:23]
	v_mfma_f32_16x16x32_bf16 v[8:11], v[186:189], v[202:205], v[8:11]
	ds_read_b128 v[172:175], v155 offset:8192
	ds_read_b128 v[176:179], v155 offset:10240
	ds_read_b128 v[182:185], v155 offset:12288
	ds_read_b128 v[186:189], v155 offset:14336
	s_waitcnt lgkmcnt(4)
	v_mfma_f32_16x16x32_bf16 v[124:127], v[156:159], v[206:209], v[124:127]
	v_mfma_f32_16x16x32_bf16 v[116:119], v[156:159], v[210:213], v[116:119]
	v_mfma_f32_16x16x32_bf16 v[120:123], v[156:159], v[214:217], v[120:123]
	v_mfma_f32_16x16x32_bf16 v[112:115], v[156:159], v[218:221], v[112:115]
	v_mfma_f32_16x16x32_bf16 v[108:111], v[160:163], v[206:209], v[108:111]
	v_mfma_f32_16x16x32_bf16 v[100:103], v[160:163], v[210:213], v[100:103]
	v_mfma_f32_16x16x32_bf16 v[104:107], v[160:163], v[214:217], v[104:107]
	v_mfma_f32_16x16x32_bf16 v[96:99], v[160:163], v[218:221], v[96:99]
	v_mfma_f32_16x16x32_bf16 v[92:95], v[164:167], v[206:209], v[92:95]
	v_mfma_f32_16x16x32_bf16 v[84:87], v[164:167], v[210:213], v[84:87]
	v_mfma_f32_16x16x32_bf16 v[88:91], v[164:167], v[214:217], v[88:91]
	v_mfma_f32_16x16x32_bf16 v[80:83], v[164:167], v[218:221], v[80:83]
	v_mfma_f32_16x16x32_bf16 v[76:79], v[168:171], v[206:209], v[76:79]
	v_mfma_f32_16x16x32_bf16 v[68:71], v[168:171], v[210:213], v[68:71]
	v_mfma_f32_16x16x32_bf16 v[72:75], v[168:171], v[214:217], v[72:75]
	v_mfma_f32_16x16x32_bf16 v[64:67], v[168:171], v[218:221], v[64:67]
	s_add_u32 s44, s44, 0x80
	s_addc_u32 s45, s45, 0
	s_add_i32 s43, s43, 1
	s_cmp_lt_u32 s43, 15
	s_cbranch_scc0 .Lg10_last
	s_waitcnt lgkmcnt(0)
	s_waitcnt vmcnt(0)
	s_barrier
	v_mfma_f32_16x16x32_bf16 v[60:63], v[172:175], v[206:209], v[60:63]
	v_mfma_f32_16x16x32_bf16 v[52:55], v[172:175], v[210:213], v[52:55]
	s_xor_b32 s57, s57, 0x10000
	s_mov_b32 m0, s57
	s_add_u32 s46, s44, s14
	s_addc_u32 s47, s45, s15
	global_load_lds_dwordx4 v144, s[46:47]
	s_add_u32 m0, s57, 0x2000
	s_add_u32 s46, s44, s16
	s_addc_u32 s47, s45, s17
	global_load_lds_dwordx4 v144, s[46:47]
	ds_read_b128 v[156:159], v223
	ds_read_b128 v[160:163], v223 offset:2048
	ds_read_b128 v[164:167], v223 offset:4096
	ds_read_b128 v[168:171], v223 offset:6144
	ds_read_b128 v[190:193], v225 offset:32768
	ds_read_b128 v[194:197], v225 offset:34816
	ds_read_b128 v[198:201], v225 offset:36864
	ds_read_b128 v[202:205], v225 offset:38912
	v_mfma_f32_16x16x32_bf16 v[56:59], v[172:175], v[214:217], v[56:59]
	v_mfma_f32_16x16x32_bf16 v[48:51], v[172:175], v[218:221], v[48:51]
	s_add_u32 m0, s57, 0x4000
	s_add_u32 s46, s44, s18
	s_addc_u32 s47, s45, s19
	global_load_lds_dwordx4 v144, s[46:47]
	v_mfma_f32_16x16x32_bf16 v[44:47], v[176:179], v[206:209], v[44:47]
	v_mfma_f32_16x16x32_bf16 v[36:39], v[176:179], v[210:213], v[36:39]
	s_add_u32 m0, s57, 0x6000
	s_add_u32 s46, s44, s22
	s_addc_u32 s47, s45, s23
	global_load_lds_dwordx4 v144, s[46:47]
	v_mfma_f32_16x16x32_bf16 v[40:43], v[176:179], v[214:217], v[40:43]
	v_mfma_f32_16x16x32_bf16 v[32:35], v[176:179], v[218:221], v[32:35]
	s_add_u32 m0, s57, 0x8000
	s_add_u32 s46, s44, s30
	s_addc_u32 s47, s45, s31
	global_load_lds_dwordx4 v145, s[46:47]
	v_mfma_f32_16x16x32_bf16 v[28:31], v[182:185], v[206:209], v[28:31]
	v_mfma_f32_16x16x32_bf16 v[16:19], v[182:185], v[210:213], v[16:19]
	s_add_u32 m0, s57, 0xa000
	s_add_u32 s46, s44, s36
	s_addc_u32 s47, s45, s37
	global_load_lds_dwordx4 v145, s[46:47]
	v_mfma_f32_16x16x32_bf16 v[24:27], v[182:185], v[214:217], v[24:27]
	v_mfma_f32_16x16x32_bf16 v[12:15], v[182:185], v[218:221], v[12:15]
	s_add_u32 m0, s57, 0xc000
	s_add_u32 s46, s44, s38
	s_addc_u32 s47, s45, s39
	global_load_lds_dwordx4 v145, s[46:47]
	v_mfma_f32_16x16x32_bf16 v[4:7], v[186:189], v[206:209], v[4:7]
	v_mfma_f32_16x16x32_bf16 v[0:3], v[186:189], v[210:213], v[0:3]
	s_add_u32 m0, s57, 0xe000
	s_add_u32 s46, s44, s40
	s_addc_u32 s47, s45, s41
	global_load_lds_dwordx4 v145, s[46:47]
	v_mfma_f32_16x16x32_bf16 v[20:23], v[186:189], v[214:217], v[20:23]
	v_mfma_f32_16x16x32_bf16 v[8:11], v[186:189], v[218:221], v[8:11]
	ds_read_b128 v[172:175], v223 offset:8192
	ds_read_b128 v[176:179], v223 offset:10240
	ds_read_b128 v[182:185], v223 offset:12288
	ds_read_b128 v[186:189], v223 offset:14336
	s_waitcnt lgkmcnt(4)
	v_mfma_f32_16x16x32_bf16 v[124:127], v[156:159], v[190:193], v[124:127]
	v_mfma_f32_16x16x32_bf16 v[116:119], v[156:159], v[194:197], v[116:119]
	v_mfma_f32_16x16x32_bf16 v[120:123], v[156:159], v[198:201], v[120:123]
	v_mfma_f32_16x16x32_bf16 v[112:115], v[156:159], v[202:205], v[112:115]
	v_mfma_f32_16x16x32_bf16 v[108:111], v[160:163], v[190:193], v[108:111]
	v_mfma_f32_16x16x32_bf16 v[100:103], v[160:163], v[194:197], v[100:103]
	v_mfma_f32_16x16x32_bf16 v[104:107], v[160:163], v[198:201], v[104:107]
	v_mfma_f32_16x16x32_bf16 v[96:99], v[160:163], v[202:205], v[96:99]
	v_mfma_f32_16x16x32_bf16 v[92:95], v[164:167], v[190:193], v[92:95]
	v_mfma_f32_16x16x32_bf16 v[84:87], v[164:167], v[194:197], v[84:87]
	v_mfma_f32_16x16x32_bf16 v[88:91], v[164:167], v[198:201], v[88:91]
	v_mfma_f32_16x16x32_bf16 v[80:83], v[164:167], v[202:205], v[80:83]
	v_mfma_f32_16x16x32_bf16 v[76:79], v[168:171], v[190:193], v[76:79]
	v_mfma_f32_16x16x32_bf16 v[68:71], v[168:171], v[194:197], v[68:71]
	v_mfma_f32_16x16x32_bf16 v[72:75], v[168:171], v[198:201], v[72:75]
	v_mfma_f32_16x16x32_bf16 v[64:67], v[168:171], v[202:205], v[64:67]
	ds_read_b128 v[156:159], v224
	ds_read_b128 v[160:163], v224 offset:2048
	ds_read_b128 v[164:167], v224 offset:4096
	ds_read_b128 v[168:171], v224 offset:6144
	ds_read_b128 v[206:209], v226 offset:32768
	ds_read_b128 v[210:213], v226 offset:34816
	ds_read_b128 v[214:217], v226 offset:36864
	ds_read_b128 v[218:221], v226 offset:38912
	s_waitcnt lgkmcnt(8)
	v_mfma_f32_16x16x32_bf16 v[60:63], v[172:175], v[190:193], v[60:63]
	v_mfma_f32_16x16x32_bf16 v[52:55], v[172:175], v[194:197], v[52:55]
	v_mfma_f32_16x16x32_bf16 v[56:59], v[172:175], v[198:201], v[56:59]
	v_mfma_f32_16x16x32_bf16 v[48:51], v[172:175], v[202:205], v[48:51]
	v_mfma_f32_16x16x32_bf16 v[44:47], v[176:179], v[190:193], v[44:47]
	v_mfma_f32_16x16x32_bf16 v[36:39], v[176:179], v[194:197], v[36:39]
	v_mfma_f32_16x16x32_bf16 v[40:43], v[176:179], v[198:201], v[40:43]
	v_mfma_f32_16x16x32_bf16 v[32:35], v[176:179], v[202:205], v[32:35]
	v_mfma_f32_16x16x32_bf16 v[28:31], v[182:185], v[190:193], v[28:31]
	v_mfma_f32_16x16x32_bf16 v[16:19], v[182:185], v[194:197], v[16:19]
	v_mfma_f32_16x16x32_bf16 v[24:27], v[182:185], v[198:201], v[24:27]
	v_mfma_f32_16x16x32_bf16 v[12:15], v[182:185], v[202:205], v[12:15]
	v_mfma_f32_16x16x32_bf16 v[4:7], v[186:189], v[190:193], v[4:7]
	v_mfma_f32_16x16x32_bf16 v[0:3], v[186:189], v[194:197], v[0:3]
	v_mfma_f32_16x16x32_bf16 v[20:23], v[186:189], v[198:201], v[20:23]
	v_mfma_f32_16x16x32_bf16 v[8:11], v[186:189], v[202:205], v[8:11]
	ds_read_b128 v[172:175], v224 offset:8192
	ds_read_b128 v[176:179], v224 offset:10240
	ds_read_b128 v[182:185], v224 offset:12288
	ds_read_b128 v[186:189], v224 offset:14336
	s_waitcnt lgkmcnt(4)
	v_mfma_f32_16x16x32_bf16 v[124:127], v[156:159], v[206:209], v[124:127]
	v_mfma_f32_16x16x32_bf16 v[116:119], v[156:159], v[210:213], v[116:119]
	v_mfma_f32_16x16x32_bf16 v[120:123], v[156:159], v[214:217], v[120:123]
	v_mfma_f32_16x16x32_bf16 v[112:115], v[156:159], v[218:221], v[112:115]
	v_mfma_f32_16x16x32_bf16 v[108:111], v[160:163], v[206:209], v[108:111]
	v_mfma_f32_16x16x32_bf16 v[100:103], v[160:163], v[210:213], v[100:103]
	v_mfma_f32_16x16x32_bf16 v[104:107], v[160:163], v[214:217], v[104:107]
	v_mfma_f32_16x16x32_bf16 v[96:99], v[160:163], v[218:221], v[96:99]
	v_mfma_f32_16x16x32_bf16 v[92:95], v[164:167], v[206:209], v[92:95]
	v_mfma_f32_16x16x32_bf16 v[84:87], v[164:167], v[210:213], v[84:87]
	v_mfma_f32_16x16x32_bf16 v[88:91], v[164:167], v[214:217], v[88:91]
	v_mfma_f32_16x16x32_bf16 v[80:83], v[164:167], v[218:221], v[80:83]
	v_mfma_f32_16x16x32_bf16 v[76:79], v[168:171], v[206:209], v[76:79]
	v_mfma_f32_16x16x32_bf16 v[68:71], v[168:171], v[210:213], v[68:71]
	v_mfma_f32_16x16x32_bf16 v[72:75], v[168:171], v[214:217], v[72:75]
	v_mfma_f32_16x16x32_bf16 v[64:67], v[168:171], v[218:221], v[64:67]
	s_add_u32 s44, s44, 0x80
	s_addc_u32 s45, s45, 0
	s_add_i32 s43, s43, 1
	s_branch .Lg10_top
.Lg10_last:
	s_waitcnt lgkmcnt(0)
	s_waitcnt vmcnt(0)
	s_barrier
	v_mfma_f32_16x16x32_bf16 v[60:63], v[172:175], v[206:209], v[60:63]
	v_mfma_f32_16x16x32_bf16 v[52:55], v[172:175], v[210:213], v[52:55]
	s_xor_b32 s57, s57, 0x10000
	ds_read_b128 v[156:159], v223
	ds_read_b128 v[160:163], v223 offset:2048
	ds_read_b128 v[164:167], v223 offset:4096
	ds_read_b128 v[168:171], v223 offset:6144
	ds_read_b128 v[190:193], v225 offset:32768
	ds_read_b128 v[194:197], v225 offset:34816
	ds_read_b128 v[198:201], v225 offset:36864
	ds_read_b128 v[202:205], v225 offset:38912
	v_mfma_f32_16x16x32_bf16 v[56:59], v[172:175], v[214:217], v[56:59]
	v_mfma_f32_16x16x32_bf16 v[48:51], v[172:175], v[218:221], v[48:51]
	v_mfma_f32_16x16x32_bf16 v[44:47], v[176:179], v[206:209], v[44:47]
	v_mfma_f32_16x16x32_bf16 v[36:39], v[176:179], v[210:213], v[36:39]
	v_mfma_f32_16x16x32_bf16 v[40:43], v[176:179], v[214:217], v[40:43]
	v_mfma_f32_16x16x32_bf16 v[32:35], v[176:179], v[218:221], v[32:35]
	v_mfma_f32_16x16x32_bf16 v[28:31], v[182:185], v[206:209], v[28:31]
	v_mfma_f32_16x16x32_bf16 v[16:19], v[182:185], v[210:213], v[16:19]
	v_mfma_f32_16x16x32_bf16 v[24:27], v[182:185], v[214:217], v[24:27]
	v_mfma_f32_16x16x32_bf16 v[12:15], v[182:185], v[218:221], v[12:15]
	v_mfma_f32_16x16x32_bf16 v[4:7], v[186:189], v[206:209], v[4:7]
	v_mfma_f32_16x16x32_bf16 v[0:3], v[186:189], v[210:213], v[0:3]
	v_mfma_f32_16x16x32_bf16 v[20:23], v[186:189], v[214:217], v[20:23]
	v_mfma_f32_16x16x32_bf16 v[8:11], v[186:189], v[218:221], v[8:11]
	ds_read_b128 v[172:175], v223 offset:8192
	ds_read_b128 v[176:179], v223 offset:10240
	ds_read_b128 v[182:185], v223 offset:12288
	ds_read_b128 v[186:189], v223 offset:14336
	s_waitcnt lgkmcnt(4)
	v_mfma_f32_16x16x32_bf16 v[124:127], v[156:159], v[190:193], v[124:127]
	v_mfma_f32_16x16x32_bf16 v[116:119], v[156:159], v[194:197], v[116:119]
	v_mfma_f32_16x16x32_bf16 v[120:123], v[156:159], v[198:201], v[120:123]
	v_mfma_f32_16x16x32_bf16 v[112:115], v[156:159], v[202:205], v[112:115]
	v_mfma_f32_16x16x32_bf16 v[108:111], v[160:163], v[190:193], v[108:111]
	v_mfma_f32_16x16x32_bf16 v[100:103], v[160:163], v[194:197], v[100:103]
	v_mfma_f32_16x16x32_bf16 v[104:107], v[160:163], v[198:201], v[104:107]
	v_mfma_f32_16x16x32_bf16 v[96:99], v[160:163], v[202:205], v[96:99]
	v_mfma_f32_16x16x32_bf16 v[92:95], v[164:167], v[190:193], v[92:95]
	v_mfma_f32_16x16x32_bf16 v[84:87], v[164:167], v[194:197], v[84:87]
	v_mfma_f32_16x16x32_bf16 v[88:91], v[164:167], v[198:201], v[88:91]
	v_mfma_f32_16x16x32_bf16 v[80:83], v[164:167], v[202:205], v[80:83]
	v_mfma_f32_16x16x32_bf16 v[76:79], v[168:171], v[190:193], v[76:79]
	v_mfma_f32_16x16x32_bf16 v[68:71], v[168:171], v[194:197], v[68:71]
	v_mfma_f32_16x16x32_bf16 v[72:75], v[168:171], v[198:201], v[72:75]
	v_mfma_f32_16x16x32_bf16 v[64:67], v[168:171], v[202:205], v[64:67]
	ds_read_b128 v[156:159], v224
	ds_read_b128 v[160:163], v224 offset:2048
	ds_read_b128 v[164:167], v224 offset:4096
	ds_read_b128 v[168:171], v224 offset:6144
	ds_read_b128 v[206:209], v226 offset:32768
	ds_read_b128 v[210:213], v226 offset:34816
	ds_read_b128 v[214:217], v226 offset:36864
	ds_read_b128 v[218:221], v226 offset:38912
	s_waitcnt lgkmcnt(8)
	v_mfma_f32_16x16x32_bf16 v[60:63], v[172:175], v[190:193], v[60:63]
	v_mfma_f32_16x16x32_bf16 v[52:55], v[172:175], v[194:197], v[52:55]
	v_mfma_f32_16x16x32_bf16 v[56:59], v[172:175], v[198:201], v[56:59]
	v_mfma_f32_16x16x32_bf16 v[48:51], v[172:175], v[202:205], v[48:51]
	v_mfma_f32_16x16x32_bf16 v[44:47], v[176:179], v[190:193], v[44:47]
	v_mfma_f32_16x16x32_bf16 v[36:39], v[176:179], v[194:197], v[36:39]
	v_mfma_f32_16x16x32_bf16 v[40:43], v[176:179], v[198:201], v[40:43]
	v_mfma_f32_16x16x32_bf16 v[32:35], v[176:179], v[202:205], v[32:35]
	v_mfma_f32_16x16x32_bf16 v[28:31], v[182:185], v[190:193], v[28:31]
	v_mfma_f32_16x16x32_bf16 v[16:19], v[182:185], v[194:197], v[16:19]
	v_mfma_f32_16x16x32_bf16 v[24:27], v[182:185], v[198:201], v[24:27]
	v_mfma_f32_16x16x32_bf16 v[12:15], v[182:185], v[202:205], v[12:15]
	v_mfma_f32_16x16x32_bf16 v[4:7], v[186:189], v[190:193], v[4:7]
	v_mfma_f32_16x16x32_bf16 v[0:3], v[186:189], v[194:197], v[0:3]
	v_mfma_f32_16x16x32_bf16 v[20:23], v[186:189], v[198:201], v[20:23]
	v_mfma_f32_16x16x32_bf16 v[8:11], v[186:189], v[202:205], v[8:11]
	ds_read_b128 v[172:175], v224 offset:8192
	ds_read_b128 v[176:179], v224 offset:10240
	ds_read_b128 v[182:185], v224 offset:12288
	ds_read_b128 v[186:189], v224 offset:14336
	s_waitcnt lgkmcnt(4)
	v_mfma_f32_16x16x32_bf16 v[124:127], v[156:159], v[206:209], v[124:127]
	v_mfma_f32_16x16x32_bf16 v[116:119], v[156:159], v[210:213], v[116:119]
	v_mfma_f32_16x16x32_bf16 v[120:123], v[156:159], v[214:217], v[120:123]
	v_mfma_f32_16x16x32_bf16 v[112:115], v[156:159], v[218:221], v[112:115]
	v_mfma_f32_16x16x32_bf16 v[108:111], v[160:163], v[206:209], v[108:111]
	v_mfma_f32_16x16x32_bf16 v[100:103], v[160:163], v[210:213], v[100:103]
	v_mfma_f32_16x16x32_bf16 v[104:107], v[160:163], v[214:217], v[104:107]
	v_mfma_f32_16x16x32_bf16 v[96:99], v[160:163], v[218:221], v[96:99]
	v_mfma_f32_16x16x32_bf16 v[92:95], v[164:167], v[206:209], v[92:95]
	v_mfma_f32_16x16x32_bf16 v[84:87], v[164:167], v[210:213], v[84:87]
	v_mfma_f32_16x16x32_bf16 v[88:91], v[164:167], v[214:217], v[88:91]
	v_mfma_f32_16x16x32_bf16 v[80:83], v[164:167], v[218:221], v[80:83]
	v_mfma_f32_16x16x32_bf16 v[76:79], v[168:171], v[206:209], v[76:79]
	v_mfma_f32_16x16x32_bf16 v[68:71], v[168:171], v[210:213], v[68:71]
	v_mfma_f32_16x16x32_bf16 v[72:75], v[168:171], v[214:217], v[72:75]
	v_mfma_f32_16x16x32_bf16 v[64:67], v[168:171], v[218:221], v[64:67]
	s_add_u32 s44, s44, 0x80
	s_addc_u32 s45, s45, 0
	s_add_i32 s43, s43, 1
	s_waitcnt lgkmcnt(0)
	s_waitcnt vmcnt(0)
	s_barrier
	v_mfma_f32_16x16x32_bf16 v[60:63], v[172:175], v[206:209], v[60:63]
	v_mfma_f32_16x16x32_bf16 v[52:55], v[172:175], v[210:213], v[52:55]
	v_mfma_f32_16x16x32_bf16 v[56:59], v[172:175], v[214:217], v[56:59]
	v_mfma_f32_16x16x32_bf16 v[48:51], v[172:175], v[218:221], v[48:51]
	v_mfma_f32_16x16x32_bf16 v[44:47], v[176:179], v[206:209], v[44:47]
	v_mfma_f32_16x16x32_bf16 v[36:39], v[176:179], v[210:213], v[36:39]
	v_mfma_f32_16x16x32_bf16 v[40:43], v[176:179], v[214:217], v[40:43]
	v_mfma_f32_16x16x32_bf16 v[32:35], v[176:179], v[218:221], v[32:35]
	v_mfma_f32_16x16x32_bf16 v[28:31], v[182:185], v[206:209], v[28:31]
	v_mfma_f32_16x16x32_bf16 v[16:19], v[182:185], v[210:213], v[16:19]
	v_mfma_f32_16x16x32_bf16 v[24:27], v[182:185], v[214:217], v[24:27]
	v_mfma_f32_16x16x32_bf16 v[12:15], v[182:185], v[218:221], v[12:15]
	v_mfma_f32_16x16x32_bf16 v[4:7], v[186:189], v[206:209], v[4:7]
	v_mfma_f32_16x16x32_bf16 v[0:3], v[186:189], v[210:213], v[0:3]
	v_mfma_f32_16x16x32_bf16 v[20:23], v[186:189], v[214:217], v[20:23]
	v_mfma_f32_16x16x32_bf16 v[8:11], v[186:189], v[218:221], v[8:11]
	s_nop 7
	s_nop 7
	s_sub_u32 s44, s44, s34
	s_subb_u32 s45, s45, s35
	s_mov_b32 s57, 0x80000
	s_mov_b32 s58, 0x80000
	s_mov_b64 s[46:47], 0
	s_mov_b64 vcc, exec
	s_branch .LBB0_1494

.Lg11_top:
	s_waitcnt lgkmcnt(0)
	s_waitcnt vmcnt(0)
	s_barrier
	v_mfma_f32_16x16x32_bf16 v[60:63], v[158:161], v[194:197], v[60:63]
	v_mfma_f32_16x16x32_bf16 v[56:59], v[158:161], v[198:201], v[56:59]
	s_xor_b32 s45, s45, 0x10000
	s_mov_b32 m0, s45
	s_add_u32 s38, s36, s12
	s_addc_u32 s39, s37, s13
	global_load_lds_dwordx4 v178, s[38:39]
	s_add_u32 m0, s45, 0x2000
	s_add_u32 s38, s36, s14
	s_addc_u32 s39, s37, s15
	global_load_lds_dwordx4 v178, s[38:39]
	ds_read_b128 v[142:145], v141
	ds_read_b128 v[146:149], v141 offset:2048
	ds_read_b128 v[150:153], v141 offset:4096
	ds_read_b128 v[154:157], v141 offset:6144
	ds_read_b128 v[174:177], v210 offset:32768
	ds_read_b128 v[182:185], v210 offset:34816
	ds_read_b128 v[186:189], v210 offset:36864
	ds_read_b128 v[190:193], v210 offset:38912
	v_mfma_f32_16x16x32_bf16 v[52:55], v[158:161], v[202:205], v[52:55]
	v_mfma_f32_16x16x32_bf16 v[48:51], v[158:161], v[206:209], v[48:51]
	s_add_u32 m0, s45, 0x4000
	s_add_u32 s38, s36, s16
	s_addc_u32 s39, s37, s17
	global_load_lds_dwordx4 v178, s[38:39]
	v_mfma_f32_16x16x32_bf16 v[44:47], v[162:165], v[194:197], v[44:47]
	v_mfma_f32_16x16x32_bf16 v[32:35], v[162:165], v[198:201], v[32:35]
	s_add_u32 m0, s45, 0x6000
	s_add_u32 s38, s36, s18
	s_addc_u32 s39, s37, s19
	global_load_lds_dwordx4 v178, s[38:39]
	v_mfma_f32_16x16x32_bf16 v[28:31], v[162:165], v[202:205], v[28:31]
	v_mfma_f32_16x16x32_bf16 v[24:27], v[162:165], v[206:209], v[24:27]
	s_add_u32 m0, s45, 0x8000
	s_add_u32 s38, s36, s22
	s_addc_u32 s39, s37, s23
	global_load_lds_dwordx4 v179, s[38:39]
	v_mfma_f32_16x16x32_bf16 v[20:23], v[166:169], v[194:197], v[20:23]
	v_mfma_f32_16x16x32_bf16 v[16:19], v[166:169], v[198:201], v[16:19]
	s_add_u32 m0, s45, 0xa000
	s_add_u32 s38, s36, s24
	s_addc_u32 s39, s37, s25
	global_load_lds_dwordx4 v179, s[38:39]
	v_mfma_f32_16x16x32_bf16 v[12:15], v[166:169], v[202:205], v[12:15]
	v_mfma_f32_16x16x32_bf16 v[8:11], v[166:169], v[206:209], v[8:11]
	s_add_u32 m0, s45, 0xc000
	s_add_u32 s38, s36, s26
	s_addc_u32 s39, s37, s27
	global_load_lds_dwordx4 v179, s[38:39]
	v_mfma_f32_16x16x32_bf16 v[4:7], v[170:173], v[194:197], v[4:7]
	v_mfma_f32_16x16x32_bf16 v[0:3], v[170:173], v[198:201], v[0:3]
	s_add_u32 m0, s45, 0xe000
	s_add_u32 s38, s36, s28
	s_addc_u32 s39, s37, s29
	global_load_lds_dwordx4 v179, s[38:39]
	v_mfma_f32_16x16x32_bf16 v[40:43], v[170:173], v[202:205], v[40:43]
	v_mfma_f32_16x16x32_bf16 v[36:39], v[170:173], v[206:209], v[36:39]
.Lg11_entry:
	ds_read_b128 v[158:161], v141 offset:8192
	ds_read_b128 v[162:165], v141 offset:10240
	ds_read_b128 v[166:169], v141 offset:12288
	ds_read_b128 v[170:173], v141 offset:14336
	s_waitcnt lgkmcnt(4)
	v_mfma_f32_16x16x32_bf16 v[124:127], v[142:145], v[174:177], v[124:127]
	v_mfma_f32_16x16x32_bf16 v[120:123], v[142:145], v[182:185], v[120:123]
	v_mfma_f32_16x16x32_bf16 v[116:119], v[142:145], v[186:189], v[116:119]
	v_mfma_f32_16x16x32_bf16 v[112:115], v[142:145], v[190:193], v[112:115]
	v_mfma_f32_16x16x32_bf16 v[108:111], v[146:149], v[174:177], v[108:111]
	v_mfma_f32_16x16x32_bf16 v[104:107], v[146:149], v[182:185], v[104:107]
	v_mfma_f32_16x16x32_bf16 v[100:103], v[146:149], v[186:189], v[100:103]
	v_mfma_f32_16x16x32_bf16 v[96:99], v[146:149], v[190:193], v[96:99]
	v_mfma_f32_16x16x32_bf16 v[92:95], v[150:153], v[174:177], v[92:95]
	v_mfma_f32_16x16x32_bf16 v[88:91], v[150:153], v[182:185], v[88:91]
	v_mfma_f32_16x16x32_bf16 v[84:87], v[150:153], v[186:189], v[84:87]
	v_mfma_f32_16x16x32_bf16 v[80:83], v[150:153], v[190:193], v[80:83]
	v_mfma_f32_16x16x32_bf16 v[76:79], v[154:157], v[174:177], v[76:79]
	v_mfma_f32_16x16x32_bf16 v[72:75], v[154:157], v[182:185], v[72:75]
	v_mfma_f32_16x16x32_bf16 v[68:71], v[154:157], v[186:189], v[68:71]
	v_mfma_f32_16x16x32_bf16 v[64:67], v[154:157], v[190:193], v[64:67]
	ds_read_b128 v[142:145], v180
	ds_read_b128 v[146:149], v180 offset:2048
	ds_read_b128 v[150:153], v180 offset:4096
	ds_read_b128 v[154:157], v180 offset:6144
	ds_read_b128 v[194:197], v211 offset:32768
	ds_read_b128 v[198:201], v211 offset:34816
	ds_read_b128 v[202:205], v211 offset:36864
	ds_read_b128 v[206:209], v211 offset:38912
	s_waitcnt lgkmcnt(8)
	v_mfma_f32_16x16x32_bf16 v[60:63], v[158:161], v[174:177], v[60:63]
	v_mfma_f32_16x16x32_bf16 v[56:59], v[158:161], v[182:185], v[56:59]
	v_mfma_f32_16x16x32_bf16 v[52:55], v[158:161], v[186:189], v[52:55]
	v_mfma_f32_16x16x32_bf16 v[48:51], v[158:161], v[190:193], v[48:51]
	v_mfma_f32_16x16x32_bf16 v[44:47], v[162:165], v[174:177], v[44:47]
	v_mfma_f32_16x16x32_bf16 v[32:35], v[162:165], v[182:185], v[32:35]
	v_mfma_f32_16x16x32_bf16 v[28:31], v[162:165], v[186:189], v[28:31]
	v_mfma_f32_16x16x32_bf16 v[24:27], v[162:165], v[190:193], v[24:27]
	v_mfma_f32_16x16x32_bf16 v[20:23], v[166:169], v[174:177], v[20:23]
	v_mfma_f32_16x16x32_bf16 v[16:19], v[166:169], v[182:185], v[16:19]
	v_mfma_f32_16x16x32_bf16 v[12:15], v[166:169], v[186:189], v[12:15]
	v_mfma_f32_16x16x32_bf16 v[8:11], v[166:169], v[190:193], v[8:11]
	v_mfma_f32_16x16x32_bf16 v[4:7], v[170:173], v[174:177], v[4:7]
	v_mfma_f32_16x16x32_bf16 v[0:3], v[170:173], v[182:185], v[0:3]
	v_mfma_f32_16x16x32_bf16 v[40:43], v[170:173], v[186:189], v[40:43]
	v_mfma_f32_16x16x32_bf16 v[36:39], v[170:173], v[190:193], v[36:39]
	ds_read_b128 v[158:161], v180 offset:8192
	ds_read_b128 v[162:165], v180 offset:10240
	ds_read_b128 v[166:169], v180 offset:12288
	ds_read_b128 v[170:173], v180 offset:14336
	s_waitcnt lgkmcnt(4)
	v_mfma_f32_16x16x32_bf16 v[124:127], v[142:145], v[194:197], v[124:127]
	v_mfma_f32_16x16x32_bf16 v[120:123], v[142:145], v[198:201], v[120:123]
	v_mfma_f32_16x16x32_bf16 v[116:119], v[142:145], v[202:205], v[116:119]
	v_mfma_f32_16x16x32_bf16 v[112:115], v[142:145], v[206:209], v[112:115]
	v_mfma_f32_16x16x32_bf16 v[108:111], v[146:149], v[194:197], v[108:111]
	v_mfma_f32_16x16x32_bf16 v[104:107], v[146:149], v[198:201], v[104:107]
	v_mfma_f32_16x16x32_bf16 v[100:103], v[146:149], v[202:205], v[100:103]
	v_mfma_f32_16x16x32_bf16 v[96:99], v[146:149], v[206:209], v[96:99]
	v_mfma_f32_16x16x32_bf16 v[92:95], v[150:153], v[194:197], v[92:95]
	v_mfma_f32_16x16x32_bf16 v[88:91], v[150:153], v[198:201], v[88:91]
	v_mfma_f32_16x16x32_bf16 v[84:87], v[150:153], v[202:205], v[84:87]
	v_mfma_f32_16x16x32_bf16 v[80:83], v[150:153], v[206:209], v[80:83]
	v_mfma_f32_16x16x32_bf16 v[76:79], v[154:157], v[194:197], v[76:79]
	v_mfma_f32_16x16x32_bf16 v[72:75], v[154:157], v[198:201], v[72:75]
	v_mfma_f32_16x16x32_bf16 v[68:71], v[154:157], v[202:205], v[68:71]
	v_mfma_f32_16x16x32_bf16 v[64:67], v[154:157], v[206:209], v[64:67]
	s_add_u32 s36, s36, 0x80
	s_addc_u32 s37, s37, 0
	s_add_i32 s31, s31, 1
	s_cmp_lt_u32 s31, 31
	s_cbranch_scc0 .Lg11_last
	s_waitcnt lgkmcnt(0)
	s_waitcnt vmcnt(0)
	s_barrier
	v_mfma_f32_16x16x32_bf16 v[60:63], v[158:161], v[194:197], v[60:63]
	v_mfma_f32_16x16x32_bf16 v[56:59], v[158:161], v[198:201], v[56:59]
	s_xor_b32 s45, s45, 0x10000
	s_mov_b32 m0, s45
	s_add_u32 s38, s36, s12
	s_addc_u32 s39, s37, s13
	global_load_lds_dwordx4 v178, s[38:39]
	s_add_u32 m0, s45, 0x2000
	s_add_u32 s38, s36, s14
	s_addc_u32 s39, s37, s15
	global_load_lds_dwordx4 v178, s[38:39]
	ds_read_b128 v[142:145], v212
	ds_read_b128 v[146:149], v212 offset:2048
	ds_read_b128 v[150:153], v212 offset:4096
	ds_read_b128 v[154:157], v212 offset:6144
	ds_read_b128 v[174:177], v214 offset:32768
	ds_read_b128 v[182:185], v214 offset:34816
	ds_read_b128 v[186:189], v214 offset:36864
	ds_read_b128 v[190:193], v214 offset:38912
	v_mfma_f32_16x16x32_bf16 v[52:55], v[158:161], v[202:205], v[52:55]
	v_mfma_f32_16x16x32_bf16 v[48:51], v[158:161], v[206:209], v[48:51]
	s_add_u32 m0, s45, 0x4000
	s_add_u32 s38, s36, s16
	s_addc_u32 s39, s37, s17
	global_load_lds_dwordx4 v178, s[38:39]
	v_mfma_f32_16x16x32_bf16 v[44:47], v[162:165], v[194:197], v[44:47]
	v_mfma_f32_16x16x32_bf16 v[32:35], v[162:165], v[198:201], v[32:35]
	s_add_u32 m0, s45, 0x6000
	s_add_u32 s38, s36, s18
	s_addc_u32 s39, s37, s19
	global_load_lds_dwordx4 v178, s[38:39]
	v_mfma_f32_16x16x32_bf16 v[28:31], v[162:165], v[202:205], v[28:31]
	v_mfma_f32_16x16x32_bf16 v[24:27], v[162:165], v[206:209], v[24:27]
	s_add_u32 m0, s45, 0x8000
	s_add_u32 s38, s36, s22
	s_addc_u32 s39, s37, s23
	global_load_lds_dwordx4 v179, s[38:39]
	v_mfma_f32_16x16x32_bf16 v[20:23], v[166:169], v[194:197], v[20:23]
	v_mfma_f32_16x16x32_bf16 v[16:19], v[166:169], v[198:201], v[16:19]
	s_add_u32 m0, s45, 0xa000
	s_add_u32 s38, s36, s24
	s_addc_u32 s39, s37, s25
	global_load_lds_dwordx4 v179, s[38:39]
	v_mfma_f32_16x16x32_bf16 v[12:15], v[166:169], v[202:205], v[12:15]
	v_mfma_f32_16x16x32_bf16 v[8:11], v[166:169], v[206:209], v[8:11]
	s_add_u32 m0, s45, 0xc000
	s_add_u32 s38, s36, s26
	s_addc_u32 s39, s37, s27
	global_load_lds_dwordx4 v179, s[38:39]
	v_mfma_f32_16x16x32_bf16 v[4:7], v[170:173], v[194:197], v[4:7]
	v_mfma_f32_16x16x32_bf16 v[0:3], v[170:173], v[198:201], v[0:3]
	s_add_u32 m0, s45, 0xe000
	s_add_u32 s38, s36, s28
	s_addc_u32 s39, s37, s29
	global_load_lds_dwordx4 v179, s[38:39]
	v_mfma_f32_16x16x32_bf16 v[40:43], v[170:173], v[202:205], v[40:43]
	v_mfma_f32_16x16x32_bf16 v[36:39], v[170:173], v[206:209], v[36:39]
	ds_read_b128 v[158:161], v212 offset:8192
	ds_read_b128 v[162:165], v212 offset:10240
	ds_read_b128 v[166:169], v212 offset:12288
	ds_read_b128 v[170:173], v212 offset:14336
	s_waitcnt lgkmcnt(4)
	v_mfma_f32_16x16x32_bf16 v[124:127], v[142:145], v[174:177], v[124:127]
	v_mfma_f32_16x16x32_bf16 v[120:123], v[142:145], v[182:185], v[120:123]
	v_mfma_f32_16x16x32_bf16 v[116:119], v[142:145], v[186:189], v[116:119]
	v_mfma_f32_16x16x32_bf16 v[112:115], v[142:145], v[190:193], v[112:115]
	v_mfma_f32_16x16x32_bf16 v[108:111], v[146:149], v[174:177], v[108:111]
	v_mfma_f32_16x16x32_bf16 v[104:107], v[146:149], v[182:185], v[104:107]
	v_mfma_f32_16x16x32_bf16 v[100:103], v[146:149], v[186:189], v[100:103]
	v_mfma_f32_16x16x32_bf16 v[96:99], v[146:149], v[190:193], v[96:99]
	v_mfma_f32_16x16x32_bf16 v[92:95], v[150:153], v[174:177], v[92:95]
	v_mfma_f32_16x16x32_bf16 v[88:91], v[150:153], v[182:185], v[88:91]
	v_mfma_f32_16x16x32_bf16 v[84:87], v[150:153], v[186:189], v[84:87]
	v_mfma_f32_16x16x32_bf16 v[80:83], v[150:153], v[190:193], v[80:83]
	v_mfma_f32_16x16x32_bf16 v[76:79], v[154:157], v[174:177], v[76:79]
	v_mfma_f32_16x16x32_bf16 v[72:75], v[154:157], v[182:185], v[72:75]
	v_mfma_f32_16x16x32_bf16 v[68:71], v[154:157], v[186:189], v[68:71]
	v_mfma_f32_16x16x32_bf16 v[64:67], v[154:157], v[190:193], v[64:67]
	ds_read_b128 v[142:145], v213
	ds_read_b128 v[146:149], v213 offset:2048
	ds_read_b128 v[150:153], v213 offset:4096
	ds_read_b128 v[154:157], v213 offset:6144
	ds_read_b128 v[194:197], v215 offset:32768
	ds_read_b128 v[198:201], v215 offset:34816
	ds_read_b128 v[202:205], v215 offset:36864
	ds_read_b128 v[206:209], v215 offset:38912
	s_waitcnt lgkmcnt(8)
	v_mfma_f32_16x16x32_bf16 v[60:63], v[158:161], v[174:177], v[60:63]
	v_mfma_f32_16x16x32_bf16 v[56:59], v[158:161], v[182:185], v[56:59]
	v_mfma_f32_16x16x32_bf16 v[52:55], v[158:161], v[186:189], v[52:55]
	v_mfma_f32_16x16x32_bf16 v[48:51], v[158:161], v[190:193], v[48:51]
	v_mfma_f32_16x16x32_bf16 v[44:47], v[162:165], v[174:177], v[44:47]
	v_mfma_f32_16x16x32_bf16 v[32:35], v[162:165], v[182:185], v[32:35]
	v_mfma_f32_16x16x32_bf16 v[28:31], v[162:165], v[186:189], v[28:31]
	v_mfma_f32_16x16x32_bf16 v[24:27], v[162:165], v[190:193], v[24:27]
	v_mfma_f32_16x16x32_bf16 v[20:23], v[166:169], v[174:177], v[20:23]
	v_mfma_f32_16x16x32_bf16 v[16:19], v[166:169], v[182:185], v[16:19]
	v_mfma_f32_16x16x32_bf16 v[12:15], v[166:169], v[186:189], v[12:15]
	v_mfma_f32_16x16x32_bf16 v[8:11], v[166:169], v[190:193], v[8:11]
	v_mfma_f32_16x16x32_bf16 v[4:7], v[170:173], v[174:177], v[4:7]
	v_mfma_f32_16x16x32_bf16 v[0:3], v[170:173], v[182:185], v[0:3]
	v_mfma_f32_16x16x32_bf16 v[40:43], v[170:173], v[186:189], v[40:43]
	v_mfma_f32_16x16x32_bf16 v[36:39], v[170:173], v[190:193], v[36:39]
	ds_read_b128 v[158:161], v213 offset:8192
	ds_read_b128 v[162:165], v213 offset:10240
	ds_read_b128 v[166:169], v213 offset:12288
	ds_read_b128 v[170:173], v213 offset:14336
	s_waitcnt lgkmcnt(4)
	v_mfma_f32_16x16x32_bf16 v[124:127], v[142:145], v[194:197], v[124:127]
	v_mfma_f32_16x16x32_bf16 v[120:123], v[142:145], v[198:201], v[120:123]
	v_mfma_f32_16x16x32_bf16 v[116:119], v[142:145], v[202:205], v[116:119]
	v_mfma_f32_16x16x32_bf16 v[112:115], v[142:145], v[206:209], v[112:115]
	v_mfma_f32_16x16x32_bf16 v[108:111], v[146:149], v[194:197], v[108:111]
	v_mfma_f32_16x16x32_bf16 v[104:107], v[146:149], v[198:201], v[104:107]
	v_mfma_f32_16x16x32_bf16 v[100:103], v[146:149], v[202:205], v[100:103]
	v_mfma_f32_16x16x32_bf16 v[96:99], v[146:149], v[206:209], v[96:99]
	v_mfma_f32_16x16x32_bf16 v[92:95], v[150:153], v[194:197], v[92:95]
	v_mfma_f32_16x16x32_bf16 v[88:91], v[150:153], v[198:201], v[88:91]
	v_mfma_f32_16x16x32_bf16 v[84:87], v[150:153], v[202:205], v[84:87]
	v_mfma_f32_16x16x32_bf16 v[80:83], v[150:153], v[206:209], v[80:83]
	v_mfma_f32_16x16x32_bf16 v[76:79], v[154:157], v[194:197], v[76:79]
	v_mfma_f32_16x16x32_bf16 v[72:75], v[154:157], v[198:201], v[72:75]
	v_mfma_f32_16x16x32_bf16 v[68:71], v[154:157], v[202:205], v[68:71]
	v_mfma_f32_16x16x32_bf16 v[64:67], v[154:157], v[206:209], v[64:67]
	s_add_u32 s36, s36, 0x80
	s_addc_u32 s37, s37, 0
	s_add_i32 s31, s31, 1
	s_branch .Lg11_top
.Lg11_last:
	s_waitcnt lgkmcnt(0)
	s_waitcnt vmcnt(0)
	s_barrier
	v_mfma_f32_16x16x32_bf16 v[60:63], v[158:161], v[194:197], v[60:63]
	v_mfma_f32_16x16x32_bf16 v[56:59], v[158:161], v[198:201], v[56:59]
	s_xor_b32 s45, s45, 0x10000
	ds_read_b128 v[142:145], v212
	ds_read_b128 v[146:149], v212 offset:2048
	ds_read_b128 v[150:153], v212 offset:4096
	ds_read_b128 v[154:157], v212 offset:6144
	ds_read_b128 v[174:177], v214 offset:32768
	ds_read_b128 v[182:185], v214 offset:34816
	ds_read_b128 v[186:189], v214 offset:36864
	ds_read_b128 v[190:193], v214 offset:38912
	v_mfma_f32_16x16x32_bf16 v[52:55], v[158:161], v[202:205], v[52:55]
	v_mfma_f32_16x16x32_bf16 v[48:51], v[158:161], v[206:209], v[48:51]
	v_mfma_f32_16x16x32_bf16 v[44:47], v[162:165], v[194:197], v[44:47]
	v_mfma_f32_16x16x32_bf16 v[32:35], v[162:165], v[198:201], v[32:35]
	v_mfma_f32_16x16x32_bf16 v[28:31], v[162:165], v[202:205], v[28:31]
	v_mfma_f32_16x16x32_bf16 v[24:27], v[162:165], v[206:209], v[24:27]
	v_mfma_f32_16x16x32_bf16 v[20:23], v[166:169], v[194:197], v[20:23]
	v_mfma_f32_16x16x32_bf16 v[16:19], v[166:169], v[198:201], v[16:19]
	v_mfma_f32_16x16x32_bf16 v[12:15], v[166:169], v[202:205], v[12:15]
	v_mfma_f32_16x16x32_bf16 v[8:11], v[166:169], v[206:209], v[8:11]
	v_mfma_f32_16x16x32_bf16 v[4:7], v[170:173], v[194:197], v[4:7]
	v_mfma_f32_16x16x32_bf16 v[0:3], v[170:173], v[198:201], v[0:3]
	v_mfma_f32_16x16x32_bf16 v[40:43], v[170:173], v[202:205], v[40:43]
	v_mfma_f32_16x16x32_bf16 v[36:39], v[170:173], v[206:209], v[36:39]
	ds_read_b128 v[158:161], v212 offset:8192
	ds_read_b128 v[162:165], v212 offset:10240
	ds_read_b128 v[166:169], v212 offset:12288
	ds_read_b128 v[170:173], v212 offset:14336
	s_waitcnt lgkmcnt(4)
	v_mfma_f32_16x16x32_bf16 v[124:127], v[142:145], v[174:177], v[124:127]
	v_mfma_f32_16x16x32_bf16 v[120:123], v[142:145], v[182:185], v[120:123]
	v_mfma_f32_16x16x32_bf16 v[116:119], v[142:145], v[186:189], v[116:119]
	v_mfma_f32_16x16x32_bf16 v[112:115], v[142:145], v[190:193], v[112:115]
	v_mfma_f32_16x16x32_bf16 v[108:111], v[146:149], v[174:177], v[108:111]
	v_mfma_f32_16x16x32_bf16 v[104:107], v[146:149], v[182:185], v[104:107]
	v_mfma_f32_16x16x32_bf16 v[100:103], v[146:149], v[186:189], v[100:103]
	v_mfma_f32_16x16x32_bf16 v[96:99], v[146:149], v[190:193], v[96:99]
	v_mfma_f32_16x16x32_bf16 v[92:95], v[150:153], v[174:177], v[92:95]
	v_mfma_f32_16x16x32_bf16 v[88:91], v[150:153], v[182:185], v[88:91]
	v_mfma_f32_16x16x32_bf16 v[84:87], v[150:153], v[186:189], v[84:87]
	v_mfma_f32_16x16x32_bf16 v[80:83], v[150:153], v[190:193], v[80:83]
	v_mfma_f32_16x16x32_bf16 v[76:79], v[154:157], v[174:177], v[76:79]
	v_mfma_f32_16x16x32_bf16 v[72:75], v[154:157], v[182:185], v[72:75]
	v_mfma_f32_16x16x32_bf16 v[68:71], v[154:157], v[186:189], v[68:71]
	v_mfma_f32_16x16x32_bf16 v[64:67], v[154:157], v[190:193], v[64:67]
	ds_read_b128 v[142:145], v213
	ds_read_b128 v[146:149], v213 offset:2048
	ds_read_b128 v[150:153], v213 offset:4096
	ds_read_b128 v[154:157], v213 offset:6144
	ds_read_b128 v[194:197], v215 offset:32768
	ds_read_b128 v[198:201], v215 offset:34816
	ds_read_b128 v[202:205], v215 offset:36864
	ds_read_b128 v[206:209], v215 offset:38912
	s_waitcnt lgkmcnt(8)
	v_mfma_f32_16x16x32_bf16 v[60:63], v[158:161], v[174:177], v[60:63]
	v_mfma_f32_16x16x32_bf16 v[56:59], v[158:161], v[182:185], v[56:59]
	v_mfma_f32_16x16x32_bf16 v[52:55], v[158:161], v[186:189], v[52:55]
	v_mfma_f32_16x16x32_bf16 v[48:51], v[158:161], v[190:193], v[48:51]
	v_mfma_f32_16x16x32_bf16 v[44:47], v[162:165], v[174:177], v[44:47]
	v_mfma_f32_16x16x32_bf16 v[32:35], v[162:165], v[182:185], v[32:35]
	v_mfma_f32_16x16x32_bf16 v[28:31], v[162:165], v[186:189], v[28:31]
	v_mfma_f32_16x16x32_bf16 v[24:27], v[162:165], v[190:193], v[24:27]
	v_mfma_f32_16x16x32_bf16 v[20:23], v[166:169], v[174:177], v[20:23]
	v_mfma_f32_16x16x32_bf16 v[16:19], v[166:169], v[182:185], v[16:19]
	v_mfma_f32_16x16x32_bf16 v[12:15], v[166:169], v[186:189], v[12:15]
	v_mfma_f32_16x16x32_bf16 v[8:11], v[166:169], v[190:193], v[8:11]
	v_mfma_f32_16x16x32_bf16 v[4:7], v[170:173], v[174:177], v[4:7]
	v_mfma_f32_16x16x32_bf16 v[0:3], v[170:173], v[182:185], v[0:3]
	v_mfma_f32_16x16x32_bf16 v[40:43], v[170:173], v[186:189], v[40:43]
	v_mfma_f32_16x16x32_bf16 v[36:39], v[170:173], v[190:193], v[36:39]
	ds_read_b128 v[158:161], v213 offset:8192
	ds_read_b128 v[162:165], v213 offset:10240
	ds_read_b128 v[166:169], v213 offset:12288
	ds_read_b128 v[170:173], v213 offset:14336
	s_waitcnt lgkmcnt(4)
	v_mfma_f32_16x16x32_bf16 v[124:127], v[142:145], v[194:197], v[124:127]
	v_mfma_f32_16x16x32_bf16 v[120:123], v[142:145], v[198:201], v[120:123]
	v_mfma_f32_16x16x32_bf16 v[116:119], v[142:145], v[202:205], v[116:119]
	v_mfma_f32_16x16x32_bf16 v[112:115], v[142:145], v[206:209], v[112:115]
	v_mfma_f32_16x16x32_bf16 v[108:111], v[146:149], v[194:197], v[108:111]
	v_mfma_f32_16x16x32_bf16 v[104:107], v[146:149], v[198:201], v[104:107]
	v_mfma_f32_16x16x32_bf16 v[100:103], v[146:149], v[202:205], v[100:103]
	v_mfma_f32_16x16x32_bf16 v[96:99], v[146:149], v[206:209], v[96:99]
	v_mfma_f32_16x16x32_bf16 v[92:95], v[150:153], v[194:197], v[92:95]
	v_mfma_f32_16x16x32_bf16 v[88:91], v[150:153], v[198:201], v[88:91]
	v_mfma_f32_16x16x32_bf16 v[84:87], v[150:153], v[202:205], v[84:87]
	v_mfma_f32_16x16x32_bf16 v[80:83], v[150:153], v[206:209], v[80:83]
	v_mfma_f32_16x16x32_bf16 v[76:79], v[154:157], v[194:197], v[76:79]
	v_mfma_f32_16x16x32_bf16 v[72:75], v[154:157], v[198:201], v[72:75]
	v_mfma_f32_16x16x32_bf16 v[68:71], v[154:157], v[202:205], v[68:71]
	v_mfma_f32_16x16x32_bf16 v[64:67], v[154:157], v[206:209], v[64:67]
	s_add_u32 s36, s36, 0x80
	s_addc_u32 s37, s37, 0
	s_add_i32 s31, s31, 1
	s_waitcnt lgkmcnt(0)
	s_waitcnt vmcnt(0)
	s_barrier
	v_mfma_f32_16x16x32_bf16 v[60:63], v[158:161], v[194:197], v[60:63]
	v_mfma_f32_16x16x32_bf16 v[56:59], v[158:161], v[198:201], v[56:59]
	v_mfma_f32_16x16x32_bf16 v[52:55], v[158:161], v[202:205], v[52:55]
	v_mfma_f32_16x16x32_bf16 v[48:51], v[158:161], v[206:209], v[48:51]
	v_mfma_f32_16x16x32_bf16 v[44:47], v[162:165], v[194:197], v[44:47]
	v_mfma_f32_16x16x32_bf16 v[32:35], v[162:165], v[198:201], v[32:35]
	v_mfma_f32_16x16x32_bf16 v[28:31], v[162:165], v[202:205], v[28:31]
	v_mfma_f32_16x16x32_bf16 v[24:27], v[162:165], v[206:209], v[24:27]
	v_mfma_f32_16x16x32_bf16 v[20:23], v[166:169], v[194:197], v[20:23]
	v_mfma_f32_16x16x32_bf16 v[16:19], v[166:169], v[198:201], v[16:19]
	v_mfma_f32_16x16x32_bf16 v[12:15], v[166:169], v[202:205], v[12:15]
	v_mfma_f32_16x16x32_bf16 v[8:11], v[166:169], v[206:209], v[8:11]
	v_mfma_f32_16x16x32_bf16 v[4:7], v[170:173], v[194:197], v[4:7]
	v_mfma_f32_16x16x32_bf16 v[0:3], v[170:173], v[198:201], v[0:3]
	v_mfma_f32_16x16x32_bf16 v[40:43], v[170:173], v[202:205], v[40:43]
	v_mfma_f32_16x16x32_bf16 v[36:39], v[170:173], v[206:209], v[36:39]
	s_nop 7
	s_nop 7
	s_sub_u32 s36, s36, s34
	s_subb_u32 s37, s37, s35
	s_mov_b32 s45, 0x100000
	s_mov_b32 s46, 0x100000
	s_mov_b64 s[38:39], 0
	s_mov_b64 vcc, exec
	s_branch .LBB0_1635
